# gated-DeltaNet prep: 64x64 unit-lower-triangular inverse rewritten with LDS-broadcast ds_read_b128 of A rows + packed f32 FMA (same f32 arithmetic and summation order) instead of v_readlane+v_fma per
# baseline (speedup 1.0000x reference)
.LBB0_1761:
	s_andn2_b64 vcc, exec, s[4:5]
	s_cbranch_vccnz .LBB0_1673
	v_mov_b32_e32 v0, v161
	s_mov_b64 s[74:75], s[48:49]
	s_mov_b64 s[24:25], s[20:21]
	s_mov_b64 s[22:23], s[54:55]
	s_mov_b64 s[8:9], s[56:57]
	v_add_u32_e32 v160, 0x18000, v65
	ds_write_b32 v160, v80 offset:0
	ds_write_b32 v160, v81 offset:256
	ds_write_b32 v160, v82 offset:512
	ds_write_b32 v160, v83 offset:768
	ds_write_b32 v160, v84 offset:1024
	ds_write_b32 v160, v85 offset:1280
	ds_write_b32 v160, v86 offset:1536
	ds_write_b32 v160, v87 offset:1792
	ds_write_b32 v160, v88 offset:2048
	ds_write_b32 v160, v89 offset:2304
	ds_write_b32 v160, v90 offset:2560
	ds_write_b32 v160, v91 offset:2816
	ds_write_b32 v160, v92 offset:3072
	ds_write_b32 v160, v93 offset:3328
	ds_write_b32 v160, v94 offset:3584
	ds_write_b32 v160, v95 offset:3840
	ds_write_b32 v160, v96 offset:4096
	ds_write_b32 v160, v97 offset:4352
	ds_write_b32 v160, v98 offset:4608
	ds_write_b32 v160, v99 offset:4864
	ds_write_b32 v160, v100 offset:5120
	ds_write_b32 v160, v101 offset:5376
	ds_write_b32 v160, v102 offset:5632
	ds_write_b32 v160, v103 offset:5888
	ds_write_b32 v160, v104 offset:6144
	ds_write_b32 v160, v105 offset:6400
	ds_write_b32 v160, v106 offset:6656
	ds_write_b32 v160, v107 offset:6912
	ds_write_b32 v160, v108 offset:7168
	ds_write_b32 v160, v109 offset:7424
	ds_write_b32 v160, v110 offset:7680
	ds_write_b32 v160, v111 offset:7936
	ds_write_b32 v160, v112 offset:8192
	ds_write_b32 v160, v113 offset:8448
	ds_write_b32 v160, v114 offset:8704
	ds_write_b32 v160, v115 offset:8960
	ds_write_b32 v160, v116 offset:9216
	ds_write_b32 v160, v117 offset:9472
	ds_write_b32 v160, v118 offset:9728
	ds_write_b32 v160, v119 offset:9984
	ds_write_b32 v160, v120 offset:10240
	ds_write_b32 v160, v121 offset:10496
	ds_write_b32 v160, v122 offset:10752
	ds_write_b32 v160, v123 offset:11008
	ds_write_b32 v160, v124 offset:11264
	ds_write_b32 v160, v125 offset:11520
	ds_write_b32 v160, v126 offset:11776
	ds_write_b32 v160, v127 offset:12032
	ds_write_b32 v160, v128 offset:12288
	ds_write_b32 v160, v129 offset:12544
	ds_write_b32 v160, v130 offset:12800
	ds_write_b32 v160, v131 offset:13056
	ds_write_b32 v160, v132 offset:13312
	ds_write_b32 v160, v133 offset:13568
	ds_write_b32 v160, v134 offset:13824
	ds_write_b32 v160, v135 offset:14080
	ds_write_b32 v160, v136 offset:14336
	ds_write_b32 v160, v137 offset:14592
	ds_write_b32 v160, v138 offset:14848
	ds_write_b32 v160, v139 offset:15104
	ds_write_b32 v160, v140 offset:15360
	ds_write_b32 v160, v141 offset:15616
	ds_write_b32 v160, v142 offset:15872
	ds_write_b32 v160, v143 offset:16128
	v_mov_b64_e32 v[0:1], 0
	v_mov_b64_e32 v[2:3], 0
	v_mov_b64_e32 v[4:5], 0
	v_mov_b64_e32 v[6:7], 0
	v_mov_b64_e32 v[22:23], 0
	v_mov_b64_e32 v[24:25], 0
	v_mov_b64_e32 v[26:27], 0
	v_mov_b64_e32 v[28:29], 0
	v_mov_b64_e32 v[30:31], 0
	v_mov_b64_e32 v[32:33], 0
	v_mov_b64_e32 v[34:35], 0
	v_mov_b64_e32 v[36:37], 0
	v_mov_b64_e32 v[38:39], 0
	v_mov_b64_e32 v[40:41], 0
	v_mov_b64_e32 v[42:43], 0
	v_mov_b64_e32 v[44:45], 0
	v_mov_b64_e32 v[46:47], 0
	v_mov_b64_e32 v[48:49], 0
	v_mov_b64_e32 v[50:51], 0
	v_mov_b64_e32 v[52:53], 0
	v_mov_b64_e32 v[54:55], 0
	v_mov_b64_e32 v[56:57], 0
	v_mov_b64_e32 v[58:59], 0
	v_mov_b64_e32 v[60:61], 0
	v_mov_b64_e32 v[62:63], 0
	v_mov_b64_e32 v[226:227], 0
	v_mov_b64_e32 v[228:229], 0
	v_mov_b64_e32 v[230:231], 0
	v_mov_b64_e32 v[232:233], 0
	v_mov_b64_e32 v[234:235], 0
	v_mov_b64_e32 v[236:237], 0
	v_mov_b64_e32 v[238:239], 0
	v_mov_b32_e32 v255, 0
	v_cvt_f32_i32_e32 v249, v208
	v_sub_f32_e64 v0, 1.0, |v249| clamp
	ds_read_b128 v[80:83], v161 offset:256
	ds_read_b128 v[84:87], v161 offset:512
	ds_read_b128 v[88:91], v161 offset:768
	ds_read_b128 v[92:95], v161 offset:1024
	ds_read_b128 v[96:99], v161 offset:1280
	ds_read_b128 v[100:103], v161 offset:1296
	ds_read_b128 v[104:107], v161 offset:1536
	ds_read_b128 v[108:111], v161 offset:1552
	ds_read_b128 v[112:115], v161 offset:1792
	ds_read_b128 v[116:119], v161 offset:1808
	ds_read_b128 v[120:123], v161 offset:2048
	ds_read_b128 v[124:127], v161 offset:2064
	ds_read_b128 v[128:131], v161 offset:2304
	ds_read_b128 v[132:135], v161 offset:2320
	ds_read_b128 v[136:139], v161 offset:2336
	ds_read_b128 v[140:143], v161 offset:2560
	s_waitcnt lgkmcnt(12)
	v_subrev_u32_e32 v249, 1, v208
	v_cvt_f32_i32_e32 v249, v249
	v_sub_f32_e64 v254, 1.0, |v249| clamp
	v_pk_fma_f32 v[250:251], v[80:81], v[0:1], v[254:255] neg_lo:[1,0,0] neg_hi:[1,0,0]
	v_pk_fma_f32 v[252:253], v[82:83], v[2:3], 0 neg_lo:[1,0,0] neg_hi:[1,0,0]
	v_add_f32_e32 v250, v250, v251
	v_add_f32_e32 v252, v252, v253
	v_add_f32_e32 v1, v250, v252
	v_subrev_u32_e32 v249, 2, v208
	v_cvt_f32_i32_e32 v249, v249
	v_sub_f32_e64 v254, 1.0, |v249| clamp
	v_pk_fma_f32 v[250:251], v[84:85], v[0:1], v[254:255] neg_lo:[1,0,0] neg_hi:[1,0,0]
	v_pk_fma_f32 v[252:253], v[86:87], v[2:3], 0 neg_lo:[1,0,0] neg_hi:[1,0,0]
	v_add_f32_e32 v250, v250, v251
	v_add_f32_e32 v252, v252, v253
	v_add_f32_e32 v2, v250, v252
	v_subrev_u32_e32 v249, 3, v208
	v_cvt_f32_i32_e32 v249, v249
	v_sub_f32_e64 v254, 1.0, |v249| clamp
	v_pk_fma_f32 v[250:251], v[88:89], v[0:1], v[254:255] neg_lo:[1,0,0] neg_hi:[1,0,0]
	v_pk_fma_f32 v[252:253], v[90:91], v[2:3], 0 neg_lo:[1,0,0] neg_hi:[1,0,0]
	v_add_f32_e32 v250, v250, v251
	v_add_f32_e32 v252, v252, v253
	v_add_f32_e32 v3, v250, v252
	v_subrev_u32_e32 v249, 4, v208
	v_cvt_f32_i32_e32 v249, v249
	v_sub_f32_e64 v254, 1.0, |v249| clamp
	v_pk_fma_f32 v[250:251], v[92:93], v[0:1], v[254:255] neg_lo:[1,0,0] neg_hi:[1,0,0]
	v_pk_fma_f32 v[252:253], v[94:95], v[2:3], 0 neg_lo:[1,0,0] neg_hi:[1,0,0]
	v_add_f32_e32 v250, v250, v251
	v_add_f32_e32 v252, v252, v253
	v_add_f32_e32 v4, v250, v252
	ds_read_b128 v[80:83], v161 offset:2576
	ds_read_b128 v[84:87], v161 offset:2592
	ds_read_b128 v[88:91], v161 offset:2816
	ds_read_b128 v[92:95], v161 offset:2832
	s_waitcnt lgkmcnt(12)
	v_subrev_u32_e32 v249, 5, v208
	v_cvt_f32_i32_e32 v249, v249
	v_sub_f32_e64 v254, 1.0, |v249| clamp
	v_pk_fma_f32 v[250:251], v[96:97], v[0:1], v[254:255] neg_lo:[1,0,0] neg_hi:[1,0,0]
	v_pk_fma_f32 v[252:253], v[98:99], v[2:3], 0 neg_lo:[1,0,0] neg_hi:[1,0,0]
	v_pk_fma_f32 v[250:251], v[100:101], v[4:5], v[250:251] neg_lo:[1,0,0] neg_hi:[1,0,0]
	v_pk_fma_f32 v[252:253], v[102:103], v[6:7], v[252:253] neg_lo:[1,0,0] neg_hi:[1,0,0]
	v_add_f32_e32 v250, v250, v251
	v_add_f32_e32 v252, v252, v253
	v_add_f32_e32 v5, v250, v252
	v_subrev_u32_e32 v249, 6, v208
	v_cvt_f32_i32_e32 v249, v249
	v_sub_f32_e64 v254, 1.0, |v249| clamp
	v_pk_fma_f32 v[250:251], v[104:105], v[0:1], v[254:255] neg_lo:[1,0,0] neg_hi:[1,0,0]
	v_pk_fma_f32 v[252:253], v[106:107], v[2:3], 0 neg_lo:[1,0,0] neg_hi:[1,0,0]
	v_pk_fma_f32 v[250:251], v[108:109], v[4:5], v[250:251] neg_lo:[1,0,0] neg_hi:[1,0,0]
	v_pk_fma_f32 v[252:253], v[110:111], v[6:7], v[252:253] neg_lo:[1,0,0] neg_hi:[1,0,0]
	v_add_f32_e32 v250, v250, v251
	v_add_f32_e32 v252, v252, v253
	v_add_f32_e32 v6, v250, v252
	ds_read_b128 v[96:99], v161 offset:2848
	ds_read_b128 v[100:103], v161 offset:3072
	ds_read_b128 v[104:107], v161 offset:3088
	ds_read_b128 v[108:111], v161 offset:3104
	s_waitcnt lgkmcnt(12)
	v_subrev_u32_e32 v249, 7, v208
	v_cvt_f32_i32_e32 v249, v249
	v_sub_f32_e64 v254, 1.0, |v249| clamp
	v_pk_fma_f32 v[250:251], v[112:113], v[0:1], v[254:255] neg_lo:[1,0,0] neg_hi:[1,0,0]
	v_pk_fma_f32 v[252:253], v[114:115], v[2:3], 0 neg_lo:[1,0,0] neg_hi:[1,0,0]
	v_pk_fma_f32 v[250:251], v[116:117], v[4:5], v[250:251] neg_lo:[1,0,0] neg_hi:[1,0,0]
	v_pk_fma_f32 v[252:253], v[118:119], v[6:7], v[252:253] neg_lo:[1,0,0] neg_hi:[1,0,0]
	v_add_f32_e32 v250, v250, v251
	v_add_f32_e32 v252, v252, v253
	v_add_f32_e32 v7, v250, v252
	v_subrev_u32_e32 v249, 8, v208
	v_cvt_f32_i32_e32 v249, v249
	v_sub_f32_e64 v254, 1.0, |v249| clamp
	v_pk_fma_f32 v[250:251], v[120:121], v[0:1], v[254:255] neg_lo:[1,0,0] neg_hi:[1,0,0]
	v_pk_fma_f32 v[252:253], v[122:123], v[2:3], 0 neg_lo:[1,0,0] neg_hi:[1,0,0]
	v_pk_fma_f32 v[250:251], v[124:125], v[4:5], v[250:251] neg_lo:[1,0,0] neg_hi:[1,0,0]
	v_pk_fma_f32 v[252:253], v[126:127], v[6:7], v[252:253] neg_lo:[1,0,0] neg_hi:[1,0,0]
	v_add_f32_e32 v250, v250, v251
	v_add_f32_e32 v252, v252, v253
	v_add_f32_e32 v22, v250, v252
	ds_read_b128 v[112:115], v161 offset:3328
	ds_read_b128 v[116:119], v161 offset:3344
	ds_read_b128 v[120:123], v161 offset:3360
	ds_read_b128 v[124:127], v161 offset:3376
	s_waitcnt lgkmcnt(12)
	v_subrev_u32_e32 v249, 9, v208
	v_cvt_f32_i32_e32 v249, v249
	v_sub_f32_e64 v254, 1.0, |v249| clamp
	v_pk_fma_f32 v[250:251], v[128:129], v[0:1], v[254:255] neg_lo:[1,0,0] neg_hi:[1,0,0]
	v_pk_fma_f32 v[252:253], v[130:131], v[2:3], 0 neg_lo:[1,0,0] neg_hi:[1,0,0]
	v_pk_fma_f32 v[250:251], v[132:133], v[4:5], v[250:251] neg_lo:[1,0,0] neg_hi:[1,0,0]
	v_pk_fma_f32 v[252:253], v[134:135], v[6:7], v[252:253] neg_lo:[1,0,0] neg_hi:[1,0,0]
	v_pk_fma_f32 v[250:251], v[136:137], v[22:23], v[250:251] neg_lo:[1,0,0] neg_hi:[1,0,0]
	v_pk_fma_f32 v[252:253], v[138:139], v[24:25], v[252:253] neg_lo:[1,0,0] neg_hi:[1,0,0]
	v_add_f32_e32 v250, v250, v251
	v_add_f32_e32 v252, v252, v253
	v_add_f32_e32 v23, v250, v252
	v_subrev_u32_e32 v249, 10, v208
	v_cvt_f32_i32_e32 v249, v249
	v_sub_f32_e64 v254, 1.0, |v249| clamp
	v_pk_fma_f32 v[250:251], v[140:141], v[0:1], v[254:255] neg_lo:[1,0,0] neg_hi:[1,0,0]
	v_pk_fma_f32 v[252:253], v[142:143], v[2:3], 0 neg_lo:[1,0,0] neg_hi:[1,0,0]
	ds_read_b128 v[128:131], v161 offset:3584
	ds_read_b128 v[132:135], v161 offset:3600
	ds_read_b128 v[136:139], v161 offset:3616
	ds_read_b128 v[140:143], v161 offset:3632
	s_waitcnt lgkmcnt(12)
	v_pk_fma_f32 v[250:251], v[80:81], v[4:5], v[250:251] neg_lo:[1,0,0] neg_hi:[1,0,0]
	v_pk_fma_f32 v[252:253], v[82:83], v[6:7], v[252:253] neg_lo:[1,0,0] neg_hi:[1,0,0]
	v_pk_fma_f32 v[250:251], v[84:85], v[22:23], v[250:251] neg_lo:[1,0,0] neg_hi:[1,0,0]
	v_pk_fma_f32 v[252:253], v[86:87], v[24:25], v[252:253] neg_lo:[1,0,0] neg_hi:[1,0,0]
	v_add_f32_e32 v250, v250, v251
	v_add_f32_e32 v252, v252, v253
	v_add_f32_e32 v24, v250, v252
	v_subrev_u32_e32 v249, 11, v208
	v_cvt_f32_i32_e32 v249, v249
	v_sub_f32_e64 v254, 1.0, |v249| clamp
	v_pk_fma_f32 v[250:251], v[88:89], v[0:1], v[254:255] neg_lo:[1,0,0] neg_hi:[1,0,0]
	v_pk_fma_f32 v[252:253], v[90:91], v[2:3], 0 neg_lo:[1,0,0] neg_hi:[1,0,0]
	v_pk_fma_f32 v[250:251], v[92:93], v[4:5], v[250:251] neg_lo:[1,0,0] neg_hi:[1,0,0]
	v_pk_fma_f32 v[252:253], v[94:95], v[6:7], v[252:253] neg_lo:[1,0,0] neg_hi:[1,0,0]
	ds_read_b128 v[80:83], v161 offset:3840
	ds_read_b128 v[84:87], v161 offset:3856
	ds_read_b128 v[88:91], v161 offset:3872
	ds_read_b128 v[92:95], v161 offset:3888
	s_waitcnt lgkmcnt(12)
	v_pk_fma_f32 v[250:251], v[96:97], v[22:23], v[250:251] neg_lo:[1,0,0] neg_hi:[1,0,0]
	v_pk_fma_f32 v[252:253], v[98:99], v[24:25], v[252:253] neg_lo:[1,0,0] neg_hi:[1,0,0]
	v_add_f32_e32 v250, v250, v251
	v_add_f32_e32 v252, v252, v253
	v_add_f32_e32 v25, v250, v252
	v_subrev_u32_e32 v249, 12, v208
	v_cvt_f32_i32_e32 v249, v249
	v_sub_f32_e64 v254, 1.0, |v249| clamp
	v_pk_fma_f32 v[250:251], v[100:101], v[0:1], v[254:255] neg_lo:[1,0,0] neg_hi:[1,0,0]
	v_pk_fma_f32 v[252:253], v[102:103], v[2:3], 0 neg_lo:[1,0,0] neg_hi:[1,0,0]
	v_pk_fma_f32 v[250:251], v[104:105], v[4:5], v[250:251] neg_lo:[1,0,0] neg_hi:[1,0,0]
	v_pk_fma_f32 v[252:253], v[106:107], v[6:7], v[252:253] neg_lo:[1,0,0] neg_hi:[1,0,0]
	v_pk_fma_f32 v[250:251], v[108:109], v[22:23], v[250:251] neg_lo:[1,0,0] neg_hi:[1,0,0]
	v_pk_fma_f32 v[252:253], v[110:111], v[24:25], v[252:253] neg_lo:[1,0,0] neg_hi:[1,0,0]
	v_add_f32_e32 v250, v250, v251
	v_add_f32_e32 v252, v252, v253
	v_add_f32_e32 v26, v250, v252
	ds_read_b128 v[96:99], v161 offset:4096
	ds_read_b128 v[100:103], v161 offset:4112
	ds_read_b128 v[104:107], v161 offset:4128
	ds_read_b128 v[108:111], v161 offset:4144
	s_waitcnt lgkmcnt(12)
	v_subrev_u32_e32 v249, 13, v208
	v_cvt_f32_i32_e32 v249, v249
	v_sub_f32_e64 v254, 1.0, |v249| clamp
	v_pk_fma_f32 v[250:251], v[112:113], v[0:1], v[254:255] neg_lo:[1,0,0] neg_hi:[1,0,0]
	v_pk_fma_f32 v[252:253], v[114:115], v[2:3], 0 neg_lo:[1,0,0] neg_hi:[1,0,0]
	v_pk_fma_f32 v[250:251], v[116:117], v[4:5], v[250:251] neg_lo:[1,0,0] neg_hi:[1,0,0]
	v_pk_fma_f32 v[252:253], v[118:119], v[6:7], v[252:253] neg_lo:[1,0,0] neg_hi:[1,0,0]
	v_pk_fma_f32 v[250:251], v[120:121], v[22:23], v[250:251] neg_lo:[1,0,0] neg_hi:[1,0,0]
	v_pk_fma_f32 v[252:253], v[122:123], v[24:25], v[252:253] neg_lo:[1,0,0] neg_hi:[1,0,0]
	v_pk_fma_f32 v[250:251], v[124:125], v[26:27], v[250:251] neg_lo:[1,0,0] neg_hi:[1,0,0]
	v_pk_fma_f32 v[252:253], v[126:127], v[28:29], v[252:253] neg_lo:[1,0,0] neg_hi:[1,0,0]
	v_add_f32_e32 v250, v250, v251
	v_add_f32_e32 v252, v252, v253
	v_add_f32_e32 v27, v250, v252
	ds_read_b128 v[112:115], v161 offset:4352
	ds_read_b128 v[116:119], v161 offset:4368
	ds_read_b128 v[120:123], v161 offset:4384
	ds_read_b128 v[124:127], v161 offset:4400
	s_waitcnt lgkmcnt(12)
	v_subrev_u32_e32 v249, 14, v208
	v_cvt_f32_i32_e32 v249, v249
	v_sub_f32_e64 v254, 1.0, |v249| clamp
	v_pk_fma_f32 v[250:251], v[128:129], v[0:1], v[254:255] neg_lo:[1,0,0] neg_hi:[1,0,0]
	v_pk_fma_f32 v[252:253], v[130:131], v[2:3], 0 neg_lo:[1,0,0] neg_hi:[1,0,0]
	v_pk_fma_f32 v[250:251], v[132:133], v[4:5], v[250:251] neg_lo:[1,0,0] neg_hi:[1,0,0]
	v_pk_fma_f32 v[252:253], v[134:135], v[6:7], v[252:253] neg_lo:[1,0,0] neg_hi:[1,0,0]
	v_pk_fma_f32 v[250:251], v[136:137], v[22:23], v[250:251] neg_lo:[1,0,0] neg_hi:[1,0,0]
	v_pk_fma_f32 v[252:253], v[138:139], v[24:25], v[252:253] neg_lo:[1,0,0] neg_hi:[1,0,0]
	v_pk_fma_f32 v[250:251], v[140:141], v[26:27], v[250:251] neg_lo:[1,0,0] neg_hi:[1,0,0]
	v_pk_fma_f32 v[252:253], v[142:143], v[28:29], v[252:253] neg_lo:[1,0,0] neg_hi:[1,0,0]
	v_add_f32_e32 v250, v250, v251
	v_add_f32_e32 v252, v252, v253
	v_add_f32_e32 v28, v250, v252
	ds_read_b128 v[128:131], v161 offset:4416
	ds_read_b128 v[132:135], v161 offset:4608
	ds_read_b128 v[136:139], v161 offset:4624
	ds_read_b128 v[140:143], v161 offset:4640
	s_waitcnt lgkmcnt(12)
	v_subrev_u32_e32 v249, 15, v208
	v_cvt_f32_i32_e32 v249, v249
	v_sub_f32_e64 v254, 1.0, |v249| clamp
	v_pk_fma_f32 v[250:251], v[80:81], v[0:1], v[254:255] neg_lo:[1,0,0] neg_hi:[1,0,0]
	v_pk_fma_f32 v[252:253], v[82:83], v[2:3], 0 neg_lo:[1,0,0] neg_hi:[1,0,0]
	v_pk_fma_f32 v[250:251], v[84:85], v[4:5], v[250:251] neg_lo:[1,0,0] neg_hi:[1,0,0]
	v_pk_fma_f32 v[252:253], v[86:87], v[6:7], v[252:253] neg_lo:[1,0,0] neg_hi:[1,0,0]
	v_pk_fma_f32 v[250:251], v[88:89], v[22:23], v[250:251] neg_lo:[1,0,0] neg_hi:[1,0,0]
	v_pk_fma_f32 v[252:253], v[90:91], v[24:25], v[252:253] neg_lo:[1,0,0] neg_hi:[1,0,0]
	v_pk_fma_f32 v[250:251], v[92:93], v[26:27], v[250:251] neg_lo:[1,0,0] neg_hi:[1,0,0]
	v_pk_fma_f32 v[252:253], v[94:95], v[28:29], v[252:253] neg_lo:[1,0,0] neg_hi:[1,0,0]
	v_add_f32_e32 v250, v250, v251
	v_add_f32_e32 v252, v252, v253
	v_add_f32_e32 v29, v250, v252
	ds_read_b128 v[80:83], v161 offset:4656
	ds_read_b128 v[84:87], v161 offset:4672
	ds_read_b128 v[88:91], v161 offset:4864
	ds_read_b128 v[92:95], v161 offset:4880
	s_waitcnt lgkmcnt(12)
	v_subrev_u32_e32 v249, 16, v208
	v_cvt_f32_i32_e32 v249, v249
	v_sub_f32_e64 v254, 1.0, |v249| clamp
	v_pk_fma_f32 v[250:251], v[96:97], v[0:1], v[254:255] neg_lo:[1,0,0] neg_hi:[1,0,0]
	v_pk_fma_f32 v[252:253], v[98:99], v[2:3], 0 neg_lo:[1,0,0] neg_hi:[1,0,0]
	v_pk_fma_f32 v[250:251], v[100:101], v[4:5], v[250:251] neg_lo:[1,0,0] neg_hi:[1,0,0]
	v_pk_fma_f32 v[252:253], v[102:103], v[6:7], v[252:253] neg_lo:[1,0,0] neg_hi:[1,0,0]
	v_pk_fma_f32 v[250:251], v[104:105], v[22:23], v[250:251] neg_lo:[1,0,0] neg_hi:[1,0,0]
	v_pk_fma_f32 v[252:253], v[106:107], v[24:25], v[252:253] neg_lo:[1,0,0] neg_hi:[1,0,0]
	v_pk_fma_f32 v[250:251], v[108:109], v[26:27], v[250:251] neg_lo:[1,0,0] neg_hi:[1,0,0]
	v_pk_fma_f32 v[252:253], v[110:111], v[28:29], v[252:253] neg_lo:[1,0,0] neg_hi:[1,0,0]
	v_add_f32_e32 v250, v250, v251
	v_add_f32_e32 v252, v252, v253
	v_add_f32_e32 v30, v250, v252
	ds_read_b128 v[96:99], v161 offset:4896
	ds_read_b128 v[100:103], v161 offset:4912
	ds_read_b128 v[104:107], v161 offset:4928
	ds_read_b128 v[108:111], v161 offset:5120
	s_waitcnt lgkmcnt(12)
	v_subrev_u32_e32 v249, 17, v208
	v_cvt_f32_i32_e32 v249, v249
	v_sub_f32_e64 v254, 1.0, |v249| clamp
	v_pk_fma_f32 v[250:251], v[112:113], v[0:1], v[254:255] neg_lo:[1,0,0] neg_hi:[1,0,0]
	v_pk_fma_f32 v[252:253], v[114:115], v[2:3], 0 neg_lo:[1,0,0] neg_hi:[1,0,0]
	v_pk_fma_f32 v[250:251], v[116:117], v[4:5], v[250:251] neg_lo:[1,0,0] neg_hi:[1,0,0]
	v_pk_fma_f32 v[252:253], v[118:119], v[6:7], v[252:253] neg_lo:[1,0,0] neg_hi:[1,0,0]
	v_pk_fma_f32 v[250:251], v[120:121], v[22:23], v[250:251] neg_lo:[1,0,0] neg_hi:[1,0,0]
	v_pk_fma_f32 v[252:253], v[122:123], v[24:25], v[252:253] neg_lo:[1,0,0] neg_hi:[1,0,0]
	v_pk_fma_f32 v[250:251], v[124:125], v[26:27], v[250:251] neg_lo:[1,0,0] neg_hi:[1,0,0]
	v_pk_fma_f32 v[252:253], v[126:127], v[28:29], v[252:253] neg_lo:[1,0,0] neg_hi:[1,0,0]
	ds_read_b128 v[112:115], v161 offset:5136
	ds_read_b128 v[116:119], v161 offset:5152
	ds_read_b128 v[120:123], v161 offset:5168
	ds_read_b128 v[124:127], v161 offset:5184
	s_waitcnt lgkmcnt(12)
	v_pk_fma_f32 v[250:251], v[128:129], v[30:31], v[250:251] neg_lo:[1,0,0] neg_hi:[1,0,0]
	v_pk_fma_f32 v[252:253], v[130:131], v[32:33], v[252:253] neg_lo:[1,0,0] neg_hi:[1,0,0]
	v_add_f32_e32 v250, v250, v251
	v_add_f32_e32 v252, v252, v253
	v_add_f32_e32 v31, v250, v252
	v_subrev_u32_e32 v249, 18, v208
	v_cvt_f32_i32_e32 v249, v249
	v_sub_f32_e64 v254, 1.0, |v249| clamp
	v_pk_fma_f32 v[250:251], v[132:133], v[0:1], v[254:255] neg_lo:[1,0,0] neg_hi:[1,0,0]
	v_pk_fma_f32 v[252:253], v[134:135], v[2:3], 0 neg_lo:[1,0,0] neg_hi:[1,0,0]
	v_pk_fma_f32 v[250:251], v[136:137], v[4:5], v[250:251] neg_lo:[1,0,0] neg_hi:[1,0,0]
	v_pk_fma_f32 v[252:253], v[138:139], v[6:7], v[252:253] neg_lo:[1,0,0] neg_hi:[1,0,0]
	v_pk_fma_f32 v[250:251], v[140:141], v[22:23], v[250:251] neg_lo:[1,0,0] neg_hi:[1,0,0]
	v_pk_fma_f32 v[252:253], v[142:143], v[24:25], v[252:253] neg_lo:[1,0,0] neg_hi:[1,0,0]
	ds_read_b128 v[128:131], v161 offset:5376
	ds_read_b128 v[132:135], v161 offset:5392
	ds_read_b128 v[136:139], v161 offset:5408
	ds_read_b128 v[140:143], v161 offset:5424
	s_waitcnt lgkmcnt(12)
	v_pk_fma_f32 v[250:251], v[80:81], v[26:27], v[250:251] neg_lo:[1,0,0] neg_hi:[1,0,0]
	v_pk_fma_f32 v[252:253], v[82:83], v[28:29], v[252:253] neg_lo:[1,0,0] neg_hi:[1,0,0]
	v_pk_fma_f32 v[250:251], v[84:85], v[30:31], v[250:251] neg_lo:[1,0,0] neg_hi:[1,0,0]
	v_pk_fma_f32 v[252:253], v[86:87], v[32:33], v[252:253] neg_lo:[1,0,0] neg_hi:[1,0,0]
	v_add_f32_e32 v250, v250, v251
	v_add_f32_e32 v252, v252, v253
	v_add_f32_e32 v32, v250, v252
	v_subrev_u32_e32 v249, 19, v208
	v_cvt_f32_i32_e32 v249, v249
	v_sub_f32_e64 v254, 1.0, |v249| clamp
	v_pk_fma_f32 v[250:251], v[88:89], v[0:1], v[254:255] neg_lo:[1,0,0] neg_hi:[1,0,0]
	v_pk_fma_f32 v[252:253], v[90:91], v[2:3], 0 neg_lo:[1,0,0] neg_hi:[1,0,0]
	v_pk_fma_f32 v[250:251], v[92:93], v[4:5], v[250:251] neg_lo:[1,0,0] neg_hi:[1,0,0]
	v_pk_fma_f32 v[252:253], v[94:95], v[6:7], v[252:253] neg_lo:[1,0,0] neg_hi:[1,0,0]
	ds_read_b128 v[80:83], v161 offset:5440
	ds_read_b128 v[84:87], v161 offset:5456
	ds_read_b128 v[88:91], v161 offset:5632
	ds_read_b128 v[92:95], v161 offset:5648
	s_waitcnt lgkmcnt(12)
	v_pk_fma_f32 v[250:251], v[96:97], v[22:23], v[250:251] neg_lo:[1,0,0] neg_hi:[1,0,0]
	v_pk_fma_f32 v[252:253], v[98:99], v[24:25], v[252:253] neg_lo:[1,0,0] neg_hi:[1,0,0]
	v_pk_fma_f32 v[250:251], v[100:101], v[26:27], v[250:251] neg_lo:[1,0,0] neg_hi:[1,0,0]
	v_pk_fma_f32 v[252:253], v[102:103], v[28:29], v[252:253] neg_lo:[1,0,0] neg_hi:[1,0,0]
	v_pk_fma_f32 v[250:251], v[104:105], v[30:31], v[250:251] neg_lo:[1,0,0] neg_hi:[1,0,0]
	v_pk_fma_f32 v[252:253], v[106:107], v[32:33], v[252:253] neg_lo:[1,0,0] neg_hi:[1,0,0]
	v_add_f32_e32 v250, v250, v251
	v_add_f32_e32 v252, v252, v253
	v_add_f32_e32 v33, v250, v252
	v_subrev_u32_e32 v249, 20, v208
	v_cvt_f32_i32_e32 v249, v249
	v_sub_f32_e64 v254, 1.0, |v249| clamp
	v_pk_fma_f32 v[250:251], v[108:109], v[0:1], v[254:255] neg_lo:[1,0,0] neg_hi:[1,0,0]
	v_pk_fma_f32 v[252:253], v[110:111], v[2:3], 0 neg_lo:[1,0,0] neg_hi:[1,0,0]
	ds_read_b128 v[96:99], v161 offset:5664
	ds_read_b128 v[100:103], v161 offset:5680
	ds_read_b128 v[104:107], v161 offset:5696
	ds_read_b128 v[108:111], v161 offset:5712
	s_waitcnt lgkmcnt(12)
	v_pk_fma_f32 v[250:251], v[112:113], v[4:5], v[250:251] neg_lo:[1,0,0] neg_hi:[1,0,0]
	v_pk_fma_f32 v[252:253], v[114:115], v[6:7], v[252:253] neg_lo:[1,0,0] neg_hi:[1,0,0]
	v_pk_fma_f32 v[250:251], v[116:117], v[22:23], v[250:251] neg_lo:[1,0,0] neg_hi:[1,0,0]
	v_pk_fma_f32 v[252:253], v[118:119], v[24:25], v[252:253] neg_lo:[1,0,0] neg_hi:[1,0,0]
	v_pk_fma_f32 v[250:251], v[120:121], v[26:27], v[250:251] neg_lo:[1,0,0] neg_hi:[1,0,0]
	v_pk_fma_f32 v[252:253], v[122:123], v[28:29], v[252:253] neg_lo:[1,0,0] neg_hi:[1,0,0]
	v_pk_fma_f32 v[250:251], v[124:125], v[30:31], v[250:251] neg_lo:[1,0,0] neg_hi:[1,0,0]
	v_pk_fma_f32 v[252:253], v[126:127], v[32:33], v[252:253] neg_lo:[1,0,0] neg_hi:[1,0,0]
	v_add_f32_e32 v250, v250, v251
	v_add_f32_e32 v252, v252, v253
	v_add_f32_e32 v34, v250, v252
	ds_read_b128 v[112:115], v161 offset:5888
	ds_read_b128 v[116:119], v161 offset:5904
	ds_read_b128 v[120:123], v161 offset:5920
	ds_read_b128 v[124:127], v161 offset:5936
	s_waitcnt lgkmcnt(12)
	v_subrev_u32_e32 v249, 21, v208
	v_cvt_f32_i32_e32 v249, v249
	v_sub_f32_e64 v254, 1.0, |v249| clamp
	v_pk_fma_f32 v[250:251], v[128:129], v[0:1], v[254:255] neg_lo:[1,0,0] neg_hi:[1,0,0]
	v_pk_fma_f32 v[252:253], v[130:131], v[2:3], 0 neg_lo:[1,0,0] neg_hi:[1,0,0]
	v_pk_fma_f32 v[250:251], v[132:133], v[4:5], v[250:251] neg_lo:[1,0,0] neg_hi:[1,0,0]
	v_pk_fma_f32 v[252:253], v[134:135], v[6:7], v[252:253] neg_lo:[1,0,0] neg_hi:[1,0,0]
	v_pk_fma_f32 v[250:251], v[136:137], v[22:23], v[250:251] neg_lo:[1,0,0] neg_hi:[1,0,0]
	v_pk_fma_f32 v[252:253], v[138:139], v[24:25], v[252:253] neg_lo:[1,0,0] neg_hi:[1,0,0]
	v_pk_fma_f32 v[250:251], v[140:141], v[26:27], v[250:251] neg_lo:[1,0,0] neg_hi:[1,0,0]
	v_pk_fma_f32 v[252:253], v[142:143], v[28:29], v[252:253] neg_lo:[1,0,0] neg_hi:[1,0,0]
	ds_read_b128 v[128:131], v161 offset:5952
	ds_read_b128 v[132:135], v161 offset:5968
	ds_read_b128 v[136:139], v161 offset:6144
	ds_read_b128 v[140:143], v161 offset:6160
	s_waitcnt lgkmcnt(12)
	v_pk_fma_f32 v[250:251], v[80:81], v[30:31], v[250:251] neg_lo:[1,0,0] neg_hi:[1,0,0]
	v_pk_fma_f32 v[252:253], v[82:83], v[32:33], v[252:253] neg_lo:[1,0,0] neg_hi:[1,0,0]
	v_pk_fma_f32 v[250:251], v[84:85], v[34:35], v[250:251] neg_lo:[1,0,0] neg_hi:[1,0,0]
	v_pk_fma_f32 v[252:253], v[86:87], v[36:37], v[252:253] neg_lo:[1,0,0] neg_hi:[1,0,0]
	v_add_f32_e32 v250, v250, v251
	v_add_f32_e32 v252, v252, v253
	v_add_f32_e32 v35, v250, v252
	v_subrev_u32_e32 v249, 22, v208
	v_cvt_f32_i32_e32 v249, v249
	v_sub_f32_e64 v254, 1.0, |v249| clamp
	v_pk_fma_f32 v[250:251], v[88:89], v[0:1], v[254:255] neg_lo:[1,0,0] neg_hi:[1,0,0]
	v_pk_fma_f32 v[252:253], v[90:91], v[2:3], 0 neg_lo:[1,0,0] neg_hi:[1,0,0]
	v_pk_fma_f32 v[250:251], v[92:93], v[4:5], v[250:251] neg_lo:[1,0,0] neg_hi:[1,0,0]
	v_pk_fma_f32 v[252:253], v[94:95], v[6:7], v[252:253] neg_lo:[1,0,0] neg_hi:[1,0,0]
	ds_read_b128 v[80:83], v161 offset:6176
	ds_read_b128 v[84:87], v161 offset:6192
	ds_read_b128 v[88:91], v161 offset:6208
	ds_read_b128 v[92:95], v161 offset:6224
	s_waitcnt lgkmcnt(12)
	v_pk_fma_f32 v[250:251], v[96:97], v[22:23], v[250:251] neg_lo:[1,0,0] neg_hi:[1,0,0]
	v_pk_fma_f32 v[252:253], v[98:99], v[24:25], v[252:253] neg_lo:[1,0,0] neg_hi:[1,0,0]
	v_pk_fma_f32 v[250:251], v[100:101], v[26:27], v[250:251] neg_lo:[1,0,0] neg_hi:[1,0,0]
	v_pk_fma_f32 v[252:253], v[102:103], v[28:29], v[252:253] neg_lo:[1,0,0] neg_hi:[1,0,0]
	v_pk_fma_f32 v[250:251], v[104:105], v[30:31], v[250:251] neg_lo:[1,0,0] neg_hi:[1,0,0]
	v_pk_fma_f32 v[252:253], v[106:107], v[32:33], v[252:253] neg_lo:[1,0,0] neg_hi:[1,0,0]
	v_pk_fma_f32 v[250:251], v[108:109], v[34:35], v[250:251] neg_lo:[1,0,0] neg_hi:[1,0,0]
	v_pk_fma_f32 v[252:253], v[110:111], v[36:37], v[252:253] neg_lo:[1,0,0] neg_hi:[1,0,0]
	v_add_f32_e32 v250, v250, v251
	v_add_f32_e32 v252, v252, v253
	v_add_f32_e32 v36, v250, v252
	ds_read_b128 v[96:99], v161 offset:6400
	ds_read_b128 v[100:103], v161 offset:6416
	ds_read_b128 v[104:107], v161 offset:6432
	ds_read_b128 v[108:111], v161 offset:6448
	s_waitcnt lgkmcnt(12)
	v_subrev_u32_e32 v249, 23, v208
	v_cvt_f32_i32_e32 v249, v249
	v_sub_f32_e64 v254, 1.0, |v249| clamp
	v_pk_fma_f32 v[250:251], v[112:113], v[0:1], v[254:255] neg_lo:[1,0,0] neg_hi:[1,0,0]
	v_pk_fma_f32 v[252:253], v[114:115], v[2:3], 0 neg_lo:[1,0,0] neg_hi:[1,0,0]
	v_pk_fma_f32 v[250:251], v[116:117], v[4:5], v[250:251] neg_lo:[1,0,0] neg_hi:[1,0,0]
	v_pk_fma_f32 v[252:253], v[118:119], v[6:7], v[252:253] neg_lo:[1,0,0] neg_hi:[1,0,0]
	v_pk_fma_f32 v[250:251], v[120:121], v[22:23], v[250:251] neg_lo:[1,0,0] neg_hi:[1,0,0]
	v_pk_fma_f32 v[252:253], v[122:123], v[24:25], v[252:253] neg_lo:[1,0,0] neg_hi:[1,0,0]
	v_pk_fma_f32 v[250:251], v[124:125], v[26:27], v[250:251] neg_lo:[1,0,0] neg_hi:[1,0,0]
	v_pk_fma_f32 v[252:253], v[126:127], v[28:29], v[252:253] neg_lo:[1,0,0] neg_hi:[1,0,0]
	ds_read_b128 v[112:115], v161 offset:6464
	ds_read_b128 v[116:119], v161 offset:6480
	ds_read_b128 v[120:123], v161 offset:6496
	ds_read_b128 v[124:127], v161 offset:6656
	s_waitcnt lgkmcnt(12)
	v_pk_fma_f32 v[250:251], v[128:129], v[30:31], v[250:251] neg_lo:[1,0,0] neg_hi:[1,0,0]
	v_pk_fma_f32 v[252:253], v[130:131], v[32:33], v[252:253] neg_lo:[1,0,0] neg_hi:[1,0,0]
	v_pk_fma_f32 v[250:251], v[132:133], v[34:35], v[250:251] neg_lo:[1,0,0] neg_hi:[1,0,0]
	v_pk_fma_f32 v[252:253], v[134:135], v[36:37], v[252:253] neg_lo:[1,0,0] neg_hi:[1,0,0]
	v_add_f32_e32 v250, v250, v251
	v_add_f32_e32 v252, v252, v253
	v_add_f32_e32 v37, v250, v252
	v_subrev_u32_e32 v249, 24, v208
	v_cvt_f32_i32_e32 v249, v249
	v_sub_f32_e64 v254, 1.0, |v249| clamp
	v_pk_fma_f32 v[250:251], v[136:137], v[0:1], v[254:255] neg_lo:[1,0,0] neg_hi:[1,0,0]
	v_pk_fma_f32 v[252:253], v[138:139], v[2:3], 0 neg_lo:[1,0,0] neg_hi:[1,0,0]
	v_pk_fma_f32 v[250:251], v[140:141], v[4:5], v[250:251] neg_lo:[1,0,0] neg_hi:[1,0,0]
	v_pk_fma_f32 v[252:253], v[142:143], v[6:7], v[252:253] neg_lo:[1,0,0] neg_hi:[1,0,0]
	ds_read_b128 v[128:131], v161 offset:6672
	ds_read_b128 v[132:135], v161 offset:6688
	ds_read_b128 v[136:139], v161 offset:6704
	ds_read_b128 v[140:143], v161 offset:6720
	s_waitcnt lgkmcnt(12)
	v_pk_fma_f32 v[250:251], v[80:81], v[22:23], v[250:251] neg_lo:[1,0,0] neg_hi:[1,0,0]
	v_pk_fma_f32 v[252:253], v[82:83], v[24:25], v[252:253] neg_lo:[1,0,0] neg_hi:[1,0,0]
	v_pk_fma_f32 v[250:251], v[84:85], v[26:27], v[250:251] neg_lo:[1,0,0] neg_hi:[1,0,0]
	v_pk_fma_f32 v[252:253], v[86:87], v[28:29], v[252:253] neg_lo:[1,0,0] neg_hi:[1,0,0]
	v_pk_fma_f32 v[250:251], v[88:89], v[30:31], v[250:251] neg_lo:[1,0,0] neg_hi:[1,0,0]
	v_pk_fma_f32 v[252:253], v[90:91], v[32:33], v[252:253] neg_lo:[1,0,0] neg_hi:[1,0,0]
	v_pk_fma_f32 v[250:251], v[92:93], v[34:35], v[250:251] neg_lo:[1,0,0] neg_hi:[1,0,0]
	v_pk_fma_f32 v[252:253], v[94:95], v[36:37], v[252:253] neg_lo:[1,0,0] neg_hi:[1,0,0]
	v_add_f32_e32 v250, v250, v251
	v_add_f32_e32 v252, v252, v253
	v_add_f32_e32 v38, v250, v252
	ds_read_b128 v[80:83], v161 offset:6736
	ds_read_b128 v[84:87], v161 offset:6752
	ds_read_b128 v[88:91], v161 offset:6912
	ds_read_b128 v[92:95], v161 offset:6928
	s_waitcnt lgkmcnt(12)
	v_subrev_u32_e32 v249, 25, v208
	v_cvt_f32_i32_e32 v249, v249
	v_sub_f32_e64 v254, 1.0, |v249| clamp
	v_pk_fma_f32 v[250:251], v[96:97], v[0:1], v[254:255] neg_lo:[1,0,0] neg_hi:[1,0,0]
	v_pk_fma_f32 v[252:253], v[98:99], v[2:3], 0 neg_lo:[1,0,0] neg_hi:[1,0,0]
	v_pk_fma_f32 v[250:251], v[100:101], v[4:5], v[250:251] neg_lo:[1,0,0] neg_hi:[1,0,0]
	v_pk_fma_f32 v[252:253], v[102:103], v[6:7], v[252:253] neg_lo:[1,0,0] neg_hi:[1,0,0]
	v_pk_fma_f32 v[250:251], v[104:105], v[22:23], v[250:251] neg_lo:[1,0,0] neg_hi:[1,0,0]
	v_pk_fma_f32 v[252:253], v[106:107], v[24:25], v[252:253] neg_lo:[1,0,0] neg_hi:[1,0,0]
	v_pk_fma_f32 v[250:251], v[108:109], v[26:27], v[250:251] neg_lo:[1,0,0] neg_hi:[1,0,0]
	v_pk_fma_f32 v[252:253], v[110:111], v[28:29], v[252:253] neg_lo:[1,0,0] neg_hi:[1,0,0]
	ds_read_b128 v[96:99], v161 offset:6944
	ds_read_b128 v[100:103], v161 offset:6960
	ds_read_b128 v[104:107], v161 offset:6976
	ds_read_b128 v[108:111], v161 offset:6992
	s_waitcnt lgkmcnt(12)
	v_pk_fma_f32 v[250:251], v[112:113], v[30:31], v[250:251] neg_lo:[1,0,0] neg_hi:[1,0,0]
	v_pk_fma_f32 v[252:253], v[114:115], v[32:33], v[252:253] neg_lo:[1,0,0] neg_hi:[1,0,0]
	v_pk_fma_f32 v[250:251], v[116:117], v[34:35], v[250:251] neg_lo:[1,0,0] neg_hi:[1,0,0]
	v_pk_fma_f32 v[252:253], v[118:119], v[36:37], v[252:253] neg_lo:[1,0,0] neg_hi:[1,0,0]
	v_pk_fma_f32 v[250:251], v[120:121], v[38:39], v[250:251] neg_lo:[1,0,0] neg_hi:[1,0,0]
	v_pk_fma_f32 v[252:253], v[122:123], v[40:41], v[252:253] neg_lo:[1,0,0] neg_hi:[1,0,0]
	v_add_f32_e32 v250, v250, v251
	v_add_f32_e32 v252, v252, v253
	v_add_f32_e32 v39, v250, v252
	v_subrev_u32_e32 v249, 26, v208
	v_cvt_f32_i32_e32 v249, v249
	v_sub_f32_e64 v254, 1.0, |v249| clamp
	v_pk_fma_f32 v[250:251], v[124:125], v[0:1], v[254:255] neg_lo:[1,0,0] neg_hi:[1,0,0]
	v_pk_fma_f32 v[252:253], v[126:127], v[2:3], 0 neg_lo:[1,0,0] neg_hi:[1,0,0]
	ds_read_b128 v[112:115], v161 offset:7008
	ds_read_b128 v[116:119], v161 offset:7168
	ds_read_b128 v[120:123], v161 offset:7184
	ds_read_b128 v[124:127], v161 offset:7200
	s_waitcnt lgkmcnt(12)
	v_pk_fma_f32 v[250:251], v[128:129], v[4:5], v[250:251] neg_lo:[1,0,0] neg_hi:[1,0,0]
	v_pk_fma_f32 v[252:253], v[130:131], v[6:7], v[252:253] neg_lo:[1,0,0] neg_hi:[1,0,0]
	v_pk_fma_f32 v[250:251], v[132:133], v[22:23], v[250:251] neg_lo:[1,0,0] neg_hi:[1,0,0]
	v_pk_fma_f32 v[252:253], v[134:135], v[24:25], v[252:253] neg_lo:[1,0,0] neg_hi:[1,0,0]
	v_pk_fma_f32 v[250:251], v[136:137], v[26:27], v[250:251] neg_lo:[1,0,0] neg_hi:[1,0,0]
	v_pk_fma_f32 v[252:253], v[138:139], v[28:29], v[252:253] neg_lo:[1,0,0] neg_hi:[1,0,0]
	v_pk_fma_f32 v[250:251], v[140:141], v[30:31], v[250:251] neg_lo:[1,0,0] neg_hi:[1,0,0]
	v_pk_fma_f32 v[252:253], v[142:143], v[32:33], v[252:253] neg_lo:[1,0,0] neg_hi:[1,0,0]
	ds_read_b128 v[128:131], v161 offset:7216
	ds_read_b128 v[132:135], v161 offset:7232
	ds_read_b128 v[136:139], v161 offset:7248
	ds_read_b128 v[140:143], v161 offset:7264
	s_waitcnt lgkmcnt(12)
	v_pk_fma_f32 v[250:251], v[80:81], v[34:35], v[250:251] neg_lo:[1,0,0] neg_hi:[1,0,0]
	v_pk_fma_f32 v[252:253], v[82:83], v[36:37], v[252:253] neg_lo:[1,0,0] neg_hi:[1,0,0]
	v_pk_fma_f32 v[250:251], v[84:85], v[38:39], v[250:251] neg_lo:[1,0,0] neg_hi:[1,0,0]
	v_pk_fma_f32 v[252:253], v[86:87], v[40:41], v[252:253] neg_lo:[1,0,0] neg_hi:[1,0,0]
	v_add_f32_e32 v250, v250, v251
	v_add_f32_e32 v252, v252, v253
	v_add_f32_e32 v40, v250, v252
	v_subrev_u32_e32 v249, 27, v208
	v_cvt_f32_i32_e32 v249, v249
	v_sub_f32_e64 v254, 1.0, |v249| clamp
	v_pk_fma_f32 v[250:251], v[88:89], v[0:1], v[254:255] neg_lo:[1,0,0] neg_hi:[1,0,0]
	v_pk_fma_f32 v[252:253], v[90:91], v[2:3], 0 neg_lo:[1,0,0] neg_hi:[1,0,0]
	v_pk_fma_f32 v[250:251], v[92:93], v[4:5], v[250:251] neg_lo:[1,0,0] neg_hi:[1,0,0]
	v_pk_fma_f32 v[252:253], v[94:95], v[6:7], v[252:253] neg_lo:[1,0,0] neg_hi:[1,0,0]
	ds_read_b128 v[80:83], v161 offset:7424
	ds_read_b128 v[84:87], v161 offset:7440
	ds_read_b128 v[88:91], v161 offset:7456
	ds_read_b128 v[92:95], v161 offset:7472
	s_waitcnt lgkmcnt(12)
	v_pk_fma_f32 v[250:251], v[96:97], v[22:23], v[250:251] neg_lo:[1,0,0] neg_hi:[1,0,0]
	v_pk_fma_f32 v[252:253], v[98:99], v[24:25], v[252:253] neg_lo:[1,0,0] neg_hi:[1,0,0]
	v_pk_fma_f32 v[250:251], v[100:101], v[26:27], v[250:251] neg_lo:[1,0,0] neg_hi:[1,0,0]
	v_pk_fma_f32 v[252:253], v[102:103], v[28:29], v[252:253] neg_lo:[1,0,0] neg_hi:[1,0,0]
	v_pk_fma_f32 v[250:251], v[104:105], v[30:31], v[250:251] neg_lo:[1,0,0] neg_hi:[1,0,0]
	v_pk_fma_f32 v[252:253], v[106:107], v[32:33], v[252:253] neg_lo:[1,0,0] neg_hi:[1,0,0]
	v_pk_fma_f32 v[250:251], v[108:109], v[34:35], v[250:251] neg_lo:[1,0,0] neg_hi:[1,0,0]
	v_pk_fma_f32 v[252:253], v[110:111], v[36:37], v[252:253] neg_lo:[1,0,0] neg_hi:[1,0,0]
	ds_read_b128 v[96:99], v161 offset:7488
	ds_read_b128 v[100:103], v161 offset:7504
	ds_read_b128 v[104:107], v161 offset:7520
	ds_read_b128 v[108:111], v161 offset:7536
	s_waitcnt lgkmcnt(12)
	v_pk_fma_f32 v[250:251], v[112:113], v[38:39], v[250:251] neg_lo:[1,0,0] neg_hi:[1,0,0]
	v_pk_fma_f32 v[252:253], v[114:115], v[40:41], v[252:253] neg_lo:[1,0,0] neg_hi:[1,0,0]
	v_add_f32_e32 v250, v250, v251
	v_add_f32_e32 v252, v252, v253
	v_add_f32_e32 v41, v250, v252
	v_subrev_u32_e32 v249, 28, v208
	v_cvt_f32_i32_e32 v249, v249
	v_sub_f32_e64 v254, 1.0, |v249| clamp
	v_pk_fma_f32 v[250:251], v[116:117], v[0:1], v[254:255] neg_lo:[1,0,0] neg_hi:[1,0,0]
	v_pk_fma_f32 v[252:253], v[118:119], v[2:3], 0 neg_lo:[1,0,0] neg_hi:[1,0,0]
	v_pk_fma_f32 v[250:251], v[120:121], v[4:5], v[250:251] neg_lo:[1,0,0] neg_hi:[1,0,0]
	v_pk_fma_f32 v[252:253], v[122:123], v[6:7], v[252:253] neg_lo:[1,0,0] neg_hi:[1,0,0]
	v_pk_fma_f32 v[250:251], v[124:125], v[22:23], v[250:251] neg_lo:[1,0,0] neg_hi:[1,0,0]
	v_pk_fma_f32 v[252:253], v[126:127], v[24:25], v[252:253] neg_lo:[1,0,0] neg_hi:[1,0,0]
	ds_read_b128 v[112:115], v161 offset:7680
	ds_read_b128 v[116:119], v161 offset:7696
	ds_read_b128 v[120:123], v161 offset:7712
	ds_read_b128 v[124:127], v161 offset:7728
	s_waitcnt lgkmcnt(12)
	v_pk_fma_f32 v[250:251], v[128:129], v[26:27], v[250:251] neg_lo:[1,0,0] neg_hi:[1,0,0]
	v_pk_fma_f32 v[252:253], v[130:131], v[28:29], v[252:253] neg_lo:[1,0,0] neg_hi:[1,0,0]
	v_pk_fma_f32 v[250:251], v[132:133], v[30:31], v[250:251] neg_lo:[1,0,0] neg_hi:[1,0,0]
	v_pk_fma_f32 v[252:253], v[134:135], v[32:33], v[252:253] neg_lo:[1,0,0] neg_hi:[1,0,0]
	v_pk_fma_f32 v[250:251], v[136:137], v[34:35], v[250:251] neg_lo:[1,0,0] neg_hi:[1,0,0]
	v_pk_fma_f32 v[252:253], v[138:139], v[36:37], v[252:253] neg_lo:[1,0,0] neg_hi:[1,0,0]
	v_pk_fma_f32 v[250:251], v[140:141], v[38:39], v[250:251] neg_lo:[1,0,0] neg_hi:[1,0,0]
	v_pk_fma_f32 v[252:253], v[142:143], v[40:41], v[252:253] neg_lo:[1,0,0] neg_hi:[1,0,0]
	v_add_f32_e32 v250, v250, v251
	v_add_f32_e32 v252, v252, v253
	v_add_f32_e32 v42, v250, v252
	ds_read_b128 v[128:131], v161 offset:7744
	ds_read_b128 v[132:135], v161 offset:7760
	ds_read_b128 v[136:139], v161 offset:7776
	ds_read_b128 v[140:143], v161 offset:7792
	s_waitcnt lgkmcnt(12)
	v_subrev_u32_e32 v249, 29, v208
	v_cvt_f32_i32_e32 v249, v249
	v_sub_f32_e64 v254, 1.0, |v249| clamp
	v_pk_fma_f32 v[250:251], v[80:81], v[0:1], v[254:255] neg_lo:[1,0,0] neg_hi:[1,0,0]
	v_pk_fma_f32 v[252:253], v[82:83], v[2:3], 0 neg_lo:[1,0,0] neg_hi:[1,0,0]
	v_pk_fma_f32 v[250:251], v[84:85], v[4:5], v[250:251] neg_lo:[1,0,0] neg_hi:[1,0,0]
	v_pk_fma_f32 v[252:253], v[86:87], v[6:7], v[252:253] neg_lo:[1,0,0] neg_hi:[1,0,0]
	v_pk_fma_f32 v[250:251], v[88:89], v[22:23], v[250:251] neg_lo:[1,0,0] neg_hi:[1,0,0]
	v_pk_fma_f32 v[252:253], v[90:91], v[24:25], v[252:253] neg_lo:[1,0,0] neg_hi:[1,0,0]
	v_pk_fma_f32 v[250:251], v[92:93], v[26:27], v[250:251] neg_lo:[1,0,0] neg_hi:[1,0,0]
	v_pk_fma_f32 v[252:253], v[94:95], v[28:29], v[252:253] neg_lo:[1,0,0] neg_hi:[1,0,0]
	ds_read_b128 v[80:83], v161 offset:7936
	ds_read_b128 v[84:87], v161 offset:7952
	ds_read_b128 v[88:91], v161 offset:7968
	ds_read_b128 v[92:95], v161 offset:7984
	s_waitcnt lgkmcnt(12)
	v_pk_fma_f32 v[250:251], v[96:97], v[30:31], v[250:251] neg_lo:[1,0,0] neg_hi:[1,0,0]
	v_pk_fma_f32 v[252:253], v[98:99], v[32:33], v[252:253] neg_lo:[1,0,0] neg_hi:[1,0,0]
	v_pk_fma_f32 v[250:251], v[100:101], v[34:35], v[250:251] neg_lo:[1,0,0] neg_hi:[1,0,0]
	v_pk_fma_f32 v[252:253], v[102:103], v[36:37], v[252:253] neg_lo:[1,0,0] neg_hi:[1,0,0]
	v_pk_fma_f32 v[250:251], v[104:105], v[38:39], v[250:251] neg_lo:[1,0,0] neg_hi:[1,0,0]
	v_pk_fma_f32 v[252:253], v[106:107], v[40:41], v[252:253] neg_lo:[1,0,0] neg_hi:[1,0,0]
	v_pk_fma_f32 v[250:251], v[108:109], v[42:43], v[250:251] neg_lo:[1,0,0] neg_hi:[1,0,0]
	v_pk_fma_f32 v[252:253], v[110:111], v[44:45], v[252:253] neg_lo:[1,0,0] neg_hi:[1,0,0]
	v_add_f32_e32 v250, v250, v251
	v_add_f32_e32 v252, v252, v253
	v_add_f32_e32 v43, v250, v252
	ds_read_b128 v[96:99], v161 offset:8000
	ds_read_b128 v[100:103], v161 offset:8016
	ds_read_b128 v[104:107], v161 offset:8032
	ds_read_b128 v[108:111], v161 offset:8048
	s_waitcnt lgkmcnt(12)
	v_subrev_u32_e32 v249, 30, v208
	v_cvt_f32_i32_e32 v249, v249
	v_sub_f32_e64 v254, 1.0, |v249| clamp
	v_pk_fma_f32 v[250:251], v[112:113], v[0:1], v[254:255] neg_lo:[1,0,0] neg_hi:[1,0,0]
	v_pk_fma_f32 v[252:253], v[114:115], v[2:3], 0 neg_lo:[1,0,0] neg_hi:[1,0,0]
	v_pk_fma_f32 v[250:251], v[116:117], v[4:5], v[250:251] neg_lo:[1,0,0] neg_hi:[1,0,0]
	v_pk_fma_f32 v[252:253], v[118:119], v[6:7], v[252:253] neg_lo:[1,0,0] neg_hi:[1,0,0]
	v_pk_fma_f32 v[250:251], v[120:121], v[22:23], v[250:251] neg_lo:[1,0,0] neg_hi:[1,0,0]
	v_pk_fma_f32 v[252:253], v[122:123], v[24:25], v[252:253] neg_lo:[1,0,0] neg_hi:[1,0,0]
	v_pk_fma_f32 v[250:251], v[124:125], v[26:27], v[250:251] neg_lo:[1,0,0] neg_hi:[1,0,0]
	v_pk_fma_f32 v[252:253], v[126:127], v[28:29], v[252:253] neg_lo:[1,0,0] neg_hi:[1,0,0]
	ds_read_b128 v[112:115], v161 offset:8192
	ds_read_b128 v[116:119], v161 offset:8208
	ds_read_b128 v[120:123], v161 offset:8224
	ds_read_b128 v[124:127], v161 offset:8240
	s_waitcnt lgkmcnt(12)
	v_pk_fma_f32 v[250:251], v[128:129], v[30:31], v[250:251] neg_lo:[1,0,0] neg_hi:[1,0,0]
	v_pk_fma_f32 v[252:253], v[130:131], v[32:33], v[252:253] neg_lo:[1,0,0] neg_hi:[1,0,0]
	v_pk_fma_f32 v[250:251], v[132:133], v[34:35], v[250:251] neg_lo:[1,0,0] neg_hi:[1,0,0]
	v_pk_fma_f32 v[252:253], v[134:135], v[36:37], v[252:253] neg_lo:[1,0,0] neg_hi:[1,0,0]
	v_pk_fma_f32 v[250:251], v[136:137], v[38:39], v[250:251] neg_lo:[1,0,0] neg_hi:[1,0,0]
	v_pk_fma_f32 v[252:253], v[138:139], v[40:41], v[252:253] neg_lo:[1,0,0] neg_hi:[1,0,0]
	v_pk_fma_f32 v[250:251], v[140:141], v[42:43], v[250:251] neg_lo:[1,0,0] neg_hi:[1,0,0]
	v_pk_fma_f32 v[252:253], v[142:143], v[44:45], v[252:253] neg_lo:[1,0,0] neg_hi:[1,0,0]
	v_add_f32_e32 v250, v250, v251
	v_add_f32_e32 v252, v252, v253
	v_add_f32_e32 v44, v250, v252
	ds_read_b128 v[128:131], v161 offset:8256
	ds_read_b128 v[132:135], v161 offset:8272
	ds_read_b128 v[136:139], v161 offset:8288
	ds_read_b128 v[140:143], v161 offset:8304
	s_waitcnt lgkmcnt(12)
	v_subrev_u32_e32 v249, 31, v208
	v_cvt_f32_i32_e32 v249, v249
	v_sub_f32_e64 v254, 1.0, |v249| clamp
	v_pk_fma_f32 v[250:251], v[80:81], v[0:1], v[254:255] neg_lo:[1,0,0] neg_hi:[1,0,0]
	v_pk_fma_f32 v[252:253], v[82:83], v[2:3], 0 neg_lo:[1,0,0] neg_hi:[1,0,0]
	v_pk_fma_f32 v[250:251], v[84:85], v[4:5], v[250:251] neg_lo:[1,0,0] neg_hi:[1,0,0]
	v_pk_fma_f32 v[252:253], v[86:87], v[6:7], v[252:253] neg_lo:[1,0,0] neg_hi:[1,0,0]
	v_pk_fma_f32 v[250:251], v[88:89], v[22:23], v[250:251] neg_lo:[1,0,0] neg_hi:[1,0,0]
	v_pk_fma_f32 v[252:253], v[90:91], v[24:25], v[252:253] neg_lo:[1,0,0] neg_hi:[1,0,0]
	v_pk_fma_f32 v[250:251], v[92:93], v[26:27], v[250:251] neg_lo:[1,0,0] neg_hi:[1,0,0]
	v_pk_fma_f32 v[252:253], v[94:95], v[28:29], v[252:253] neg_lo:[1,0,0] neg_hi:[1,0,0]
	ds_read_b128 v[80:83], v161 offset:8448
	ds_read_b128 v[84:87], v161 offset:8464
	ds_read_b128 v[88:91], v161 offset:8480
	ds_read_b128 v[92:95], v161 offset:8496
	s_waitcnt lgkmcnt(12)
	v_pk_fma_f32 v[250:251], v[96:97], v[30:31], v[250:251] neg_lo:[1,0,0] neg_hi:[1,0,0]
	v_pk_fma_f32 v[252:253], v[98:99], v[32:33], v[252:253] neg_lo:[1,0,0] neg_hi:[1,0,0]
	v_pk_fma_f32 v[250:251], v[100:101], v[34:35], v[250:251] neg_lo:[1,0,0] neg_hi:[1,0,0]
	v_pk_fma_f32 v[252:253], v[102:103], v[36:37], v[252:253] neg_lo:[1,0,0] neg_hi:[1,0,0]
	v_pk_fma_f32 v[250:251], v[104:105], v[38:39], v[250:251] neg_lo:[1,0,0] neg_hi:[1,0,0]
	v_pk_fma_f32 v[252:253], v[106:107], v[40:41], v[252:253] neg_lo:[1,0,0] neg_hi:[1,0,0]
	v_pk_fma_f32 v[250:251], v[108:109], v[42:43], v[250:251] neg_lo:[1,0,0] neg_hi:[1,0,0]
	v_pk_fma_f32 v[252:253], v[110:111], v[44:45], v[252:253] neg_lo:[1,0,0] neg_hi:[1,0,0]
	v_add_f32_e32 v250, v250, v251
	v_add_f32_e32 v252, v252, v253
	v_add_f32_e32 v45, v250, v252
	ds_read_b128 v[96:99], v161 offset:8512
	ds_read_b128 v[100:103], v161 offset:8528
	ds_read_b128 v[104:107], v161 offset:8544
	ds_read_b128 v[108:111], v161 offset:8560
	s_waitcnt lgkmcnt(12)
	v_subrev_u32_e32 v249, 32, v208
	v_cvt_f32_i32_e32 v249, v249
	v_sub_f32_e64 v254, 1.0, |v249| clamp
	v_pk_fma_f32 v[250:251], v[112:113], v[0:1], v[254:255] neg_lo:[1,0,0] neg_hi:[1,0,0]
	v_pk_fma_f32 v[252:253], v[114:115], v[2:3], 0 neg_lo:[1,0,0] neg_hi:[1,0,0]
	v_pk_fma_f32 v[250:251], v[116:117], v[4:5], v[250:251] neg_lo:[1,0,0] neg_hi:[1,0,0]
	v_pk_fma_f32 v[252:253], v[118:119], v[6:7], v[252:253] neg_lo:[1,0,0] neg_hi:[1,0,0]
	v_pk_fma_f32 v[250:251], v[120:121], v[22:23], v[250:251] neg_lo:[1,0,0] neg_hi:[1,0,0]
	v_pk_fma_f32 v[252:253], v[122:123], v[24:25], v[252:253] neg_lo:[1,0,0] neg_hi:[1,0,0]
	v_pk_fma_f32 v[250:251], v[124:125], v[26:27], v[250:251] neg_lo:[1,0,0] neg_hi:[1,0,0]
	v_pk_fma_f32 v[252:253], v[126:127], v[28:29], v[252:253] neg_lo:[1,0,0] neg_hi:[1,0,0]
	ds_read_b128 v[112:115], v161 offset:8576
	ds_read_b128 v[116:119], v161 offset:8704
	ds_read_b128 v[120:123], v161 offset:8720
	ds_read_b128 v[124:127], v161 offset:8736
	s_waitcnt lgkmcnt(12)
	v_pk_fma_f32 v[250:251], v[128:129], v[30:31], v[250:251] neg_lo:[1,0,0] neg_hi:[1,0,0]
	v_pk_fma_f32 v[252:253], v[130:131], v[32:33], v[252:253] neg_lo:[1,0,0] neg_hi:[1,0,0]
	v_pk_fma_f32 v[250:251], v[132:133], v[34:35], v[250:251] neg_lo:[1,0,0] neg_hi:[1,0,0]
	v_pk_fma_f32 v[252:253], v[134:135], v[36:37], v[252:253] neg_lo:[1,0,0] neg_hi:[1,0,0]
	v_pk_fma_f32 v[250:251], v[136:137], v[38:39], v[250:251] neg_lo:[1,0,0] neg_hi:[1,0,0]
	v_pk_fma_f32 v[252:253], v[138:139], v[40:41], v[252:253] neg_lo:[1,0,0] neg_hi:[1,0,0]
	v_pk_fma_f32 v[250:251], v[140:141], v[42:43], v[250:251] neg_lo:[1,0,0] neg_hi:[1,0,0]
	v_pk_fma_f32 v[252:253], v[142:143], v[44:45], v[252:253] neg_lo:[1,0,0] neg_hi:[1,0,0]
	v_add_f32_e32 v250, v250, v251
	v_add_f32_e32 v252, v252, v253
	v_add_f32_e32 v46, v250, v252
	ds_read_b128 v[128:131], v161 offset:8752
	ds_read_b128 v[132:135], v161 offset:8768
	ds_read_b128 v[136:139], v161 offset:8784
	ds_read_b128 v[140:143], v161 offset:8800
	s_waitcnt lgkmcnt(12)
	v_subrev_u32_e32 v249, 33, v208
	v_cvt_f32_i32_e32 v249, v249
	v_sub_f32_e64 v254, 1.0, |v249| clamp
	v_pk_fma_f32 v[250:251], v[80:81], v[0:1], v[254:255] neg_lo:[1,0,0] neg_hi:[1,0,0]
	v_pk_fma_f32 v[252:253], v[82:83], v[2:3], 0 neg_lo:[1,0,0] neg_hi:[1,0,0]
	v_pk_fma_f32 v[250:251], v[84:85], v[4:5], v[250:251] neg_lo:[1,0,0] neg_hi:[1,0,0]
	v_pk_fma_f32 v[252:253], v[86:87], v[6:7], v[252:253] neg_lo:[1,0,0] neg_hi:[1,0,0]
	v_pk_fma_f32 v[250:251], v[88:89], v[22:23], v[250:251] neg_lo:[1,0,0] neg_hi:[1,0,0]
	v_pk_fma_f32 v[252:253], v[90:91], v[24:25], v[252:253] neg_lo:[1,0,0] neg_hi:[1,0,0]
	v_pk_fma_f32 v[250:251], v[92:93], v[26:27], v[250:251] neg_lo:[1,0,0] neg_hi:[1,0,0]
	v_pk_fma_f32 v[252:253], v[94:95], v[28:29], v[252:253] neg_lo:[1,0,0] neg_hi:[1,0,0]
	ds_read_b128 v[80:83], v161 offset:8816
	ds_read_b128 v[84:87], v161 offset:8832
	ds_read_b128 v[88:91], v161 offset:8960
	ds_read_b128 v[92:95], v161 offset:8976
	s_waitcnt lgkmcnt(12)
	v_pk_fma_f32 v[250:251], v[96:97], v[30:31], v[250:251] neg_lo:[1,0,0] neg_hi:[1,0,0]
	v_pk_fma_f32 v[252:253], v[98:99], v[32:33], v[252:253] neg_lo:[1,0,0] neg_hi:[1,0,0]
	v_pk_fma_f32 v[250:251], v[100:101], v[34:35], v[250:251] neg_lo:[1,0,0] neg_hi:[1,0,0]
	v_pk_fma_f32 v[252:253], v[102:103], v[36:37], v[252:253] neg_lo:[1,0,0] neg_hi:[1,0,0]
	v_pk_fma_f32 v[250:251], v[104:105], v[38:39], v[250:251] neg_lo:[1,0,0] neg_hi:[1,0,0]
	v_pk_fma_f32 v[252:253], v[106:107], v[40:41], v[252:253] neg_lo:[1,0,0] neg_hi:[1,0,0]
	v_pk_fma_f32 v[250:251], v[108:109], v[42:43], v[250:251] neg_lo:[1,0,0] neg_hi:[1,0,0]
	v_pk_fma_f32 v[252:253], v[110:111], v[44:45], v[252:253] neg_lo:[1,0,0] neg_hi:[1,0,0]
	ds_read_b128 v[96:99], v161 offset:8992
	ds_read_b128 v[100:103], v161 offset:9008
	ds_read_b128 v[104:107], v161 offset:9024
	ds_read_b128 v[108:111], v161 offset:9040
	s_waitcnt lgkmcnt(12)
	v_pk_fma_f32 v[250:251], v[112:113], v[46:47], v[250:251] neg_lo:[1,0,0] neg_hi:[1,0,0]
	v_pk_fma_f32 v[252:253], v[114:115], v[48:49], v[252:253] neg_lo:[1,0,0] neg_hi:[1,0,0]
	v_add_f32_e32 v250, v250, v251
	v_add_f32_e32 v252, v252, v253
	v_add_f32_e32 v47, v250, v252
	v_subrev_u32_e32 v249, 34, v208
	v_cvt_f32_i32_e32 v249, v249
	v_sub_f32_e64 v254, 1.0, |v249| clamp
	v_pk_fma_f32 v[250:251], v[116:117], v[0:1], v[254:255] neg_lo:[1,0,0] neg_hi:[1,0,0]
	v_pk_fma_f32 v[252:253], v[118:119], v[2:3], 0 neg_lo:[1,0,0] neg_hi:[1,0,0]
	v_pk_fma_f32 v[250:251], v[120:121], v[4:5], v[250:251] neg_lo:[1,0,0] neg_hi:[1,0,0]
	v_pk_fma_f32 v[252:253], v[122:123], v[6:7], v[252:253] neg_lo:[1,0,0] neg_hi:[1,0,0]
	v_pk_fma_f32 v[250:251], v[124:125], v[22:23], v[250:251] neg_lo:[1,0,0] neg_hi:[1,0,0]
	v_pk_fma_f32 v[252:253], v[126:127], v[24:25], v[252:253] neg_lo:[1,0,0] neg_hi:[1,0,0]
	ds_read_b128 v[112:115], v161 offset:9056
	ds_read_b128 v[116:119], v161 offset:9072
	ds_read_b128 v[120:123], v161 offset:9088
	ds_read_b128 v[124:127], v161 offset:9216
	s_waitcnt lgkmcnt(12)
	v_pk_fma_f32 v[250:251], v[128:129], v[26:27], v[250:251] neg_lo:[1,0,0] neg_hi:[1,0,0]
	v_pk_fma_f32 v[252:253], v[130:131], v[28:29], v[252:253] neg_lo:[1,0,0] neg_hi:[1,0,0]
	v_pk_fma_f32 v[250:251], v[132:133], v[30:31], v[250:251] neg_lo:[1,0,0] neg_hi:[1,0,0]
	v_pk_fma_f32 v[252:253], v[134:135], v[32:33], v[252:253] neg_lo:[1,0,0] neg_hi:[1,0,0]
	v_pk_fma_f32 v[250:251], v[136:137], v[34:35], v[250:251] neg_lo:[1,0,0] neg_hi:[1,0,0]
	v_pk_fma_f32 v[252:253], v[138:139], v[36:37], v[252:253] neg_lo:[1,0,0] neg_hi:[1,0,0]
	v_pk_fma_f32 v[250:251], v[140:141], v[38:39], v[250:251] neg_lo:[1,0,0] neg_hi:[1,0,0]
	v_pk_fma_f32 v[252:253], v[142:143], v[40:41], v[252:253] neg_lo:[1,0,0] neg_hi:[1,0,0]
	ds_read_b128 v[128:131], v161 offset:9232
	ds_read_b128 v[132:135], v161 offset:9248
	ds_read_b128 v[136:139], v161 offset:9264
	ds_read_b128 v[140:143], v161 offset:9280
	s_waitcnt lgkmcnt(12)
	v_pk_fma_f32 v[250:251], v[80:81], v[42:43], v[250:251] neg_lo:[1,0,0] neg_hi:[1,0,0]
	v_pk_fma_f32 v[252:253], v[82:83], v[44:45], v[252:253] neg_lo:[1,0,0] neg_hi:[1,0,0]
	v_pk_fma_f32 v[250:251], v[84:85], v[46:47], v[250:251] neg_lo:[1,0,0] neg_hi:[1,0,0]
	v_pk_fma_f32 v[252:253], v[86:87], v[48:49], v[252:253] neg_lo:[1,0,0] neg_hi:[1,0,0]
	v_add_f32_e32 v250, v250, v251
	v_add_f32_e32 v252, v252, v253
	v_add_f32_e32 v48, v250, v252
	v_subrev_u32_e32 v249, 35, v208
	v_cvt_f32_i32_e32 v249, v249
	v_sub_f32_e64 v254, 1.0, |v249| clamp
	v_pk_fma_f32 v[250:251], v[88:89], v[0:1], v[254:255] neg_lo:[1,0,0] neg_hi:[1,0,0]
	v_pk_fma_f32 v[252:253], v[90:91], v[2:3], 0 neg_lo:[1,0,0] neg_hi:[1,0,0]
	v_pk_fma_f32 v[250:251], v[92:93], v[4:5], v[250:251] neg_lo:[1,0,0] neg_hi:[1,0,0]
	v_pk_fma_f32 v[252:253], v[94:95], v[6:7], v[252:253] neg_lo:[1,0,0] neg_hi:[1,0,0]
	ds_read_b128 v[80:83], v161 offset:9296
	ds_read_b128 v[84:87], v161 offset:9312
	ds_read_b128 v[88:91], v161 offset:9328
	ds_read_b128 v[92:95], v161 offset:9344
	s_waitcnt lgkmcnt(12)
	v_pk_fma_f32 v[250:251], v[96:97], v[22:23], v[250:251] neg_lo:[1,0,0] neg_hi:[1,0,0]
	v_pk_fma_f32 v[252:253], v[98:99], v[24:25], v[252:253] neg_lo:[1,0,0] neg_hi:[1,0,0]
	v_pk_fma_f32 v[250:251], v[100:101], v[26:27], v[250:251] neg_lo:[1,0,0] neg_hi:[1,0,0]
	v_pk_fma_f32 v[252:253], v[102:103], v[28:29], v[252:253] neg_lo:[1,0,0] neg_hi:[1,0,0]
	v_pk_fma_f32 v[250:251], v[104:105], v[30:31], v[250:251] neg_lo:[1,0,0] neg_hi:[1,0,0]
	v_pk_fma_f32 v[252:253], v[106:107], v[32:33], v[252:253] neg_lo:[1,0,0] neg_hi:[1,0,0]
	v_pk_fma_f32 v[250:251], v[108:109], v[34:35], v[250:251] neg_lo:[1,0,0] neg_hi:[1,0,0]
	v_pk_fma_f32 v[252:253], v[110:111], v[36:37], v[252:253] neg_lo:[1,0,0] neg_hi:[1,0,0]
	ds_read_b128 v[96:99], v161 offset:9472
	ds_read_b128 v[100:103], v161 offset:9488
	ds_read_b128 v[104:107], v161 offset:9504
	ds_read_b128 v[108:111], v161 offset:9520
	s_waitcnt lgkmcnt(12)
	v_pk_fma_f32 v[250:251], v[112:113], v[38:39], v[250:251] neg_lo:[1,0,0] neg_hi:[1,0,0]
	v_pk_fma_f32 v[252:253], v[114:115], v[40:41], v[252:253] neg_lo:[1,0,0] neg_hi:[1,0,0]
	v_pk_fma_f32 v[250:251], v[116:117], v[42:43], v[250:251] neg_lo:[1,0,0] neg_hi:[1,0,0]
	v_pk_fma_f32 v[252:253], v[118:119], v[44:45], v[252:253] neg_lo:[1,0,0] neg_hi:[1,0,0]
	v_pk_fma_f32 v[250:251], v[120:121], v[46:47], v[250:251] neg_lo:[1,0,0] neg_hi:[1,0,0]
	v_pk_fma_f32 v[252:253], v[122:123], v[48:49], v[252:253] neg_lo:[1,0,0] neg_hi:[1,0,0]
	v_add_f32_e32 v250, v250, v251
	v_add_f32_e32 v252, v252, v253
	v_add_f32_e32 v49, v250, v252
	v_subrev_u32_e32 v249, 36, v208
	v_cvt_f32_i32_e32 v249, v249
	v_sub_f32_e64 v254, 1.0, |v249| clamp
	v_pk_fma_f32 v[250:251], v[124:125], v[0:1], v[254:255] neg_lo:[1,0,0] neg_hi:[1,0,0]
	v_pk_fma_f32 v[252:253], v[126:127], v[2:3], 0 neg_lo:[1,0,0] neg_hi:[1,0,0]
	ds_read_b128 v[112:115], v161 offset:9536
	ds_read_b128 v[116:119], v161 offset:9552
	ds_read_b128 v[120:123], v161 offset:9568
	ds_read_b128 v[124:127], v161 offset:9584
	s_waitcnt lgkmcnt(12)
	v_pk_fma_f32 v[250:251], v[128:129], v[4:5], v[250:251] neg_lo:[1,0,0] neg_hi:[1,0,0]
	v_pk_fma_f32 v[252:253], v[130:131], v[6:7], v[252:253] neg_lo:[1,0,0] neg_hi:[1,0,0]
	v_pk_fma_f32 v[250:251], v[132:133], v[22:23], v[250:251] neg_lo:[1,0,0] neg_hi:[1,0,0]
	v_pk_fma_f32 v[252:253], v[134:135], v[24:25], v[252:253] neg_lo:[1,0,0] neg_hi:[1,0,0]
	v_pk_fma_f32 v[250:251], v[136:137], v[26:27], v[250:251] neg_lo:[1,0,0] neg_hi:[1,0,0]
	v_pk_fma_f32 v[252:253], v[138:139], v[28:29], v[252:253] neg_lo:[1,0,0] neg_hi:[1,0,0]
	v_pk_fma_f32 v[250:251], v[140:141], v[30:31], v[250:251] neg_lo:[1,0,0] neg_hi:[1,0,0]
	v_pk_fma_f32 v[252:253], v[142:143], v[32:33], v[252:253] neg_lo:[1,0,0] neg_hi:[1,0,0]
	ds_read_b128 v[128:131], v161 offset:9600
	ds_read_b128 v[132:135], v161 offset:9616
	ds_read_b128 v[136:139], v161 offset:9728
	ds_read_b128 v[140:143], v161 offset:9744
	s_waitcnt lgkmcnt(12)
	v_pk_fma_f32 v[250:251], v[80:81], v[34:35], v[250:251] neg_lo:[1,0,0] neg_hi:[1,0,0]
	v_pk_fma_f32 v[252:253], v[82:83], v[36:37], v[252:253] neg_lo:[1,0,0] neg_hi:[1,0,0]
	v_pk_fma_f32 v[250:251], v[84:85], v[38:39], v[250:251] neg_lo:[1,0,0] neg_hi:[1,0,0]
	v_pk_fma_f32 v[252:253], v[86:87], v[40:41], v[252:253] neg_lo:[1,0,0] neg_hi:[1,0,0]
	v_pk_fma_f32 v[250:251], v[88:89], v[42:43], v[250:251] neg_lo:[1,0,0] neg_hi:[1,0,0]
	v_pk_fma_f32 v[252:253], v[90:91], v[44:45], v[252:253] neg_lo:[1,0,0] neg_hi:[1,0,0]
	v_pk_fma_f32 v[250:251], v[92:93], v[46:47], v[250:251] neg_lo:[1,0,0] neg_hi:[1,0,0]
	v_pk_fma_f32 v[252:253], v[94:95], v[48:49], v[252:253] neg_lo:[1,0,0] neg_hi:[1,0,0]
	v_add_f32_e32 v250, v250, v251
	v_add_f32_e32 v252, v252, v253
	v_add_f32_e32 v50, v250, v252
	ds_read_b128 v[80:83], v161 offset:9760
	ds_read_b128 v[84:87], v161 offset:9776
	ds_read_b128 v[88:91], v161 offset:9792
	ds_read_b128 v[92:95], v161 offset:9808
	s_waitcnt lgkmcnt(12)
	v_subrev_u32_e32 v249, 37, v208
	v_cvt_f32_i32_e32 v249, v249
	v_sub_f32_e64 v254, 1.0, |v249| clamp
	v_pk_fma_f32 v[250:251], v[96:97], v[0:1], v[254:255] neg_lo:[1,0,0] neg_hi:[1,0,0]
	v_pk_fma_f32 v[252:253], v[98:99], v[2:3], 0 neg_lo:[1,0,0] neg_hi:[1,0,0]
	v_pk_fma_f32 v[250:251], v[100:101], v[4:5], v[250:251] neg_lo:[1,0,0] neg_hi:[1,0,0]
	v_pk_fma_f32 v[252:253], v[102:103], v[6:7], v[252:253] neg_lo:[1,0,0] neg_hi:[1,0,0]
	v_pk_fma_f32 v[250:251], v[104:105], v[22:23], v[250:251] neg_lo:[1,0,0] neg_hi:[1,0,0]
	v_pk_fma_f32 v[252:253], v[106:107], v[24:25], v[252:253] neg_lo:[1,0,0] neg_hi:[1,0,0]
	v_pk_fma_f32 v[250:251], v[108:109], v[26:27], v[250:251] neg_lo:[1,0,0] neg_hi:[1,0,0]
	v_pk_fma_f32 v[252:253], v[110:111], v[28:29], v[252:253] neg_lo:[1,0,0] neg_hi:[1,0,0]
	ds_read_b128 v[96:99], v161 offset:9824
	ds_read_b128 v[100:103], v161 offset:9840
	ds_read_b128 v[104:107], v161 offset:9856
	ds_read_b128 v[108:111], v161 offset:9872
	s_waitcnt lgkmcnt(12)
	v_pk_fma_f32 v[250:251], v[112:113], v[30:31], v[250:251] neg_lo:[1,0,0] neg_hi:[1,0,0]
	v_pk_fma_f32 v[252:253], v[114:115], v[32:33], v[252:253] neg_lo:[1,0,0] neg_hi:[1,0,0]
	v_pk_fma_f32 v[250:251], v[116:117], v[34:35], v[250:251] neg_lo:[1,0,0] neg_hi:[1,0,0]
	v_pk_fma_f32 v[252:253], v[118:119], v[36:37], v[252:253] neg_lo:[1,0,0] neg_hi:[1,0,0]
	v_pk_fma_f32 v[250:251], v[120:121], v[38:39], v[250:251] neg_lo:[1,0,0] neg_hi:[1,0,0]
	v_pk_fma_f32 v[252:253], v[122:123], v[40:41], v[252:253] neg_lo:[1,0,0] neg_hi:[1,0,0]
	v_pk_fma_f32 v[250:251], v[124:125], v[42:43], v[250:251] neg_lo:[1,0,0] neg_hi:[1,0,0]
	v_pk_fma_f32 v[252:253], v[126:127], v[44:45], v[252:253] neg_lo:[1,0,0] neg_hi:[1,0,0]
	ds_read_b128 v[112:115], v161 offset:9984
	ds_read_b128 v[116:119], v161 offset:10000
	ds_read_b128 v[120:123], v161 offset:10016
	ds_read_b128 v[124:127], v161 offset:10032
	s_waitcnt lgkmcnt(12)
	v_pk_fma_f32 v[250:251], v[128:129], v[46:47], v[250:251] neg_lo:[1,0,0] neg_hi:[1,0,0]
	v_pk_fma_f32 v[252:253], v[130:131], v[48:49], v[252:253] neg_lo:[1,0,0] neg_hi:[1,0,0]
	v_pk_fma_f32 v[250:251], v[132:133], v[50:51], v[250:251] neg_lo:[1,0,0] neg_hi:[1,0,0]
	v_pk_fma_f32 v[252:253], v[134:135], v[52:53], v[252:253] neg_lo:[1,0,0] neg_hi:[1,0,0]
	v_add_f32_e32 v250, v250, v251
	v_add_f32_e32 v252, v252, v253
	v_add_f32_e32 v51, v250, v252
	v_subrev_u32_e32 v249, 38, v208
	v_cvt_f32_i32_e32 v249, v249
	v_sub_f32_e64 v254, 1.0, |v249| clamp
	v_pk_fma_f32 v[250:251], v[136:137], v[0:1], v[254:255] neg_lo:[1,0,0] neg_hi:[1,0,0]
	v_pk_fma_f32 v[252:253], v[138:139], v[2:3], 0 neg_lo:[1,0,0] neg_hi:[1,0,0]
	v_pk_fma_f32 v[250:251], v[140:141], v[4:5], v[250:251] neg_lo:[1,0,0] neg_hi:[1,0,0]
	v_pk_fma_f32 v[252:253], v[142:143], v[6:7], v[252:253] neg_lo:[1,0,0] neg_hi:[1,0,0]
	ds_read_b128 v[128:131], v161 offset:10048
	ds_read_b128 v[132:135], v161 offset:10064
	ds_read_b128 v[136:139], v161 offset:10080
	ds_read_b128 v[140:143], v161 offset:10096
	s_waitcnt lgkmcnt(12)
	v_pk_fma_f32 v[250:251], v[80:81], v[22:23], v[250:251] neg_lo:[1,0,0] neg_hi:[1,0,0]
	v_pk_fma_f32 v[252:253], v[82:83], v[24:25], v[252:253] neg_lo:[1,0,0] neg_hi:[1,0,0]
	v_pk_fma_f32 v[250:251], v[84:85], v[26:27], v[250:251] neg_lo:[1,0,0] neg_hi:[1,0,0]
	v_pk_fma_f32 v[252:253], v[86:87], v[28:29], v[252:253] neg_lo:[1,0,0] neg_hi:[1,0,0]
	v_pk_fma_f32 v[250:251], v[88:89], v[30:31], v[250:251] neg_lo:[1,0,0] neg_hi:[1,0,0]
	v_pk_fma_f32 v[252:253], v[90:91], v[32:33], v[252:253] neg_lo:[1,0,0] neg_hi:[1,0,0]
	v_pk_fma_f32 v[250:251], v[92:93], v[34:35], v[250:251] neg_lo:[1,0,0] neg_hi:[1,0,0]
	v_pk_fma_f32 v[252:253], v[94:95], v[36:37], v[252:253] neg_lo:[1,0,0] neg_hi:[1,0,0]
	ds_read_b128 v[80:83], v161 offset:10112
	ds_read_b128 v[84:87], v161 offset:10128
	ds_read_b128 v[88:91], v161 offset:10240
	ds_read_b128 v[92:95], v161 offset:10256
	s_waitcnt lgkmcnt(12)
	v_pk_fma_f32 v[250:251], v[96:97], v[38:39], v[250:251] neg_lo:[1,0,0] neg_hi:[1,0,0]
	v_pk_fma_f32 v[252:253], v[98:99], v[40:41], v[252:253] neg_lo:[1,0,0] neg_hi:[1,0,0]
	v_pk_fma_f32 v[250:251], v[100:101], v[42:43], v[250:251] neg_lo:[1,0,0] neg_hi:[1,0,0]
	v_pk_fma_f32 v[252:253], v[102:103], v[44:45], v[252:253] neg_lo:[1,0,0] neg_hi:[1,0,0]
	v_pk_fma_f32 v[250:251], v[104:105], v[46:47], v[250:251] neg_lo:[1,0,0] neg_hi:[1,0,0]
	v_pk_fma_f32 v[252:253], v[106:107], v[48:49], v[252:253] neg_lo:[1,0,0] neg_hi:[1,0,0]
	v_pk_fma_f32 v[250:251], v[108:109], v[50:51], v[250:251] neg_lo:[1,0,0] neg_hi:[1,0,0]
	v_pk_fma_f32 v[252:253], v[110:111], v[52:53], v[252:253] neg_lo:[1,0,0] neg_hi:[1,0,0]
	v_add_f32_e32 v250, v250, v251
	v_add_f32_e32 v252, v252, v253
	v_add_f32_e32 v52, v250, v252
	ds_read_b128 v[96:99], v161 offset:10272
	ds_read_b128 v[100:103], v161 offset:10288
	ds_read_b128 v[104:107], v161 offset:10304
	ds_read_b128 v[108:111], v161 offset:10320
	s_waitcnt lgkmcnt(12)
	v_subrev_u32_e32 v249, 39, v208
	v_cvt_f32_i32_e32 v249, v249
	v_sub_f32_e64 v254, 1.0, |v249| clamp
	v_pk_fma_f32 v[250:251], v[112:113], v[0:1], v[254:255] neg_lo:[1,0,0] neg_hi:[1,0,0]
	v_pk_fma_f32 v[252:253], v[114:115], v[2:3], 0 neg_lo:[1,0,0] neg_hi:[1,0,0]
	v_pk_fma_f32 v[250:251], v[116:117], v[4:5], v[250:251] neg_lo:[1,0,0] neg_hi:[1,0,0]
	v_pk_fma_f32 v[252:253], v[118:119], v[6:7], v[252:253] neg_lo:[1,0,0] neg_hi:[1,0,0]
	v_pk_fma_f32 v[250:251], v[120:121], v[22:23], v[250:251] neg_lo:[1,0,0] neg_hi:[1,0,0]
	v_pk_fma_f32 v[252:253], v[122:123], v[24:25], v[252:253] neg_lo:[1,0,0] neg_hi:[1,0,0]
	v_pk_fma_f32 v[250:251], v[124:125], v[26:27], v[250:251] neg_lo:[1,0,0] neg_hi:[1,0,0]
	v_pk_fma_f32 v[252:253], v[126:127], v[28:29], v[252:253] neg_lo:[1,0,0] neg_hi:[1,0,0]
	ds_read_b128 v[112:115], v161 offset:10336
	ds_read_b128 v[116:119], v161 offset:10352
	ds_read_b128 v[120:123], v161 offset:10368
	ds_read_b128 v[124:127], v161 offset:10384
	s_waitcnt lgkmcnt(12)
	v_pk_fma_f32 v[250:251], v[128:129], v[30:31], v[250:251] neg_lo:[1,0,0] neg_hi:[1,0,0]
	v_pk_fma_f32 v[252:253], v[130:131], v[32:33], v[252:253] neg_lo:[1,0,0] neg_hi:[1,0,0]
	v_pk_fma_f32 v[250:251], v[132:133], v[34:35], v[250:251] neg_lo:[1,0,0] neg_hi:[1,0,0]
	v_pk_fma_f32 v[252:253], v[134:135], v[36:37], v[252:253] neg_lo:[1,0,0] neg_hi:[1,0,0]
	v_pk_fma_f32 v[250:251], v[136:137], v[38:39], v[250:251] neg_lo:[1,0,0] neg_hi:[1,0,0]
	v_pk_fma_f32 v[252:253], v[138:139], v[40:41], v[252:253] neg_lo:[1,0,0] neg_hi:[1,0,0]
	v_pk_fma_f32 v[250:251], v[140:141], v[42:43], v[250:251] neg_lo:[1,0,0] neg_hi:[1,0,0]
	v_pk_fma_f32 v[252:253], v[142:143], v[44:45], v[252:253] neg_lo:[1,0,0] neg_hi:[1,0,0]
	ds_read_b128 v[128:131], v161 offset:10496
	ds_read_b128 v[132:135], v161 offset:10512
	ds_read_b128 v[136:139], v161 offset:10528
	ds_read_b128 v[140:143], v161 offset:10544
	s_waitcnt lgkmcnt(12)
	v_pk_fma_f32 v[250:251], v[80:81], v[46:47], v[250:251] neg_lo:[1,0,0] neg_hi:[1,0,0]
	v_pk_fma_f32 v[252:253], v[82:83], v[48:49], v[252:253] neg_lo:[1,0,0] neg_hi:[1,0,0]
	v_pk_fma_f32 v[250:251], v[84:85], v[50:51], v[250:251] neg_lo:[1,0,0] neg_hi:[1,0,0]
	v_pk_fma_f32 v[252:253], v[86:87], v[52:53], v[252:253] neg_lo:[1,0,0] neg_hi:[1,0,0]
	v_add_f32_e32 v250, v250, v251
	v_add_f32_e32 v252, v252, v253
	v_add_f32_e32 v53, v250, v252
	v_subrev_u32_e32 v249, 40, v208
	v_cvt_f32_i32_e32 v249, v249
	v_sub_f32_e64 v254, 1.0, |v249| clamp
	v_pk_fma_f32 v[250:251], v[88:89], v[0:1], v[254:255] neg_lo:[1,0,0] neg_hi:[1,0,0]
	v_pk_fma_f32 v[252:253], v[90:91], v[2:3], 0 neg_lo:[1,0,0] neg_hi:[1,0,0]
	v_pk_fma_f32 v[250:251], v[92:93], v[4:5], v[250:251] neg_lo:[1,0,0] neg_hi:[1,0,0]
	v_pk_fma_f32 v[252:253], v[94:95], v[6:7], v[252:253] neg_lo:[1,0,0] neg_hi:[1,0,0]
	ds_read_b128 v[80:83], v161 offset:10560
	ds_read_b128 v[84:87], v161 offset:10576
	ds_read_b128 v[88:91], v161 offset:10592
	ds_read_b128 v[92:95], v161 offset:10608
	s_waitcnt lgkmcnt(12)
	v_pk_fma_f32 v[250:251], v[96:97], v[22:23], v[250:251] neg_lo:[1,0,0] neg_hi:[1,0,0]
	v_pk_fma_f32 v[252:253], v[98:99], v[24:25], v[252:253] neg_lo:[1,0,0] neg_hi:[1,0,0]
	v_pk_fma_f32 v[250:251], v[100:101], v[26:27], v[250:251] neg_lo:[1,0,0] neg_hi:[1,0,0]
	v_pk_fma_f32 v[252:253], v[102:103], v[28:29], v[252:253] neg_lo:[1,0,0] neg_hi:[1,0,0]
	v_pk_fma_f32 v[250:251], v[104:105], v[30:31], v[250:251] neg_lo:[1,0,0] neg_hi:[1,0,0]
	v_pk_fma_f32 v[252:253], v[106:107], v[32:33], v[252:253] neg_lo:[1,0,0] neg_hi:[1,0,0]
	v_pk_fma_f32 v[250:251], v[108:109], v[34:35], v[250:251] neg_lo:[1,0,0] neg_hi:[1,0,0]
	v_pk_fma_f32 v[252:253], v[110:111], v[36:37], v[252:253] neg_lo:[1,0,0] neg_hi:[1,0,0]
	ds_read_b128 v[96:99], v161 offset:10624
	ds_read_b128 v[100:103], v161 offset:10640
	ds_read_b128 v[104:107], v161 offset:10656
	ds_read_b128 v[108:111], v161 offset:10752
	s_waitcnt lgkmcnt(12)
	v_pk_fma_f32 v[250:251], v[112:113], v[38:39], v[250:251] neg_lo:[1,0,0] neg_hi:[1,0,0]
	v_pk_fma_f32 v[252:253], v[114:115], v[40:41], v[252:253] neg_lo:[1,0,0] neg_hi:[1,0,0]
	v_pk_fma_f32 v[250:251], v[116:117], v[42:43], v[250:251] neg_lo:[1,0,0] neg_hi:[1,0,0]
	v_pk_fma_f32 v[252:253], v[118:119], v[44:45], v[252:253] neg_lo:[1,0,0] neg_hi:[1,0,0]
	v_pk_fma_f32 v[250:251], v[120:121], v[46:47], v[250:251] neg_lo:[1,0,0] neg_hi:[1,0,0]
	v_pk_fma_f32 v[252:253], v[122:123], v[48:49], v[252:253] neg_lo:[1,0,0] neg_hi:[1,0,0]
	v_pk_fma_f32 v[250:251], v[124:125], v[50:51], v[250:251] neg_lo:[1,0,0] neg_hi:[1,0,0]
	v_pk_fma_f32 v[252:253], v[126:127], v[52:53], v[252:253] neg_lo:[1,0,0] neg_hi:[1,0,0]
	v_add_f32_e32 v250, v250, v251
	v_add_f32_e32 v252, v252, v253
	v_add_f32_e32 v54, v250, v252
	ds_read_b128 v[112:115], v161 offset:10768
	ds_read_b128 v[116:119], v161 offset:10784
	ds_read_b128 v[120:123], v161 offset:10800
	ds_read_b128 v[124:127], v161 offset:10816
	s_waitcnt lgkmcnt(12)
	v_subrev_u32_e32 v249, 41, v208
	v_cvt_f32_i32_e32 v249, v249
	v_sub_f32_e64 v254, 1.0, |v249| clamp
	v_pk_fma_f32 v[250:251], v[128:129], v[0:1], v[254:255] neg_lo:[1,0,0] neg_hi:[1,0,0]
	v_pk_fma_f32 v[252:253], v[130:131], v[2:3], 0 neg_lo:[1,0,0] neg_hi:[1,0,0]
	v_pk_fma_f32 v[250:251], v[132:133], v[4:5], v[250:251] neg_lo:[1,0,0] neg_hi:[1,0,0]
	v_pk_fma_f32 v[252:253], v[134:135], v[6:7], v[252:253] neg_lo:[1,0,0] neg_hi:[1,0,0]
	v_pk_fma_f32 v[250:251], v[136:137], v[22:23], v[250:251] neg_lo:[1,0,0] neg_hi:[1,0,0]
	v_pk_fma_f32 v[252:253], v[138:139], v[24:25], v[252:253] neg_lo:[1,0,0] neg_hi:[1,0,0]
	v_pk_fma_f32 v[250:251], v[140:141], v[26:27], v[250:251] neg_lo:[1,0,0] neg_hi:[1,0,0]
	v_pk_fma_f32 v[252:253], v[142:143], v[28:29], v[252:253] neg_lo:[1,0,0] neg_hi:[1,0,0]
	ds_read_b128 v[128:131], v161 offset:10832
	ds_read_b128 v[132:135], v161 offset:10848
	ds_read_b128 v[136:139], v161 offset:10864
	ds_read_b128 v[140:143], v161 offset:10880
	s_waitcnt lgkmcnt(12)
	v_pk_fma_f32 v[250:251], v[80:81], v[30:31], v[250:251] neg_lo:[1,0,0] neg_hi:[1,0,0]
	v_pk_fma_f32 v[252:253], v[82:83], v[32:33], v[252:253] neg_lo:[1,0,0] neg_hi:[1,0,0]
	v_pk_fma_f32 v[250:251], v[84:85], v[34:35], v[250:251] neg_lo:[1,0,0] neg_hi:[1,0,0]
	v_pk_fma_f32 v[252:253], v[86:87], v[36:37], v[252:253] neg_lo:[1,0,0] neg_hi:[1,0,0]
	v_pk_fma_f32 v[250:251], v[88:89], v[38:39], v[250:251] neg_lo:[1,0,0] neg_hi:[1,0,0]
	v_pk_fma_f32 v[252:253], v[90:91], v[40:41], v[252:253] neg_lo:[1,0,0] neg_hi:[1,0,0]
	v_pk_fma_f32 v[250:251], v[92:93], v[42:43], v[250:251] neg_lo:[1,0,0] neg_hi:[1,0,0]
	v_pk_fma_f32 v[252:253], v[94:95], v[44:45], v[252:253] neg_lo:[1,0,0] neg_hi:[1,0,0]
	ds_read_b128 v[80:83], v161 offset:10896
	ds_read_b128 v[84:87], v161 offset:10912
	ds_read_b128 v[88:91], v161 offset:11008
	ds_read_b128 v[92:95], v161 offset:11024
	s_waitcnt lgkmcnt(12)
	v_pk_fma_f32 v[250:251], v[96:97], v[46:47], v[250:251] neg_lo:[1,0,0] neg_hi:[1,0,0]
	v_pk_fma_f32 v[252:253], v[98:99], v[48:49], v[252:253] neg_lo:[1,0,0] neg_hi:[1,0,0]
	v_pk_fma_f32 v[250:251], v[100:101], v[50:51], v[250:251] neg_lo:[1,0,0] neg_hi:[1,0,0]
	v_pk_fma_f32 v[252:253], v[102:103], v[52:53], v[252:253] neg_lo:[1,0,0] neg_hi:[1,0,0]
	v_pk_fma_f32 v[250:251], v[104:105], v[54:55], v[250:251] neg_lo:[1,0,0] neg_hi:[1,0,0]
	v_pk_fma_f32 v[252:253], v[106:107], v[56:57], v[252:253] neg_lo:[1,0,0] neg_hi:[1,0,0]
	v_add_f32_e32 v250, v250, v251
	v_add_f32_e32 v252, v252, v253
	v_add_f32_e32 v55, v250, v252
	v_subrev_u32_e32 v249, 42, v208
	v_cvt_f32_i32_e32 v249, v249
	v_sub_f32_e64 v254, 1.0, |v249| clamp
	v_pk_fma_f32 v[250:251], v[108:109], v[0:1], v[254:255] neg_lo:[1,0,0] neg_hi:[1,0,0]
	v_pk_fma_f32 v[252:253], v[110:111], v[2:3], 0 neg_lo:[1,0,0] neg_hi:[1,0,0]
	ds_read_b128 v[96:99], v161 offset:11040
	ds_read_b128 v[100:103], v161 offset:11056
	ds_read_b128 v[104:107], v161 offset:11072
	ds_read_b128 v[108:111], v161 offset:11088
	s_waitcnt lgkmcnt(12)
	v_pk_fma_f32 v[250:251], v[112:113], v[4:5], v[250:251] neg_lo:[1,0,0] neg_hi:[1,0,0]
	v_pk_fma_f32 v[252:253], v[114:115], v[6:7], v[252:253] neg_lo:[1,0,0] neg_hi:[1,0,0]
	v_pk_fma_f32 v[250:251], v[116:117], v[22:23], v[250:251] neg_lo:[1,0,0] neg_hi:[1,0,0]
	v_pk_fma_f32 v[252:253], v[118:119], v[24:25], v[252:253] neg_lo:[1,0,0] neg_hi:[1,0,0]
	v_pk_fma_f32 v[250:251], v[120:121], v[26:27], v[250:251] neg_lo:[1,0,0] neg_hi:[1,0,0]
	v_pk_fma_f32 v[252:253], v[122:123], v[28:29], v[252:253] neg_lo:[1,0,0] neg_hi:[1,0,0]
	v_pk_fma_f32 v[250:251], v[124:125], v[30:31], v[250:251] neg_lo:[1,0,0] neg_hi:[1,0,0]
	v_pk_fma_f32 v[252:253], v[126:127], v[32:33], v[252:253] neg_lo:[1,0,0] neg_hi:[1,0,0]
	ds_read_b128 v[112:115], v161 offset:11104
	ds_read_b128 v[116:119], v161 offset:11120
	ds_read_b128 v[120:123], v161 offset:11136
	ds_read_b128 v[124:127], v161 offset:11152
	s_waitcnt lgkmcnt(12)
	v_pk_fma_f32 v[250:251], v[128:129], v[34:35], v[250:251] neg_lo:[1,0,0] neg_hi:[1,0,0]
	v_pk_fma_f32 v[252:253], v[130:131], v[36:37], v[252:253] neg_lo:[1,0,0] neg_hi:[1,0,0]
	v_pk_fma_f32 v[250:251], v[132:133], v[38:39], v[250:251] neg_lo:[1,0,0] neg_hi:[1,0,0]
	v_pk_fma_f32 v[252:253], v[134:135], v[40:41], v[252:253] neg_lo:[1,0,0] neg_hi:[1,0,0]
	v_pk_fma_f32 v[250:251], v[136:137], v[42:43], v[250:251] neg_lo:[1,0,0] neg_hi:[1,0,0]
	v_pk_fma_f32 v[252:253], v[138:139], v[44:45], v[252:253] neg_lo:[1,0,0] neg_hi:[1,0,0]
	v_pk_fma_f32 v[250:251], v[140:141], v[46:47], v[250:251] neg_lo:[1,0,0] neg_hi:[1,0,0]
	v_pk_fma_f32 v[252:253], v[142:143], v[48:49], v[252:253] neg_lo:[1,0,0] neg_hi:[1,0,0]
	ds_read_b128 v[128:131], v161 offset:11168
	ds_read_b128 v[132:135], v161 offset:11264
	ds_read_b128 v[136:139], v161 offset:11280
	ds_read_b128 v[140:143], v161 offset:11296
	s_waitcnt lgkmcnt(12)
	v_pk_fma_f32 v[250:251], v[80:81], v[50:51], v[250:251] neg_lo:[1,0,0] neg_hi:[1,0,0]
	v_pk_fma_f32 v[252:253], v[82:83], v[52:53], v[252:253] neg_lo:[1,0,0] neg_hi:[1,0,0]
	v_pk_fma_f32 v[250:251], v[84:85], v[54:55], v[250:251] neg_lo:[1,0,0] neg_hi:[1,0,0]
	v_pk_fma_f32 v[252:253], v[86:87], v[56:57], v[252:253] neg_lo:[1,0,0] neg_hi:[1,0,0]
	v_add_f32_e32 v250, v250, v251
	v_add_f32_e32 v252, v252, v253
	v_add_f32_e32 v56, v250, v252
	v_subrev_u32_e32 v249, 43, v208
	v_cvt_f32_i32_e32 v249, v249
	v_sub_f32_e64 v254, 1.0, |v249| clamp
	v_pk_fma_f32 v[250:251], v[88:89], v[0:1], v[254:255] neg_lo:[1,0,0] neg_hi:[1,0,0]
	v_pk_fma_f32 v[252:253], v[90:91], v[2:3], 0 neg_lo:[1,0,0] neg_hi:[1,0,0]
	v_pk_fma_f32 v[250:251], v[92:93], v[4:5], v[250:251] neg_lo:[1,0,0] neg_hi:[1,0,0]
	v_pk_fma_f32 v[252:253], v[94:95], v[6:7], v[252:253] neg_lo:[1,0,0] neg_hi:[1,0,0]
	ds_read_b128 v[80:83], v161 offset:11312
	ds_read_b128 v[84:87], v161 offset:11328
	ds_read_b128 v[88:91], v161 offset:11344
	ds_read_b128 v[92:95], v161 offset:11360
	s_waitcnt lgkmcnt(12)
	v_pk_fma_f32 v[250:251], v[96:97], v[22:23], v[250:251] neg_lo:[1,0,0] neg_hi:[1,0,0]
	v_pk_fma_f32 v[252:253], v[98:99], v[24:25], v[252:253] neg_lo:[1,0,0] neg_hi:[1,0,0]
	v_pk_fma_f32 v[250:251], v[100:101], v[26:27], v[250:251] neg_lo:[1,0,0] neg_hi:[1,0,0]
	v_pk_fma_f32 v[252:253], v[102:103], v[28:29], v[252:253] neg_lo:[1,0,0] neg_hi:[1,0,0]
	v_pk_fma_f32 v[250:251], v[104:105], v[30:31], v[250:251] neg_lo:[1,0,0] neg_hi:[1,0,0]
	v_pk_fma_f32 v[252:253], v[106:107], v[32:33], v[252:253] neg_lo:[1,0,0] neg_hi:[1,0,0]
	v_pk_fma_f32 v[250:251], v[108:109], v[34:35], v[250:251] neg_lo:[1,0,0] neg_hi:[1,0,0]
	v_pk_fma_f32 v[252:253], v[110:111], v[36:37], v[252:253] neg_lo:[1,0,0] neg_hi:[1,0,0]
	ds_read_b128 v[96:99], v161 offset:11376
	ds_read_b128 v[100:103], v161 offset:11392
	ds_read_b128 v[104:107], v161 offset:11408
	ds_read_b128 v[108:111], v161 offset:11424
	s_waitcnt lgkmcnt(12)
	v_pk_fma_f32 v[250:251], v[112:113], v[38:39], v[250:251] neg_lo:[1,0,0] neg_hi:[1,0,0]
	v_pk_fma_f32 v[252:253], v[114:115], v[40:41], v[252:253] neg_lo:[1,0,0] neg_hi:[1,0,0]
	v_pk_fma_f32 v[250:251], v[116:117], v[42:43], v[250:251] neg_lo:[1,0,0] neg_hi:[1,0,0]
	v_pk_fma_f32 v[252:253], v[118:119], v[44:45], v[252:253] neg_lo:[1,0,0] neg_hi:[1,0,0]
	v_pk_fma_f32 v[250:251], v[120:121], v[46:47], v[250:251] neg_lo:[1,0,0] neg_hi:[1,0,0]
	v_pk_fma_f32 v[252:253], v[122:123], v[48:49], v[252:253] neg_lo:[1,0,0] neg_hi:[1,0,0]
	v_pk_fma_f32 v[250:251], v[124:125], v[50:51], v[250:251] neg_lo:[1,0,0] neg_hi:[1,0,0]
	v_pk_fma_f32 v[252:253], v[126:127], v[52:53], v[252:253] neg_lo:[1,0,0] neg_hi:[1,0,0]
	ds_read_b128 v[112:115], v161 offset:11520
	ds_read_b128 v[116:119], v161 offset:11536
	ds_read_b128 v[120:123], v161 offset:11552
	ds_read_b128 v[124:127], v161 offset:11568
	s_waitcnt lgkmcnt(12)
	v_pk_fma_f32 v[250:251], v[128:129], v[54:55], v[250:251] neg_lo:[1,0,0] neg_hi:[1,0,0]
	v_pk_fma_f32 v[252:253], v[130:131], v[56:57], v[252:253] neg_lo:[1,0,0] neg_hi:[1,0,0]
	v_add_f32_e32 v250, v250, v251
	v_add_f32_e32 v252, v252, v253
	v_add_f32_e32 v57, v250, v252
	v_subrev_u32_e32 v249, 44, v208
	v_cvt_f32_i32_e32 v249, v249
	v_sub_f32_e64 v254, 1.0, |v249| clamp
	v_pk_fma_f32 v[250:251], v[132:133], v[0:1], v[254:255] neg_lo:[1,0,0] neg_hi:[1,0,0]
	v_pk_fma_f32 v[252:253], v[134:135], v[2:3], 0 neg_lo:[1,0,0] neg_hi:[1,0,0]
	v_pk_fma_f32 v[250:251], v[136:137], v[4:5], v[250:251] neg_lo:[1,0,0] neg_hi:[1,0,0]
	v_pk_fma_f32 v[252:253], v[138:139], v[6:7], v[252:253] neg_lo:[1,0,0] neg_hi:[1,0,0]
	v_pk_fma_f32 v[250:251], v[140:141], v[22:23], v[250:251] neg_lo:[1,0,0] neg_hi:[1,0,0]
	v_pk_fma_f32 v[252:253], v[142:143], v[24:25], v[252:253] neg_lo:[1,0,0] neg_hi:[1,0,0]
	ds_read_b128 v[128:131], v161 offset:11584
	ds_read_b128 v[132:135], v161 offset:11600
	ds_read_b128 v[136:139], v161 offset:11616
	ds_read_b128 v[140:143], v161 offset:11632
	s_waitcnt lgkmcnt(12)
	v_pk_fma_f32 v[250:251], v[80:81], v[26:27], v[250:251] neg_lo:[1,0,0] neg_hi:[1,0,0]
	v_pk_fma_f32 v[252:253], v[82:83], v[28:29], v[252:253] neg_lo:[1,0,0] neg_hi:[1,0,0]
	v_pk_fma_f32 v[250:251], v[84:85], v[30:31], v[250:251] neg_lo:[1,0,0] neg_hi:[1,0,0]
	v_pk_fma_f32 v[252:253], v[86:87], v[32:33], v[252:253] neg_lo:[1,0,0] neg_hi:[1,0,0]
	v_pk_fma_f32 v[250:251], v[88:89], v[34:35], v[250:251] neg_lo:[1,0,0] neg_hi:[1,0,0]
	v_pk_fma_f32 v[252:253], v[90:91], v[36:37], v[252:253] neg_lo:[1,0,0] neg_hi:[1,0,0]
	v_pk_fma_f32 v[250:251], v[92:93], v[38:39], v[250:251] neg_lo:[1,0,0] neg_hi:[1,0,0]
	v_pk_fma_f32 v[252:253], v[94:95], v[40:41], v[252:253] neg_lo:[1,0,0] neg_hi:[1,0,0]
	ds_read_b128 v[80:83], v161 offset:11648
	ds_read_b128 v[84:87], v161 offset:11664
	ds_read_b128 v[88:91], v161 offset:11680
	ds_read_b128 v[92:95], v161 offset:11696
	s_waitcnt lgkmcnt(12)
	v_pk_fma_f32 v[250:251], v[96:97], v[42:43], v[250:251] neg_lo:[1,0,0] neg_hi:[1,0,0]
	v_pk_fma_f32 v[252:253], v[98:99], v[44:45], v[252:253] neg_lo:[1,0,0] neg_hi:[1,0,0]
	v_pk_fma_f32 v[250:251], v[100:101], v[46:47], v[250:251] neg_lo:[1,0,0] neg_hi:[1,0,0]
	v_pk_fma_f32 v[252:253], v[102:103], v[48:49], v[252:253] neg_lo:[1,0,0] neg_hi:[1,0,0]
	v_pk_fma_f32 v[250:251], v[104:105], v[50:51], v[250:251] neg_lo:[1,0,0] neg_hi:[1,0,0]
	v_pk_fma_f32 v[252:253], v[106:107], v[52:53], v[252:253] neg_lo:[1,0,0] neg_hi:[1,0,0]
	v_pk_fma_f32 v[250:251], v[108:109], v[54:55], v[250:251] neg_lo:[1,0,0] neg_hi:[1,0,0]
	v_pk_fma_f32 v[252:253], v[110:111], v[56:57], v[252:253] neg_lo:[1,0,0] neg_hi:[1,0,0]
	v_add_f32_e32 v250, v250, v251
	v_add_f32_e32 v252, v252, v253
	v_add_f32_e32 v58, v250, v252
	ds_read_b128 v[96:99], v161 offset:11776
	ds_read_b128 v[100:103], v161 offset:11792
	ds_read_b128 v[104:107], v161 offset:11808
	ds_read_b128 v[108:111], v161 offset:11824
	s_waitcnt lgkmcnt(12)
	v_subrev_u32_e32 v249, 45, v208
	v_cvt_f32_i32_e32 v249, v249
	v_sub_f32_e64 v254, 1.0, |v249| clamp
	v_pk_fma_f32 v[250:251], v[112:113], v[0:1], v[254:255] neg_lo:[1,0,0] neg_hi:[1,0,0]
	v_pk_fma_f32 v[252:253], v[114:115], v[2:3], 0 neg_lo:[1,0,0] neg_hi:[1,0,0]
	v_pk_fma_f32 v[250:251], v[116:117], v[4:5], v[250:251] neg_lo:[1,0,0] neg_hi:[1,0,0]
	v_pk_fma_f32 v[252:253], v[118:119], v[6:7], v[252:253] neg_lo:[1,0,0] neg_hi:[1,0,0]
	v_pk_fma_f32 v[250:251], v[120:121], v[22:23], v[250:251] neg_lo:[1,0,0] neg_hi:[1,0,0]
	v_pk_fma_f32 v[252:253], v[122:123], v[24:25], v[252:253] neg_lo:[1,0,0] neg_hi:[1,0,0]
	v_pk_fma_f32 v[250:251], v[124:125], v[26:27], v[250:251] neg_lo:[1,0,0] neg_hi:[1,0,0]
	v_pk_fma_f32 v[252:253], v[126:127], v[28:29], v[252:253] neg_lo:[1,0,0] neg_hi:[1,0,0]
	ds_read_b128 v[112:115], v161 offset:11840
	ds_read_b128 v[116:119], v161 offset:11856
	ds_read_b128 v[120:123], v161 offset:11872
	ds_read_b128 v[124:127], v161 offset:11888
	s_waitcnt lgkmcnt(12)
	v_pk_fma_f32 v[250:251], v[128:129], v[30:31], v[250:251] neg_lo:[1,0,0] neg_hi:[1,0,0]
	v_pk_fma_f32 v[252:253], v[130:131], v[32:33], v[252:253] neg_lo:[1,0,0] neg_hi:[1,0,0]
	v_pk_fma_f32 v[250:251], v[132:133], v[34:35], v[250:251] neg_lo:[1,0,0] neg_hi:[1,0,0]
	v_pk_fma_f32 v[252:253], v[134:135], v[36:37], v[252:253] neg_lo:[1,0,0] neg_hi:[1,0,0]
	v_pk_fma_f32 v[250:251], v[136:137], v[38:39], v[250:251] neg_lo:[1,0,0] neg_hi:[1,0,0]
	v_pk_fma_f32 v[252:253], v[138:139], v[40:41], v[252:253] neg_lo:[1,0,0] neg_hi:[1,0,0]
	v_pk_fma_f32 v[250:251], v[140:141], v[42:43], v[250:251] neg_lo:[1,0,0] neg_hi:[1,0,0]
	v_pk_fma_f32 v[252:253], v[142:143], v[44:45], v[252:253] neg_lo:[1,0,0] neg_hi:[1,0,0]
	ds_read_b128 v[128:131], v161 offset:11904
	ds_read_b128 v[132:135], v161 offset:11920
	ds_read_b128 v[136:139], v161 offset:11936
	ds_read_b128 v[140:143], v161 offset:11952
	s_waitcnt lgkmcnt(12)
	v_pk_fma_f32 v[250:251], v[80:81], v[46:47], v[250:251] neg_lo:[1,0,0] neg_hi:[1,0,0]
	v_pk_fma_f32 v[252:253], v[82:83], v[48:49], v[252:253] neg_lo:[1,0,0] neg_hi:[1,0,0]
	v_pk_fma_f32 v[250:251], v[84:85], v[50:51], v[250:251] neg_lo:[1,0,0] neg_hi:[1,0,0]
	v_pk_fma_f32 v[252:253], v[86:87], v[52:53], v[252:253] neg_lo:[1,0,0] neg_hi:[1,0,0]
	v_pk_fma_f32 v[250:251], v[88:89], v[54:55], v[250:251] neg_lo:[1,0,0] neg_hi:[1,0,0]
	v_pk_fma_f32 v[252:253], v[90:91], v[56:57], v[252:253] neg_lo:[1,0,0] neg_hi:[1,0,0]
	v_pk_fma_f32 v[250:251], v[92:93], v[58:59], v[250:251] neg_lo:[1,0,0] neg_hi:[1,0,0]
	v_pk_fma_f32 v[252:253], v[94:95], v[60:61], v[252:253] neg_lo:[1,0,0] neg_hi:[1,0,0]
	v_add_f32_e32 v250, v250, v251
	v_add_f32_e32 v252, v252, v253
	v_add_f32_e32 v59, v250, v252
	ds_read_b128 v[80:83], v161 offset:12032
	ds_read_b128 v[84:87], v161 offset:12048
	ds_read_b128 v[88:91], v161 offset:12064
	ds_read_b128 v[92:95], v161 offset:12080
	s_waitcnt lgkmcnt(12)
	v_subrev_u32_e32 v249, 46, v208
	v_cvt_f32_i32_e32 v249, v249
	v_sub_f32_e64 v254, 1.0, |v249| clamp
	v_pk_fma_f32 v[250:251], v[96:97], v[0:1], v[254:255] neg_lo:[1,0,0] neg_hi:[1,0,0]
	v_pk_fma_f32 v[252:253], v[98:99], v[2:3], 0 neg_lo:[1,0,0] neg_hi:[1,0,0]
	v_pk_fma_f32 v[250:251], v[100:101], v[4:5], v[250:251] neg_lo:[1,0,0] neg_hi:[1,0,0]
	v_pk_fma_f32 v[252:253], v[102:103], v[6:7], v[252:253] neg_lo:[1,0,0] neg_hi:[1,0,0]
	v_pk_fma_f32 v[250:251], v[104:105], v[22:23], v[250:251] neg_lo:[1,0,0] neg_hi:[1,0,0]
	v_pk_fma_f32 v[252:253], v[106:107], v[24:25], v[252:253] neg_lo:[1,0,0] neg_hi:[1,0,0]
	v_pk_fma_f32 v[250:251], v[108:109], v[26:27], v[250:251] neg_lo:[1,0,0] neg_hi:[1,0,0]
	v_pk_fma_f32 v[252:253], v[110:111], v[28:29], v[252:253] neg_lo:[1,0,0] neg_hi:[1,0,0]
	ds_read_b128 v[96:99], v161 offset:12096
	ds_read_b128 v[100:103], v161 offset:12112
	ds_read_b128 v[104:107], v161 offset:12128
	ds_read_b128 v[108:111], v161 offset:12144
	s_waitcnt lgkmcnt(12)
	v_pk_fma_f32 v[250:251], v[112:113], v[30:31], v[250:251] neg_lo:[1,0,0] neg_hi:[1,0,0]
	v_pk_fma_f32 v[252:253], v[114:115], v[32:33], v[252:253] neg_lo:[1,0,0] neg_hi:[1,0,0]
	v_pk_fma_f32 v[250:251], v[116:117], v[34:35], v[250:251] neg_lo:[1,0,0] neg_hi:[1,0,0]
	v_pk_fma_f32 v[252:253], v[118:119], v[36:37], v[252:253] neg_lo:[1,0,0] neg_hi:[1,0,0]
	v_pk_fma_f32 v[250:251], v[120:121], v[38:39], v[250:251] neg_lo:[1,0,0] neg_hi:[1,0,0]
	v_pk_fma_f32 v[252:253], v[122:123], v[40:41], v[252:253] neg_lo:[1,0,0] neg_hi:[1,0,0]
	v_pk_fma_f32 v[250:251], v[124:125], v[42:43], v[250:251] neg_lo:[1,0,0] neg_hi:[1,0,0]
	v_pk_fma_f32 v[252:253], v[126:127], v[44:45], v[252:253] neg_lo:[1,0,0] neg_hi:[1,0,0]
	ds_read_b128 v[112:115], v161 offset:12160
	ds_read_b128 v[116:119], v161 offset:12176
	ds_read_b128 v[120:123], v161 offset:12192
	ds_read_b128 v[124:127], v161 offset:12208
	s_waitcnt lgkmcnt(12)
	v_pk_fma_f32 v[250:251], v[128:129], v[46:47], v[250:251] neg_lo:[1,0,0] neg_hi:[1,0,0]
	v_pk_fma_f32 v[252:253], v[130:131], v[48:49], v[252:253] neg_lo:[1,0,0] neg_hi:[1,0,0]
	v_pk_fma_f32 v[250:251], v[132:133], v[50:51], v[250:251] neg_lo:[1,0,0] neg_hi:[1,0,0]
	v_pk_fma_f32 v[252:253], v[134:135], v[52:53], v[252:253] neg_lo:[1,0,0] neg_hi:[1,0,0]
	v_pk_fma_f32 v[250:251], v[136:137], v[54:55], v[250:251] neg_lo:[1,0,0] neg_hi:[1,0,0]
	v_pk_fma_f32 v[252:253], v[138:139], v[56:57], v[252:253] neg_lo:[1,0,0] neg_hi:[1,0,0]
	v_pk_fma_f32 v[250:251], v[140:141], v[58:59], v[250:251] neg_lo:[1,0,0] neg_hi:[1,0,0]
	v_pk_fma_f32 v[252:253], v[142:143], v[60:61], v[252:253] neg_lo:[1,0,0] neg_hi:[1,0,0]
	v_add_f32_e32 v250, v250, v251
	v_add_f32_e32 v252, v252, v253
	v_add_f32_e32 v60, v250, v252
	ds_read_b128 v[128:131], v161 offset:12288
	ds_read_b128 v[132:135], v161 offset:12304
	ds_read_b128 v[136:139], v161 offset:12320
	ds_read_b128 v[140:143], v161 offset:12336
	s_waitcnt lgkmcnt(12)
	v_subrev_u32_e32 v249, 47, v208
	v_cvt_f32_i32_e32 v249, v249
	v_sub_f32_e64 v254, 1.0, |v249| clamp
	v_pk_fma_f32 v[250:251], v[80:81], v[0:1], v[254:255] neg_lo:[1,0,0] neg_hi:[1,0,0]
	v_pk_fma_f32 v[252:253], v[82:83], v[2:3], 0 neg_lo:[1,0,0] neg_hi:[1,0,0]
	v_pk_fma_f32 v[250:251], v[84:85], v[4:5], v[250:251] neg_lo:[1,0,0] neg_hi:[1,0,0]
	v_pk_fma_f32 v[252:253], v[86:87], v[6:7], v[252:253] neg_lo:[1,0,0] neg_hi:[1,0,0]
	v_pk_fma_f32 v[250:251], v[88:89], v[22:23], v[250:251] neg_lo:[1,0,0] neg_hi:[1,0,0]
	v_pk_fma_f32 v[252:253], v[90:91], v[24:25], v[252:253] neg_lo:[1,0,0] neg_hi:[1,0,0]
	v_pk_fma_f32 v[250:251], v[92:93], v[26:27], v[250:251] neg_lo:[1,0,0] neg_hi:[1,0,0]
	v_pk_fma_f32 v[252:253], v[94:95], v[28:29], v[252:253] neg_lo:[1,0,0] neg_hi:[1,0,0]
	ds_read_b128 v[80:83], v161 offset:12352
	ds_read_b128 v[84:87], v161 offset:12368
	ds_read_b128 v[88:91], v161 offset:12384
	ds_read_b128 v[92:95], v161 offset:12400
	s_waitcnt lgkmcnt(12)
	v_pk_fma_f32 v[250:251], v[96:97], v[30:31], v[250:251] neg_lo:[1,0,0] neg_hi:[1,0,0]
	v_pk_fma_f32 v[252:253], v[98:99], v[32:33], v[252:253] neg_lo:[1,0,0] neg_hi:[1,0,0]
	v_pk_fma_f32 v[250:251], v[100:101], v[34:35], v[250:251] neg_lo:[1,0,0] neg_hi:[1,0,0]
	v_pk_fma_f32 v[252:253], v[102:103], v[36:37], v[252:253] neg_lo:[1,0,0] neg_hi:[1,0,0]
	v_pk_fma_f32 v[250:251], v[104:105], v[38:39], v[250:251] neg_lo:[1,0,0] neg_hi:[1,0,0]
	v_pk_fma_f32 v[252:253], v[106:107], v[40:41], v[252:253] neg_lo:[1,0,0] neg_hi:[1,0,0]
	v_pk_fma_f32 v[250:251], v[108:109], v[42:43], v[250:251] neg_lo:[1,0,0] neg_hi:[1,0,0]
	v_pk_fma_f32 v[252:253], v[110:111], v[44:45], v[252:253] neg_lo:[1,0,0] neg_hi:[1,0,0]
	ds_read_b128 v[96:99], v161 offset:12416
	ds_read_b128 v[100:103], v161 offset:12432
	ds_read_b128 v[104:107], v161 offset:12448
	ds_read_b128 v[108:111], v161 offset:12464
	s_waitcnt lgkmcnt(12)
	v_pk_fma_f32 v[250:251], v[112:113], v[46:47], v[250:251] neg_lo:[1,0,0] neg_hi:[1,0,0]
	v_pk_fma_f32 v[252:253], v[114:115], v[48:49], v[252:253] neg_lo:[1,0,0] neg_hi:[1,0,0]
	v_pk_fma_f32 v[250:251], v[116:117], v[50:51], v[250:251] neg_lo:[1,0,0] neg_hi:[1,0,0]
	v_pk_fma_f32 v[252:253], v[118:119], v[52:53], v[252:253] neg_lo:[1,0,0] neg_hi:[1,0,0]
	v_pk_fma_f32 v[250:251], v[120:121], v[54:55], v[250:251] neg_lo:[1,0,0] neg_hi:[1,0,0]
	v_pk_fma_f32 v[252:253], v[122:123], v[56:57], v[252:253] neg_lo:[1,0,0] neg_hi:[1,0,0]
	v_pk_fma_f32 v[250:251], v[124:125], v[58:59], v[250:251] neg_lo:[1,0,0] neg_hi:[1,0,0]
	v_pk_fma_f32 v[252:253], v[126:127], v[60:61], v[252:253] neg_lo:[1,0,0] neg_hi:[1,0,0]
	v_add_f32_e32 v250, v250, v251
	v_add_f32_e32 v252, v252, v253
	v_add_f32_e32 v61, v250, v252
	ds_read_b128 v[112:115], v161 offset:12544
	ds_read_b128 v[116:119], v161 offset:12560
	ds_read_b128 v[120:123], v161 offset:12576
	ds_read_b128 v[124:127], v161 offset:12592
	s_waitcnt lgkmcnt(12)
	v_subrev_u32_e32 v249, 48, v208
	v_cvt_f32_i32_e32 v249, v249
	v_sub_f32_e64 v254, 1.0, |v249| clamp
	v_pk_fma_f32 v[250:251], v[128:129], v[0:1], v[254:255] neg_lo:[1,0,0] neg_hi:[1,0,0]
	v_pk_fma_f32 v[252:253], v[130:131], v[2:3], 0 neg_lo:[1,0,0] neg_hi:[1,0,0]
	v_pk_fma_f32 v[250:251], v[132:133], v[4:5], v[250:251] neg_lo:[1,0,0] neg_hi:[1,0,0]
	v_pk_fma_f32 v[252:253], v[134:135], v[6:7], v[252:253] neg_lo:[1,0,0] neg_hi:[1,0,0]
	v_pk_fma_f32 v[250:251], v[136:137], v[22:23], v[250:251] neg_lo:[1,0,0] neg_hi:[1,0,0]
	v_pk_fma_f32 v[252:253], v[138:139], v[24:25], v[252:253] neg_lo:[1,0,0] neg_hi:[1,0,0]
	v_pk_fma_f32 v[250:251], v[140:141], v[26:27], v[250:251] neg_lo:[1,0,0] neg_hi:[1,0,0]
	v_pk_fma_f32 v[252:253], v[142:143], v[28:29], v[252:253] neg_lo:[1,0,0] neg_hi:[1,0,0]
	ds_read_b128 v[128:131], v161 offset:12608
	ds_read_b128 v[132:135], v161 offset:12624
	ds_read_b128 v[136:139], v161 offset:12640
	ds_read_b128 v[140:143], v161 offset:12656
	s_waitcnt lgkmcnt(12)
	v_pk_fma_f32 v[250:251], v[80:81], v[30:31], v[250:251] neg_lo:[1,0,0] neg_hi:[1,0,0]
	v_pk_fma_f32 v[252:253], v[82:83], v[32:33], v[252:253] neg_lo:[1,0,0] neg_hi:[1,0,0]
	v_pk_fma_f32 v[250:251], v[84:85], v[34:35], v[250:251] neg_lo:[1,0,0] neg_hi:[1,0,0]
	v_pk_fma_f32 v[252:253], v[86:87], v[36:37], v[252:253] neg_lo:[1,0,0] neg_hi:[1,0,0]
	v_pk_fma_f32 v[250:251], v[88:89], v[38:39], v[250:251] neg_lo:[1,0,0] neg_hi:[1,0,0]
	v_pk_fma_f32 v[252:253], v[90:91], v[40:41], v[252:253] neg_lo:[1,0,0] neg_hi:[1,0,0]
	v_pk_fma_f32 v[250:251], v[92:93], v[42:43], v[250:251] neg_lo:[1,0,0] neg_hi:[1,0,0]
	v_pk_fma_f32 v[252:253], v[94:95], v[44:45], v[252:253] neg_lo:[1,0,0] neg_hi:[1,0,0]
	ds_read_b128 v[80:83], v161 offset:12672
	ds_read_b128 v[84:87], v161 offset:12688
	ds_read_b128 v[88:91], v161 offset:12704
	ds_read_b128 v[92:95], v161 offset:12720
	s_waitcnt lgkmcnt(12)
	v_pk_fma_f32 v[250:251], v[96:97], v[46:47], v[250:251] neg_lo:[1,0,0] neg_hi:[1,0,0]
	v_pk_fma_f32 v[252:253], v[98:99], v[48:49], v[252:253] neg_lo:[1,0,0] neg_hi:[1,0,0]
	v_pk_fma_f32 v[250:251], v[100:101], v[50:51], v[250:251] neg_lo:[1,0,0] neg_hi:[1,0,0]
	v_pk_fma_f32 v[252:253], v[102:103], v[52:53], v[252:253] neg_lo:[1,0,0] neg_hi:[1,0,0]
	v_pk_fma_f32 v[250:251], v[104:105], v[54:55], v[250:251] neg_lo:[1,0,0] neg_hi:[1,0,0]
	v_pk_fma_f32 v[252:253], v[106:107], v[56:57], v[252:253] neg_lo:[1,0,0] neg_hi:[1,0,0]
	v_pk_fma_f32 v[250:251], v[108:109], v[58:59], v[250:251] neg_lo:[1,0,0] neg_hi:[1,0,0]
	v_pk_fma_f32 v[252:253], v[110:111], v[60:61], v[252:253] neg_lo:[1,0,0] neg_hi:[1,0,0]
	v_add_f32_e32 v250, v250, v251
	v_add_f32_e32 v252, v252, v253
	v_add_f32_e32 v62, v250, v252
	ds_read_b128 v[96:99], v161 offset:12736
	ds_read_b128 v[100:103], v161 offset:12800
	ds_read_b128 v[104:107], v161 offset:12816
	ds_read_b128 v[108:111], v161 offset:12832
	s_waitcnt lgkmcnt(12)
	v_subrev_u32_e32 v249, 49, v208
	v_cvt_f32_i32_e32 v249, v249
	v_sub_f32_e64 v254, 1.0, |v249| clamp
	v_pk_fma_f32 v[250:251], v[112:113], v[0:1], v[254:255] neg_lo:[1,0,0] neg_hi:[1,0,0]
	v_pk_fma_f32 v[252:253], v[114:115], v[2:3], 0 neg_lo:[1,0,0] neg_hi:[1,0,0]
	v_pk_fma_f32 v[250:251], v[116:117], v[4:5], v[250:251] neg_lo:[1,0,0] neg_hi:[1,0,0]
	v_pk_fma_f32 v[252:253], v[118:119], v[6:7], v[252:253] neg_lo:[1,0,0] neg_hi:[1,0,0]
	v_pk_fma_f32 v[250:251], v[120:121], v[22:23], v[250:251] neg_lo:[1,0,0] neg_hi:[1,0,0]
	v_pk_fma_f32 v[252:253], v[122:123], v[24:25], v[252:253] neg_lo:[1,0,0] neg_hi:[1,0,0]
	v_pk_fma_f32 v[250:251], v[124:125], v[26:27], v[250:251] neg_lo:[1,0,0] neg_hi:[1,0,0]
	v_pk_fma_f32 v[252:253], v[126:127], v[28:29], v[252:253] neg_lo:[1,0,0] neg_hi:[1,0,0]
	ds_read_b128 v[112:115], v161 offset:12848
	ds_read_b128 v[116:119], v161 offset:12864
	ds_read_b128 v[120:123], v161 offset:12880
	ds_read_b128 v[124:127], v161 offset:12896
	s_waitcnt lgkmcnt(12)
	v_pk_fma_f32 v[250:251], v[128:129], v[30:31], v[250:251] neg_lo:[1,0,0] neg_hi:[1,0,0]
	v_pk_fma_f32 v[252:253], v[130:131], v[32:33], v[252:253] neg_lo:[1,0,0] neg_hi:[1,0,0]
	v_pk_fma_f32 v[250:251], v[132:133], v[34:35], v[250:251] neg_lo:[1,0,0] neg_hi:[1,0,0]
	v_pk_fma_f32 v[252:253], v[134:135], v[36:37], v[252:253] neg_lo:[1,0,0] neg_hi:[1,0,0]
	v_pk_fma_f32 v[250:251], v[136:137], v[38:39], v[250:251] neg_lo:[1,0,0] neg_hi:[1,0,0]
	v_pk_fma_f32 v[252:253], v[138:139], v[40:41], v[252:253] neg_lo:[1,0,0] neg_hi:[1,0,0]
	v_pk_fma_f32 v[250:251], v[140:141], v[42:43], v[250:251] neg_lo:[1,0,0] neg_hi:[1,0,0]
	v_pk_fma_f32 v[252:253], v[142:143], v[44:45], v[252:253] neg_lo:[1,0,0] neg_hi:[1,0,0]
	ds_read_b128 v[128:131], v161 offset:12912
	ds_read_b128 v[132:135], v161 offset:12928
	ds_read_b128 v[136:139], v161 offset:12944
	ds_read_b128 v[140:143], v161 offset:12960
	s_waitcnt lgkmcnt(12)
	v_pk_fma_f32 v[250:251], v[80:81], v[46:47], v[250:251] neg_lo:[1,0,0] neg_hi:[1,0,0]
	v_pk_fma_f32 v[252:253], v[82:83], v[48:49], v[252:253] neg_lo:[1,0,0] neg_hi:[1,0,0]
	v_pk_fma_f32 v[250:251], v[84:85], v[50:51], v[250:251] neg_lo:[1,0,0] neg_hi:[1,0,0]
	v_pk_fma_f32 v[252:253], v[86:87], v[52:53], v[252:253] neg_lo:[1,0,0] neg_hi:[1,0,0]
	v_pk_fma_f32 v[250:251], v[88:89], v[54:55], v[250:251] neg_lo:[1,0,0] neg_hi:[1,0,0]
	v_pk_fma_f32 v[252:253], v[90:91], v[56:57], v[252:253] neg_lo:[1,0,0] neg_hi:[1,0,0]
	v_pk_fma_f32 v[250:251], v[92:93], v[58:59], v[250:251] neg_lo:[1,0,0] neg_hi:[1,0,0]
	v_pk_fma_f32 v[252:253], v[94:95], v[60:61], v[252:253] neg_lo:[1,0,0] neg_hi:[1,0,0]
	ds_read_b128 v[80:83], v161 offset:12976
	ds_read_b128 v[84:87], v161 offset:12992
	ds_read_b128 v[88:91], v161 offset:13056
	ds_read_b128 v[92:95], v161 offset:13072
	s_waitcnt lgkmcnt(12)
	v_pk_fma_f32 v[250:251], v[96:97], v[62:63], v[250:251] neg_lo:[1,0,0] neg_hi:[1,0,0]
	v_pk_fma_f32 v[252:253], v[98:99], v[226:227], v[252:253] neg_lo:[1,0,0] neg_hi:[1,0,0]
	v_add_f32_e32 v250, v250, v251
	v_add_f32_e32 v252, v252, v253
	v_add_f32_e32 v63, v250, v252
	v_subrev_u32_e32 v249, 50, v208
	v_cvt_f32_i32_e32 v249, v249
	v_sub_f32_e64 v254, 1.0, |v249| clamp
	v_pk_fma_f32 v[250:251], v[100:101], v[0:1], v[254:255] neg_lo:[1,0,0] neg_hi:[1,0,0]
	v_pk_fma_f32 v[252:253], v[102:103], v[2:3], 0 neg_lo:[1,0,0] neg_hi:[1,0,0]
	v_pk_fma_f32 v[250:251], v[104:105], v[4:5], v[250:251] neg_lo:[1,0,0] neg_hi:[1,0,0]
	v_pk_fma_f32 v[252:253], v[106:107], v[6:7], v[252:253] neg_lo:[1,0,0] neg_hi:[1,0,0]
	v_pk_fma_f32 v[250:251], v[108:109], v[22:23], v[250:251] neg_lo:[1,0,0] neg_hi:[1,0,0]
	v_pk_fma_f32 v[252:253], v[110:111], v[24:25], v[252:253] neg_lo:[1,0,0] neg_hi:[1,0,0]
	ds_read_b128 v[96:99], v161 offset:13088
	ds_read_b128 v[100:103], v161 offset:13104
	ds_read_b128 v[104:107], v161 offset:13120
	ds_read_b128 v[108:111], v161 offset:13136
	s_waitcnt lgkmcnt(12)
	v_pk_fma_f32 v[250:251], v[112:113], v[26:27], v[250:251] neg_lo:[1,0,0] neg_hi:[1,0,0]
	v_pk_fma_f32 v[252:253], v[114:115], v[28:29], v[252:253] neg_lo:[1,0,0] neg_hi:[1,0,0]
	v_pk_fma_f32 v[250:251], v[116:117], v[30:31], v[250:251] neg_lo:[1,0,0] neg_hi:[1,0,0]
	v_pk_fma_f32 v[252:253], v[118:119], v[32:33], v[252:253] neg_lo:[1,0,0] neg_hi:[1,0,0]
	v_pk_fma_f32 v[250:251], v[120:121], v[34:35], v[250:251] neg_lo:[1,0,0] neg_hi:[1,0,0]
	v_pk_fma_f32 v[252:253], v[122:123], v[36:37], v[252:253] neg_lo:[1,0,0] neg_hi:[1,0,0]
	v_pk_fma_f32 v[250:251], v[124:125], v[38:39], v[250:251] neg_lo:[1,0,0] neg_hi:[1,0,0]
	v_pk_fma_f32 v[252:253], v[126:127], v[40:41], v[252:253] neg_lo:[1,0,0] neg_hi:[1,0,0]
	ds_read_b128 v[112:115], v161 offset:13152
	ds_read_b128 v[116:119], v161 offset:13168
	ds_read_b128 v[120:123], v161 offset:13184
	ds_read_b128 v[124:127], v161 offset:13200
	s_waitcnt lgkmcnt(12)
	v_pk_fma_f32 v[250:251], v[128:129], v[42:43], v[250:251] neg_lo:[1,0,0] neg_hi:[1,0,0]
	v_pk_fma_f32 v[252:253], v[130:131], v[44:45], v[252:253] neg_lo:[1,0,0] neg_hi:[1,0,0]
	v_pk_fma_f32 v[250:251], v[132:133], v[46:47], v[250:251] neg_lo:[1,0,0] neg_hi:[1,0,0]
	v_pk_fma_f32 v[252:253], v[134:135], v[48:49], v[252:253] neg_lo:[1,0,0] neg_hi:[1,0,0]
	v_pk_fma_f32 v[250:251], v[136:137], v[50:51], v[250:251] neg_lo:[1,0,0] neg_hi:[1,0,0]
	v_pk_fma_f32 v[252:253], v[138:139], v[52:53], v[252:253] neg_lo:[1,0,0] neg_hi:[1,0,0]
	v_pk_fma_f32 v[250:251], v[140:141], v[54:55], v[250:251] neg_lo:[1,0,0] neg_hi:[1,0,0]
	v_pk_fma_f32 v[252:253], v[142:143], v[56:57], v[252:253] neg_lo:[1,0,0] neg_hi:[1,0,0]
	ds_read_b128 v[128:131], v161 offset:13216
	ds_read_b128 v[132:135], v161 offset:13232
	ds_read_b128 v[136:139], v161 offset:13248
	ds_read_b128 v[140:143], v161 offset:13312
	s_waitcnt lgkmcnt(12)
	v_pk_fma_f32 v[250:251], v[80:81], v[58:59], v[250:251] neg_lo:[1,0,0] neg_hi:[1,0,0]
	v_pk_fma_f32 v[252:253], v[82:83], v[60:61], v[252:253] neg_lo:[1,0,0] neg_hi:[1,0,0]
	v_pk_fma_f32 v[250:251], v[84:85], v[62:63], v[250:251] neg_lo:[1,0,0] neg_hi:[1,0,0]
	v_pk_fma_f32 v[252:253], v[86:87], v[226:227], v[252:253] neg_lo:[1,0,0] neg_hi:[1,0,0]
	v_add_f32_e32 v250, v250, v251
	v_add_f32_e32 v252, v252, v253
	v_add_f32_e32 v226, v250, v252
	v_subrev_u32_e32 v249, 51, v208
	v_cvt_f32_i32_e32 v249, v249
	v_sub_f32_e64 v254, 1.0, |v249| clamp
	v_pk_fma_f32 v[250:251], v[88:89], v[0:1], v[254:255] neg_lo:[1,0,0] neg_hi:[1,0,0]
	v_pk_fma_f32 v[252:253], v[90:91], v[2:3], 0 neg_lo:[1,0,0] neg_hi:[1,0,0]
	v_pk_fma_f32 v[250:251], v[92:93], v[4:5], v[250:251] neg_lo:[1,0,0] neg_hi:[1,0,0]
	v_pk_fma_f32 v[252:253], v[94:95], v[6:7], v[252:253] neg_lo:[1,0,0] neg_hi:[1,0,0]
	ds_read_b128 v[80:83], v161 offset:13328
	ds_read_b128 v[84:87], v161 offset:13344
	ds_read_b128 v[88:91], v161 offset:13360
	ds_read_b128 v[92:95], v161 offset:13376
	s_waitcnt lgkmcnt(12)
	v_pk_fma_f32 v[250:251], v[96:97], v[22:23], v[250:251] neg_lo:[1,0,0] neg_hi:[1,0,0]
	v_pk_fma_f32 v[252:253], v[98:99], v[24:25], v[252:253] neg_lo:[1,0,0] neg_hi:[1,0,0]
	v_pk_fma_f32 v[250:251], v[100:101], v[26:27], v[250:251] neg_lo:[1,0,0] neg_hi:[1,0,0]
	v_pk_fma_f32 v[252:253], v[102:103], v[28:29], v[252:253] neg_lo:[1,0,0] neg_hi:[1,0,0]
	v_pk_fma_f32 v[250:251], v[104:105], v[30:31], v[250:251] neg_lo:[1,0,0] neg_hi:[1,0,0]
	v_pk_fma_f32 v[252:253], v[106:107], v[32:33], v[252:253] neg_lo:[1,0,0] neg_hi:[1,0,0]
	v_pk_fma_f32 v[250:251], v[108:109], v[34:35], v[250:251] neg_lo:[1,0,0] neg_hi:[1,0,0]
	v_pk_fma_f32 v[252:253], v[110:111], v[36:37], v[252:253] neg_lo:[1,0,0] neg_hi:[1,0,0]
	ds_read_b128 v[96:99], v161 offset:13392
	ds_read_b128 v[100:103], v161 offset:13408
	ds_read_b128 v[104:107], v161 offset:13424
	ds_read_b128 v[108:111], v161 offset:13440
	s_waitcnt lgkmcnt(12)
	v_pk_fma_f32 v[250:251], v[112:113], v[38:39], v[250:251] neg_lo:[1,0,0] neg_hi:[1,0,0]
	v_pk_fma_f32 v[252:253], v[114:115], v[40:41], v[252:253] neg_lo:[1,0,0] neg_hi:[1,0,0]
	v_pk_fma_f32 v[250:251], v[116:117], v[42:43], v[250:251] neg_lo:[1,0,0] neg_hi:[1,0,0]
	v_pk_fma_f32 v[252:253], v[118:119], v[44:45], v[252:253] neg_lo:[1,0,0] neg_hi:[1,0,0]
	v_pk_fma_f32 v[250:251], v[120:121], v[46:47], v[250:251] neg_lo:[1,0,0] neg_hi:[1,0,0]
	v_pk_fma_f32 v[252:253], v[122:123], v[48:49], v[252:253] neg_lo:[1,0,0] neg_hi:[1,0,0]
	v_pk_fma_f32 v[250:251], v[124:125], v[50:51], v[250:251] neg_lo:[1,0,0] neg_hi:[1,0,0]
	v_pk_fma_f32 v[252:253], v[126:127], v[52:53], v[252:253] neg_lo:[1,0,0] neg_hi:[1,0,0]
	ds_read_b128 v[112:115], v161 offset:13456
	ds_read_b128 v[116:119], v161 offset:13472
	ds_read_b128 v[120:123], v161 offset:13488
	ds_read_b128 v[124:127], v161 offset:13504
	s_waitcnt lgkmcnt(12)
	v_pk_fma_f32 v[250:251], v[128:129], v[54:55], v[250:251] neg_lo:[1,0,0] neg_hi:[1,0,0]
	v_pk_fma_f32 v[252:253], v[130:131], v[56:57], v[252:253] neg_lo:[1,0,0] neg_hi:[1,0,0]
	v_pk_fma_f32 v[250:251], v[132:133], v[58:59], v[250:251] neg_lo:[1,0,0] neg_hi:[1,0,0]
	v_pk_fma_f32 v[252:253], v[134:135], v[60:61], v[252:253] neg_lo:[1,0,0] neg_hi:[1,0,0]
	v_pk_fma_f32 v[250:251], v[136:137], v[62:63], v[250:251] neg_lo:[1,0,0] neg_hi:[1,0,0]
	v_pk_fma_f32 v[252:253], v[138:139], v[226:227], v[252:253] neg_lo:[1,0,0] neg_hi:[1,0,0]
	v_add_f32_e32 v250, v250, v251
	v_add_f32_e32 v252, v252, v253
	v_add_f32_e32 v227, v250, v252
	v_subrev_u32_e32 v249, 52, v208
	v_cvt_f32_i32_e32 v249, v249
	v_sub_f32_e64 v254, 1.0, |v249| clamp
	v_pk_fma_f32 v[250:251], v[140:141], v[0:1], v[254:255] neg_lo:[1,0,0] neg_hi:[1,0,0]
	v_pk_fma_f32 v[252:253], v[142:143], v[2:3], 0 neg_lo:[1,0,0] neg_hi:[1,0,0]
	ds_read_b128 v[128:131], v161 offset:13568
	ds_read_b128 v[132:135], v161 offset:13584
	ds_read_b128 v[136:139], v161 offset:13600
	ds_read_b128 v[140:143], v161 offset:13616
	s_waitcnt lgkmcnt(12)
	v_pk_fma_f32 v[250:251], v[80:81], v[4:5], v[250:251] neg_lo:[1,0,0] neg_hi:[1,0,0]
	v_pk_fma_f32 v[252:253], v[82:83], v[6:7], v[252:253] neg_lo:[1,0,0] neg_hi:[1,0,0]
	v_pk_fma_f32 v[250:251], v[84:85], v[22:23], v[250:251] neg_lo:[1,0,0] neg_hi:[1,0,0]
	v_pk_fma_f32 v[252:253], v[86:87], v[24:25], v[252:253] neg_lo:[1,0,0] neg_hi:[1,0,0]
	v_pk_fma_f32 v[250:251], v[88:89], v[26:27], v[250:251] neg_lo:[1,0,0] neg_hi:[1,0,0]
	v_pk_fma_f32 v[252:253], v[90:91], v[28:29], v[252:253] neg_lo:[1,0,0] neg_hi:[1,0,0]
	v_pk_fma_f32 v[250:251], v[92:93], v[30:31], v[250:251] neg_lo:[1,0,0] neg_hi:[1,0,0]
	v_pk_fma_f32 v[252:253], v[94:95], v[32:33], v[252:253] neg_lo:[1,0,0] neg_hi:[1,0,0]
	ds_read_b128 v[80:83], v161 offset:13632
	ds_read_b128 v[84:87], v161 offset:13648
	ds_read_b128 v[88:91], v161 offset:13664
	ds_read_b128 v[92:95], v161 offset:13680
	s_waitcnt lgkmcnt(12)
	v_pk_fma_f32 v[250:251], v[96:97], v[34:35], v[250:251] neg_lo:[1,0,0] neg_hi:[1,0,0]
	v_pk_fma_f32 v[252:253], v[98:99], v[36:37], v[252:253] neg_lo:[1,0,0] neg_hi:[1,0,0]
	v_pk_fma_f32 v[250:251], v[100:101], v[38:39], v[250:251] neg_lo:[1,0,0] neg_hi:[1,0,0]
	v_pk_fma_f32 v[252:253], v[102:103], v[40:41], v[252:253] neg_lo:[1,0,0] neg_hi:[1,0,0]
	v_pk_fma_f32 v[250:251], v[104:105], v[42:43], v[250:251] neg_lo:[1,0,0] neg_hi:[1,0,0]
	v_pk_fma_f32 v[252:253], v[106:107], v[44:45], v[252:253] neg_lo:[1,0,0] neg_hi:[1,0,0]
	v_pk_fma_f32 v[250:251], v[108:109], v[46:47], v[250:251] neg_lo:[1,0,0] neg_hi:[1,0,0]
	v_pk_fma_f32 v[252:253], v[110:111], v[48:49], v[252:253] neg_lo:[1,0,0] neg_hi:[1,0,0]
	ds_read_b128 v[96:99], v161 offset:13696
	ds_read_b128 v[100:103], v161 offset:13712
	ds_read_b128 v[104:107], v161 offset:13728
	ds_read_b128 v[108:111], v161 offset:13744
	s_waitcnt lgkmcnt(12)
	v_pk_fma_f32 v[250:251], v[112:113], v[50:51], v[250:251] neg_lo:[1,0,0] neg_hi:[1,0,0]
	v_pk_fma_f32 v[252:253], v[114:115], v[52:53], v[252:253] neg_lo:[1,0,0] neg_hi:[1,0,0]
	v_pk_fma_f32 v[250:251], v[116:117], v[54:55], v[250:251] neg_lo:[1,0,0] neg_hi:[1,0,0]
	v_pk_fma_f32 v[252:253], v[118:119], v[56:57], v[252:253] neg_lo:[1,0,0] neg_hi:[1,0,0]
	v_pk_fma_f32 v[250:251], v[120:121], v[58:59], v[250:251] neg_lo:[1,0,0] neg_hi:[1,0,0]
	v_pk_fma_f32 v[252:253], v[122:123], v[60:61], v[252:253] neg_lo:[1,0,0] neg_hi:[1,0,0]
	v_pk_fma_f32 v[250:251], v[124:125], v[62:63], v[250:251] neg_lo:[1,0,0] neg_hi:[1,0,0]
	v_pk_fma_f32 v[252:253], v[126:127], v[226:227], v[252:253] neg_lo:[1,0,0] neg_hi:[1,0,0]
	v_add_f32_e32 v250, v250, v251
	v_add_f32_e32 v252, v252, v253
	v_add_f32_e32 v228, v250, v252
	ds_read_b128 v[112:115], v161 offset:13760
	ds_read_b128 v[116:119], v161 offset:13776
	ds_read_b128 v[120:123], v161 offset:13824
	ds_read_b128 v[124:127], v161 offset:13840
	s_waitcnt lgkmcnt(12)
	v_subrev_u32_e32 v249, 53, v208
	v_cvt_f32_i32_e32 v249, v249
	v_sub_f32_e64 v254, 1.0, |v249| clamp
	v_pk_fma_f32 v[250:251], v[128:129], v[0:1], v[254:255] neg_lo:[1,0,0] neg_hi:[1,0,0]
	v_pk_fma_f32 v[252:253], v[130:131], v[2:3], 0 neg_lo:[1,0,0] neg_hi:[1,0,0]
	v_pk_fma_f32 v[250:251], v[132:133], v[4:5], v[250:251] neg_lo:[1,0,0] neg_hi:[1,0,0]
	v_pk_fma_f32 v[252:253], v[134:135], v[6:7], v[252:253] neg_lo:[1,0,0] neg_hi:[1,0,0]
	v_pk_fma_f32 v[250:251], v[136:137], v[22:23], v[250:251] neg_lo:[1,0,0] neg_hi:[1,0,0]
	v_pk_fma_f32 v[252:253], v[138:139], v[24:25], v[252:253] neg_lo:[1,0,0] neg_hi:[1,0,0]
	v_pk_fma_f32 v[250:251], v[140:141], v[26:27], v[250:251] neg_lo:[1,0,0] neg_hi:[1,0,0]
	v_pk_fma_f32 v[252:253], v[142:143], v[28:29], v[252:253] neg_lo:[1,0,0] neg_hi:[1,0,0]
	ds_read_b128 v[128:131], v161 offset:13856
	ds_read_b128 v[132:135], v161 offset:13872
	ds_read_b128 v[136:139], v161 offset:13888
	ds_read_b128 v[140:143], v161 offset:13904
	s_waitcnt lgkmcnt(12)
	v_pk_fma_f32 v[250:251], v[80:81], v[30:31], v[250:251] neg_lo:[1,0,0] neg_hi:[1,0,0]
	v_pk_fma_f32 v[252:253], v[82:83], v[32:33], v[252:253] neg_lo:[1,0,0] neg_hi:[1,0,0]
	v_pk_fma_f32 v[250:251], v[84:85], v[34:35], v[250:251] neg_lo:[1,0,0] neg_hi:[1,0,0]
	v_pk_fma_f32 v[252:253], v[86:87], v[36:37], v[252:253] neg_lo:[1,0,0] neg_hi:[1,0,0]
	v_pk_fma_f32 v[250:251], v[88:89], v[38:39], v[250:251] neg_lo:[1,0,0] neg_hi:[1,0,0]
	v_pk_fma_f32 v[252:253], v[90:91], v[40:41], v[252:253] neg_lo:[1,0,0] neg_hi:[1,0,0]
	v_pk_fma_f32 v[250:251], v[92:93], v[42:43], v[250:251] neg_lo:[1,0,0] neg_hi:[1,0,0]
	v_pk_fma_f32 v[252:253], v[94:95], v[44:45], v[252:253] neg_lo:[1,0,0] neg_hi:[1,0,0]
	ds_read_b128 v[80:83], v161 offset:13920
	ds_read_b128 v[84:87], v161 offset:13936
	ds_read_b128 v[88:91], v161 offset:13952
	ds_read_b128 v[92:95], v161 offset:13968
	s_waitcnt lgkmcnt(12)
	v_pk_fma_f32 v[250:251], v[96:97], v[46:47], v[250:251] neg_lo:[1,0,0] neg_hi:[1,0,0]
	v_pk_fma_f32 v[252:253], v[98:99], v[48:49], v[252:253] neg_lo:[1,0,0] neg_hi:[1,0,0]
	v_pk_fma_f32 v[250:251], v[100:101], v[50:51], v[250:251] neg_lo:[1,0,0] neg_hi:[1,0,0]
	v_pk_fma_f32 v[252:253], v[102:103], v[52:53], v[252:253] neg_lo:[1,0,0] neg_hi:[1,0,0]
	v_pk_fma_f32 v[250:251], v[104:105], v[54:55], v[250:251] neg_lo:[1,0,0] neg_hi:[1,0,0]
	v_pk_fma_f32 v[252:253], v[106:107], v[56:57], v[252:253] neg_lo:[1,0,0] neg_hi:[1,0,0]
	v_pk_fma_f32 v[250:251], v[108:109], v[58:59], v[250:251] neg_lo:[1,0,0] neg_hi:[1,0,0]
	v_pk_fma_f32 v[252:253], v[110:111], v[60:61], v[252:253] neg_lo:[1,0,0] neg_hi:[1,0,0]
	ds_read_b128 v[96:99], v161 offset:13984
	ds_read_b128 v[100:103], v161 offset:14000
	ds_read_b128 v[104:107], v161 offset:14016
	ds_read_b128 v[108:111], v161 offset:14032
	s_waitcnt lgkmcnt(12)
	v_pk_fma_f32 v[250:251], v[112:113], v[62:63], v[250:251] neg_lo:[1,0,0] neg_hi:[1,0,0]
	v_pk_fma_f32 v[252:253], v[114:115], v[226:227], v[252:253] neg_lo:[1,0,0] neg_hi:[1,0,0]
	v_pk_fma_f32 v[250:251], v[116:117], v[228:229], v[250:251] neg_lo:[1,0,0] neg_hi:[1,0,0]
	v_pk_fma_f32 v[252:253], v[118:119], v[230:231], v[252:253] neg_lo:[1,0,0] neg_hi:[1,0,0]
	v_add_f32_e32 v250, v250, v251
	v_add_f32_e32 v252, v252, v253
	v_add_f32_e32 v229, v250, v252
	v_subrev_u32_e32 v249, 54, v208
	v_cvt_f32_i32_e32 v249, v249
	v_sub_f32_e64 v254, 1.0, |v249| clamp
	v_pk_fma_f32 v[250:251], v[120:121], v[0:1], v[254:255] neg_lo:[1,0,0] neg_hi:[1,0,0]
	v_pk_fma_f32 v[252:253], v[122:123], v[2:3], 0 neg_lo:[1,0,0] neg_hi:[1,0,0]
	v_pk_fma_f32 v[250:251], v[124:125], v[4:5], v[250:251] neg_lo:[1,0,0] neg_hi:[1,0,0]
	v_pk_fma_f32 v[252:253], v[126:127], v[6:7], v[252:253] neg_lo:[1,0,0] neg_hi:[1,0,0]
	ds_read_b128 v[112:115], v161 offset:14080
	ds_read_b128 v[116:119], v161 offset:14096
	ds_read_b128 v[120:123], v161 offset:14112
	ds_read_b128 v[124:127], v161 offset:14128
	s_waitcnt lgkmcnt(12)
	v_pk_fma_f32 v[250:251], v[128:129], v[22:23], v[250:251] neg_lo:[1,0,0] neg_hi:[1,0,0]
	v_pk_fma_f32 v[252:253], v[130:131], v[24:25], v[252:253] neg_lo:[1,0,0] neg_hi:[1,0,0]
	v_pk_fma_f32 v[250:251], v[132:133], v[26:27], v[250:251] neg_lo:[1,0,0] neg_hi:[1,0,0]
	v_pk_fma_f32 v[252:253], v[134:135], v[28:29], v[252:253] neg_lo:[1,0,0] neg_hi:[1,0,0]
	v_pk_fma_f32 v[250:251], v[136:137], v[30:31], v[250:251] neg_lo:[1,0,0] neg_hi:[1,0,0]
	v_pk_fma_f32 v[252:253], v[138:139], v[32:33], v[252:253] neg_lo:[1,0,0] neg_hi:[1,0,0]
	v_pk_fma_f32 v[250:251], v[140:141], v[34:35], v[250:251] neg_lo:[1,0,0] neg_hi:[1,0,0]
	v_pk_fma_f32 v[252:253], v[142:143], v[36:37], v[252:253] neg_lo:[1,0,0] neg_hi:[1,0,0]
	ds_read_b128 v[128:131], v161 offset:14144
	ds_read_b128 v[132:135], v161 offset:14160
	ds_read_b128 v[136:139], v161 offset:14176
	ds_read_b128 v[140:143], v161 offset:14192
	s_waitcnt lgkmcnt(12)
	v_pk_fma_f32 v[250:251], v[80:81], v[38:39], v[250:251] neg_lo:[1,0,0] neg_hi:[1,0,0]
	v_pk_fma_f32 v[252:253], v[82:83], v[40:41], v[252:253] neg_lo:[1,0,0] neg_hi:[1,0,0]
	v_pk_fma_f32 v[250:251], v[84:85], v[42:43], v[250:251] neg_lo:[1,0,0] neg_hi:[1,0,0]
	v_pk_fma_f32 v[252:253], v[86:87], v[44:45], v[252:253] neg_lo:[1,0,0] neg_hi:[1,0,0]
	v_pk_fma_f32 v[250:251], v[88:89], v[46:47], v[250:251] neg_lo:[1,0,0] neg_hi:[1,0,0]
	v_pk_fma_f32 v[252:253], v[90:91], v[48:49], v[252:253] neg_lo:[1,0,0] neg_hi:[1,0,0]
	v_pk_fma_f32 v[250:251], v[92:93], v[50:51], v[250:251] neg_lo:[1,0,0] neg_hi:[1,0,0]
	v_pk_fma_f32 v[252:253], v[94:95], v[52:53], v[252:253] neg_lo:[1,0,0] neg_hi:[1,0,0]
	ds_read_b128 v[80:83], v161 offset:14208
	ds_read_b128 v[84:87], v161 offset:14224
	ds_read_b128 v[88:91], v161 offset:14240
	ds_read_b128 v[92:95], v161 offset:14256
	s_waitcnt lgkmcnt(12)
	v_pk_fma_f32 v[250:251], v[96:97], v[54:55], v[250:251] neg_lo:[1,0,0] neg_hi:[1,0,0]
	v_pk_fma_f32 v[252:253], v[98:99], v[56:57], v[252:253] neg_lo:[1,0,0] neg_hi:[1,0,0]
	v_pk_fma_f32 v[250:251], v[100:101], v[58:59], v[250:251] neg_lo:[1,0,0] neg_hi:[1,0,0]
	v_pk_fma_f32 v[252:253], v[102:103], v[60:61], v[252:253] neg_lo:[1,0,0] neg_hi:[1,0,0]
	v_pk_fma_f32 v[250:251], v[104:105], v[62:63], v[250:251] neg_lo:[1,0,0] neg_hi:[1,0,0]
	v_pk_fma_f32 v[252:253], v[106:107], v[226:227], v[252:253] neg_lo:[1,0,0] neg_hi:[1,0,0]
	v_pk_fma_f32 v[250:251], v[108:109], v[228:229], v[250:251] neg_lo:[1,0,0] neg_hi:[1,0,0]
	v_pk_fma_f32 v[252:253], v[110:111], v[230:231], v[252:253] neg_lo:[1,0,0] neg_hi:[1,0,0]
	v_add_f32_e32 v250, v250, v251
	v_add_f32_e32 v252, v252, v253
	v_add_f32_e32 v230, v250, v252
	ds_read_b128 v[96:99], v161 offset:14272
	ds_read_b128 v[100:103], v161 offset:14288
	ds_read_b128 v[104:107], v161 offset:14336
	ds_read_b128 v[108:111], v161 offset:14352
	s_waitcnt lgkmcnt(12)
	v_subrev_u32_e32 v249, 55, v208
	v_cvt_f32_i32_e32 v249, v249
	v_sub_f32_e64 v254, 1.0, |v249| clamp
	v_pk_fma_f32 v[250:251], v[112:113], v[0:1], v[254:255] neg_lo:[1,0,0] neg_hi:[1,0,0]
	v_pk_fma_f32 v[252:253], v[114:115], v[2:3], 0 neg_lo:[1,0,0] neg_hi:[1,0,0]
	v_pk_fma_f32 v[250:251], v[116:117], v[4:5], v[250:251] neg_lo:[1,0,0] neg_hi:[1,0,0]
	v_pk_fma_f32 v[252:253], v[118:119], v[6:7], v[252:253] neg_lo:[1,0,0] neg_hi:[1,0,0]
	v_pk_fma_f32 v[250:251], v[120:121], v[22:23], v[250:251] neg_lo:[1,0,0] neg_hi:[1,0,0]
	v_pk_fma_f32 v[252:253], v[122:123], v[24:25], v[252:253] neg_lo:[1,0,0] neg_hi:[1,0,0]
	v_pk_fma_f32 v[250:251], v[124:125], v[26:27], v[250:251] neg_lo:[1,0,0] neg_hi:[1,0,0]
	v_pk_fma_f32 v[252:253], v[126:127], v[28:29], v[252:253] neg_lo:[1,0,0] neg_hi:[1,0,0]
	ds_read_b128 v[112:115], v161 offset:14368
	ds_read_b128 v[116:119], v161 offset:14384
	ds_read_b128 v[120:123], v161 offset:14400
	ds_read_b128 v[124:127], v161 offset:14416
	s_waitcnt lgkmcnt(12)
	v_pk_fma_f32 v[250:251], v[128:129], v[30:31], v[250:251] neg_lo:[1,0,0] neg_hi:[1,0,0]
	v_pk_fma_f32 v[252:253], v[130:131], v[32:33], v[252:253] neg_lo:[1,0,0] neg_hi:[1,0,0]
	v_pk_fma_f32 v[250:251], v[132:133], v[34:35], v[250:251] neg_lo:[1,0,0] neg_hi:[1,0,0]
	v_pk_fma_f32 v[252:253], v[134:135], v[36:37], v[252:253] neg_lo:[1,0,0] neg_hi:[1,0,0]
	v_pk_fma_f32 v[250:251], v[136:137], v[38:39], v[250:251] neg_lo:[1,0,0] neg_hi:[1,0,0]
	v_pk_fma_f32 v[252:253], v[138:139], v[40:41], v[252:253] neg_lo:[1,0,0] neg_hi:[1,0,0]
	v_pk_fma_f32 v[250:251], v[140:141], v[42:43], v[250:251] neg_lo:[1,0,0] neg_hi:[1,0,0]
	v_pk_fma_f32 v[252:253], v[142:143], v[44:45], v[252:253] neg_lo:[1,0,0] neg_hi:[1,0,0]
	ds_read_b128 v[128:131], v161 offset:14432
	ds_read_b128 v[132:135], v161 offset:14448
	ds_read_b128 v[136:139], v161 offset:14464
	ds_read_b128 v[140:143], v161 offset:14480
	s_waitcnt lgkmcnt(12)
	v_pk_fma_f32 v[250:251], v[80:81], v[46:47], v[250:251] neg_lo:[1,0,0] neg_hi:[1,0,0]
	v_pk_fma_f32 v[252:253], v[82:83], v[48:49], v[252:253] neg_lo:[1,0,0] neg_hi:[1,0,0]
	v_pk_fma_f32 v[250:251], v[84:85], v[50:51], v[250:251] neg_lo:[1,0,0] neg_hi:[1,0,0]
	v_pk_fma_f32 v[252:253], v[86:87], v[52:53], v[252:253] neg_lo:[1,0,0] neg_hi:[1,0,0]
	v_pk_fma_f32 v[250:251], v[88:89], v[54:55], v[250:251] neg_lo:[1,0,0] neg_hi:[1,0,0]
	v_pk_fma_f32 v[252:253], v[90:91], v[56:57], v[252:253] neg_lo:[1,0,0] neg_hi:[1,0,0]
	v_pk_fma_f32 v[250:251], v[92:93], v[58:59], v[250:251] neg_lo:[1,0,0] neg_hi:[1,0,0]
	v_pk_fma_f32 v[252:253], v[94:95], v[60:61], v[252:253] neg_lo:[1,0,0] neg_hi:[1,0,0]
	ds_read_b128 v[80:83], v161 offset:14496
	ds_read_b128 v[84:87], v161 offset:14512
	ds_read_b128 v[88:91], v161 offset:14528
	ds_read_b128 v[92:95], v161 offset:14544
	s_waitcnt lgkmcnt(12)
	v_pk_fma_f32 v[250:251], v[96:97], v[62:63], v[250:251] neg_lo:[1,0,0] neg_hi:[1,0,0]
	v_pk_fma_f32 v[252:253], v[98:99], v[226:227], v[252:253] neg_lo:[1,0,0] neg_hi:[1,0,0]
	v_pk_fma_f32 v[250:251], v[100:101], v[228:229], v[250:251] neg_lo:[1,0,0] neg_hi:[1,0,0]
	v_pk_fma_f32 v[252:253], v[102:103], v[230:231], v[252:253] neg_lo:[1,0,0] neg_hi:[1,0,0]
	v_add_f32_e32 v250, v250, v251
	v_add_f32_e32 v252, v252, v253
	v_add_f32_e32 v231, v250, v252
	v_subrev_u32_e32 v249, 56, v208
	v_cvt_f32_i32_e32 v249, v249
	v_sub_f32_e64 v254, 1.0, |v249| clamp
	v_pk_fma_f32 v[250:251], v[104:105], v[0:1], v[254:255] neg_lo:[1,0,0] neg_hi:[1,0,0]
	v_pk_fma_f32 v[252:253], v[106:107], v[2:3], 0 neg_lo:[1,0,0] neg_hi:[1,0,0]
	v_pk_fma_f32 v[250:251], v[108:109], v[4:5], v[250:251] neg_lo:[1,0,0] neg_hi:[1,0,0]
	v_pk_fma_f32 v[252:253], v[110:111], v[6:7], v[252:253] neg_lo:[1,0,0] neg_hi:[1,0,0]
	ds_read_b128 v[96:99], v161 offset:14592
	ds_read_b128 v[100:103], v161 offset:14608
	ds_read_b128 v[104:107], v161 offset:14624
	ds_read_b128 v[108:111], v161 offset:14640
	s_waitcnt lgkmcnt(12)
	v_pk_fma_f32 v[250:251], v[112:113], v[22:23], v[250:251] neg_lo:[1,0,0] neg_hi:[1,0,0]
	v_pk_fma_f32 v[252:253], v[114:115], v[24:25], v[252:253] neg_lo:[1,0,0] neg_hi:[1,0,0]
	v_pk_fma_f32 v[250:251], v[116:117], v[26:27], v[250:251] neg_lo:[1,0,0] neg_hi:[1,0,0]
	v_pk_fma_f32 v[252:253], v[118:119], v[28:29], v[252:253] neg_lo:[1,0,0] neg_hi:[1,0,0]
	v_pk_fma_f32 v[250:251], v[120:121], v[30:31], v[250:251] neg_lo:[1,0,0] neg_hi:[1,0,0]
	v_pk_fma_f32 v[252:253], v[122:123], v[32:33], v[252:253] neg_lo:[1,0,0] neg_hi:[1,0,0]
	v_pk_fma_f32 v[250:251], v[124:125], v[34:35], v[250:251] neg_lo:[1,0,0] neg_hi:[1,0,0]
	v_pk_fma_f32 v[252:253], v[126:127], v[36:37], v[252:253] neg_lo:[1,0,0] neg_hi:[1,0,0]
	ds_read_b128 v[112:115], v161 offset:14656
	ds_read_b128 v[116:119], v161 offset:14672
	ds_read_b128 v[120:123], v161 offset:14688
	ds_read_b128 v[124:127], v161 offset:14704
	s_waitcnt lgkmcnt(12)
	v_pk_fma_f32 v[250:251], v[128:129], v[38:39], v[250:251] neg_lo:[1,0,0] neg_hi:[1,0,0]
	v_pk_fma_f32 v[252:253], v[130:131], v[40:41], v[252:253] neg_lo:[1,0,0] neg_hi:[1,0,0]
	v_pk_fma_f32 v[250:251], v[132:133], v[42:43], v[250:251] neg_lo:[1,0,0] neg_hi:[1,0,0]
	v_pk_fma_f32 v[252:253], v[134:135], v[44:45], v[252:253] neg_lo:[1,0,0] neg_hi:[1,0,0]
	v_pk_fma_f32 v[250:251], v[136:137], v[46:47], v[250:251] neg_lo:[1,0,0] neg_hi:[1,0,0]
	v_pk_fma_f32 v[252:253], v[138:139], v[48:49], v[252:253] neg_lo:[1,0,0] neg_hi:[1,0,0]
	v_pk_fma_f32 v[250:251], v[140:141], v[50:51], v[250:251] neg_lo:[1,0,0] neg_hi:[1,0,0]
	v_pk_fma_f32 v[252:253], v[142:143], v[52:53], v[252:253] neg_lo:[1,0,0] neg_hi:[1,0,0]
	ds_read_b128 v[128:131], v161 offset:14720
	ds_read_b128 v[132:135], v161 offset:14736
	ds_read_b128 v[136:139], v161 offset:14752
	ds_read_b128 v[140:143], v161 offset:14768
	s_waitcnt lgkmcnt(12)
	v_pk_fma_f32 v[250:251], v[80:81], v[54:55], v[250:251] neg_lo:[1,0,0] neg_hi:[1,0,0]
	v_pk_fma_f32 v[252:253], v[82:83], v[56:57], v[252:253] neg_lo:[1,0,0] neg_hi:[1,0,0]
	v_pk_fma_f32 v[250:251], v[84:85], v[58:59], v[250:251] neg_lo:[1,0,0] neg_hi:[1,0,0]
	v_pk_fma_f32 v[252:253], v[86:87], v[60:61], v[252:253] neg_lo:[1,0,0] neg_hi:[1,0,0]
	v_pk_fma_f32 v[250:251], v[88:89], v[62:63], v[250:251] neg_lo:[1,0,0] neg_hi:[1,0,0]
	v_pk_fma_f32 v[252:253], v[90:91], v[226:227], v[252:253] neg_lo:[1,0,0] neg_hi:[1,0,0]
	v_pk_fma_f32 v[250:251], v[92:93], v[228:229], v[250:251] neg_lo:[1,0,0] neg_hi:[1,0,0]
	v_pk_fma_f32 v[252:253], v[94:95], v[230:231], v[252:253] neg_lo:[1,0,0] neg_hi:[1,0,0]
	v_add_f32_e32 v250, v250, v251
	v_add_f32_e32 v252, v252, v253
	v_add_f32_e32 v232, v250, v252
	ds_read_b128 v[80:83], v161 offset:14784
	ds_read_b128 v[84:87], v161 offset:14800
	ds_read_b128 v[88:91], v161 offset:14816
	ds_read_b128 v[92:95], v161 offset:14848
	s_waitcnt lgkmcnt(12)
	v_subrev_u32_e32 v249, 57, v208
	v_cvt_f32_i32_e32 v249, v249
	v_sub_f32_e64 v254, 1.0, |v249| clamp
	v_pk_fma_f32 v[250:251], v[96:97], v[0:1], v[254:255] neg_lo:[1,0,0] neg_hi:[1,0,0]
	v_pk_fma_f32 v[252:253], v[98:99], v[2:3], 0 neg_lo:[1,0,0] neg_hi:[1,0,0]
	v_pk_fma_f32 v[250:251], v[100:101], v[4:5], v[250:251] neg_lo:[1,0,0] neg_hi:[1,0,0]
	v_pk_fma_f32 v[252:253], v[102:103], v[6:7], v[252:253] neg_lo:[1,0,0] neg_hi:[1,0,0]
	v_pk_fma_f32 v[250:251], v[104:105], v[22:23], v[250:251] neg_lo:[1,0,0] neg_hi:[1,0,0]
	v_pk_fma_f32 v[252:253], v[106:107], v[24:25], v[252:253] neg_lo:[1,0,0] neg_hi:[1,0,0]
	v_pk_fma_f32 v[250:251], v[108:109], v[26:27], v[250:251] neg_lo:[1,0,0] neg_hi:[1,0,0]
	v_pk_fma_f32 v[252:253], v[110:111], v[28:29], v[252:253] neg_lo:[1,0,0] neg_hi:[1,0,0]
	ds_read_b128 v[96:99], v161 offset:14864
	ds_read_b128 v[100:103], v161 offset:14880
	ds_read_b128 v[104:107], v161 offset:14896
	ds_read_b128 v[108:111], v161 offset:14912
	s_waitcnt lgkmcnt(12)
	v_pk_fma_f32 v[250:251], v[112:113], v[30:31], v[250:251] neg_lo:[1,0,0] neg_hi:[1,0,0]
	v_pk_fma_f32 v[252:253], v[114:115], v[32:33], v[252:253] neg_lo:[1,0,0] neg_hi:[1,0,0]
	v_pk_fma_f32 v[250:251], v[116:117], v[34:35], v[250:251] neg_lo:[1,0,0] neg_hi:[1,0,0]
	v_pk_fma_f32 v[252:253], v[118:119], v[36:37], v[252:253] neg_lo:[1,0,0] neg_hi:[1,0,0]
	v_pk_fma_f32 v[250:251], v[120:121], v[38:39], v[250:251] neg_lo:[1,0,0] neg_hi:[1,0,0]
	v_pk_fma_f32 v[252:253], v[122:123], v[40:41], v[252:253] neg_lo:[1,0,0] neg_hi:[1,0,0]
	v_pk_fma_f32 v[250:251], v[124:125], v[42:43], v[250:251] neg_lo:[1,0,0] neg_hi:[1,0,0]
	v_pk_fma_f32 v[252:253], v[126:127], v[44:45], v[252:253] neg_lo:[1,0,0] neg_hi:[1,0,0]
	ds_read_b128 v[112:115], v161 offset:14928
	ds_read_b128 v[116:119], v161 offset:14944
	ds_read_b128 v[120:123], v161 offset:14960
	ds_read_b128 v[124:127], v161 offset:14976
	s_waitcnt lgkmcnt(12)
	v_pk_fma_f32 v[250:251], v[128:129], v[46:47], v[250:251] neg_lo:[1,0,0] neg_hi:[1,0,0]
	v_pk_fma_f32 v[252:253], v[130:131], v[48:49], v[252:253] neg_lo:[1,0,0] neg_hi:[1,0,0]
	v_pk_fma_f32 v[250:251], v[132:133], v[50:51], v[250:251] neg_lo:[1,0,0] neg_hi:[1,0,0]
	v_pk_fma_f32 v[252:253], v[134:135], v[52:53], v[252:253] neg_lo:[1,0,0] neg_hi:[1,0,0]
	v_pk_fma_f32 v[250:251], v[136:137], v[54:55], v[250:251] neg_lo:[1,0,0] neg_hi:[1,0,0]
	v_pk_fma_f32 v[252:253], v[138:139], v[56:57], v[252:253] neg_lo:[1,0,0] neg_hi:[1,0,0]
	v_pk_fma_f32 v[250:251], v[140:141], v[58:59], v[250:251] neg_lo:[1,0,0] neg_hi:[1,0,0]
	v_pk_fma_f32 v[252:253], v[142:143], v[60:61], v[252:253] neg_lo:[1,0,0] neg_hi:[1,0,0]
	ds_read_b128 v[128:131], v161 offset:14992
	ds_read_b128 v[132:135], v161 offset:15008
	ds_read_b128 v[136:139], v161 offset:15024
	ds_read_b128 v[140:143], v161 offset:15040
	s_waitcnt lgkmcnt(12)
	v_pk_fma_f32 v[250:251], v[80:81], v[62:63], v[250:251] neg_lo:[1,0,0] neg_hi:[1,0,0]
	v_pk_fma_f32 v[252:253], v[82:83], v[226:227], v[252:253] neg_lo:[1,0,0] neg_hi:[1,0,0]
	v_pk_fma_f32 v[250:251], v[84:85], v[228:229], v[250:251] neg_lo:[1,0,0] neg_hi:[1,0,0]
	v_pk_fma_f32 v[252:253], v[86:87], v[230:231], v[252:253] neg_lo:[1,0,0] neg_hi:[1,0,0]
	v_pk_fma_f32 v[250:251], v[88:89], v[232:233], v[250:251] neg_lo:[1,0,0] neg_hi:[1,0,0]
	v_pk_fma_f32 v[252:253], v[90:91], v[234:235], v[252:253] neg_lo:[1,0,0] neg_hi:[1,0,0]
	v_add_f32_e32 v250, v250, v251
	v_add_f32_e32 v252, v252, v253
	v_add_f32_e32 v233, v250, v252
	v_subrev_u32_e32 v249, 58, v208
	v_cvt_f32_i32_e32 v249, v249
	v_sub_f32_e64 v254, 1.0, |v249| clamp
	v_pk_fma_f32 v[250:251], v[92:93], v[0:1], v[254:255] neg_lo:[1,0,0] neg_hi:[1,0,0]
	v_pk_fma_f32 v[252:253], v[94:95], v[2:3], 0 neg_lo:[1,0,0] neg_hi:[1,0,0]
	ds_read_b128 v[80:83], v161 offset:15056
	ds_read_b128 v[84:87], v161 offset:15072
	ds_read_b128 v[88:91], v161 offset:15104
	ds_read_b128 v[92:95], v161 offset:15120
	s_waitcnt lgkmcnt(12)
	v_pk_fma_f32 v[250:251], v[96:97], v[4:5], v[250:251] neg_lo:[1,0,0] neg_hi:[1,0,0]
	v_pk_fma_f32 v[252:253], v[98:99], v[6:7], v[252:253] neg_lo:[1,0,0] neg_hi:[1,0,0]
	v_pk_fma_f32 v[250:251], v[100:101], v[22:23], v[250:251] neg_lo:[1,0,0] neg_hi:[1,0,0]
	v_pk_fma_f32 v[252:253], v[102:103], v[24:25], v[252:253] neg_lo:[1,0,0] neg_hi:[1,0,0]
	v_pk_fma_f32 v[250:251], v[104:105], v[26:27], v[250:251] neg_lo:[1,0,0] neg_hi:[1,0,0]
	v_pk_fma_f32 v[252:253], v[106:107], v[28:29], v[252:253] neg_lo:[1,0,0] neg_hi:[1,0,0]
	v_pk_fma_f32 v[250:251], v[108:109], v[30:31], v[250:251] neg_lo:[1,0,0] neg_hi:[1,0,0]
	v_pk_fma_f32 v[252:253], v[110:111], v[32:33], v[252:253] neg_lo:[1,0,0] neg_hi:[1,0,0]
	ds_read_b128 v[96:99], v161 offset:15136
	ds_read_b128 v[100:103], v161 offset:15152
	ds_read_b128 v[104:107], v161 offset:15168
	ds_read_b128 v[108:111], v161 offset:15184
	s_waitcnt lgkmcnt(12)
	v_pk_fma_f32 v[250:251], v[112:113], v[34:35], v[250:251] neg_lo:[1,0,0] neg_hi:[1,0,0]
	v_pk_fma_f32 v[252:253], v[114:115], v[36:37], v[252:253] neg_lo:[1,0,0] neg_hi:[1,0,0]
	v_pk_fma_f32 v[250:251], v[116:117], v[38:39], v[250:251] neg_lo:[1,0,0] neg_hi:[1,0,0]
	v_pk_fma_f32 v[252:253], v[118:119], v[40:41], v[252:253] neg_lo:[1,0,0] neg_hi:[1,0,0]
	v_pk_fma_f32 v[250:251], v[120:121], v[42:43], v[250:251] neg_lo:[1,0,0] neg_hi:[1,0,0]
	v_pk_fma_f32 v[252:253], v[122:123], v[44:45], v[252:253] neg_lo:[1,0,0] neg_hi:[1,0,0]
	v_pk_fma_f32 v[250:251], v[124:125], v[46:47], v[250:251] neg_lo:[1,0,0] neg_hi:[1,0,0]
	v_pk_fma_f32 v[252:253], v[126:127], v[48:49], v[252:253] neg_lo:[1,0,0] neg_hi:[1,0,0]
	ds_read_b128 v[112:115], v161 offset:15200
	ds_read_b128 v[116:119], v161 offset:15216
	ds_read_b128 v[120:123], v161 offset:15232
	ds_read_b128 v[124:127], v161 offset:15248
	s_waitcnt lgkmcnt(12)
	v_pk_fma_f32 v[250:251], v[128:129], v[50:51], v[250:251] neg_lo:[1,0,0] neg_hi:[1,0,0]
	v_pk_fma_f32 v[252:253], v[130:131], v[52:53], v[252:253] neg_lo:[1,0,0] neg_hi:[1,0,0]
	v_pk_fma_f32 v[250:251], v[132:133], v[54:55], v[250:251] neg_lo:[1,0,0] neg_hi:[1,0,0]
	v_pk_fma_f32 v[252:253], v[134:135], v[56:57], v[252:253] neg_lo:[1,0,0] neg_hi:[1,0,0]
	v_pk_fma_f32 v[250:251], v[136:137], v[58:59], v[250:251] neg_lo:[1,0,0] neg_hi:[1,0,0]
	v_pk_fma_f32 v[252:253], v[138:139], v[60:61], v[252:253] neg_lo:[1,0,0] neg_hi:[1,0,0]
	v_pk_fma_f32 v[250:251], v[140:141], v[62:63], v[250:251] neg_lo:[1,0,0] neg_hi:[1,0,0]
	v_pk_fma_f32 v[252:253], v[142:143], v[226:227], v[252:253] neg_lo:[1,0,0] neg_hi:[1,0,0]
	ds_read_b128 v[128:131], v161 offset:15264
	ds_read_b128 v[132:135], v161 offset:15280
	ds_read_b128 v[136:139], v161 offset:15296
	ds_read_b128 v[140:143], v161 offset:15312
	s_waitcnt lgkmcnt(12)
	v_pk_fma_f32 v[250:251], v[80:81], v[228:229], v[250:251] neg_lo:[1,0,0] neg_hi:[1,0,0]
	v_pk_fma_f32 v[252:253], v[82:83], v[230:231], v[252:253] neg_lo:[1,0,0] neg_hi:[1,0,0]
	v_pk_fma_f32 v[250:251], v[84:85], v[232:233], v[250:251] neg_lo:[1,0,0] neg_hi:[1,0,0]
	v_pk_fma_f32 v[252:253], v[86:87], v[234:235], v[252:253] neg_lo:[1,0,0] neg_hi:[1,0,0]
	v_add_f32_e32 v250, v250, v251
	v_add_f32_e32 v252, v252, v253
	v_add_f32_e32 v234, v250, v252
	v_subrev_u32_e32 v249, 59, v208
	v_cvt_f32_i32_e32 v249, v249
	v_sub_f32_e64 v254, 1.0, |v249| clamp
	v_pk_fma_f32 v[250:251], v[88:89], v[0:1], v[254:255] neg_lo:[1,0,0] neg_hi:[1,0,0]
	v_pk_fma_f32 v[252:253], v[90:91], v[2:3], 0 neg_lo:[1,0,0] neg_hi:[1,0,0]
	v_pk_fma_f32 v[250:251], v[92:93], v[4:5], v[250:251] neg_lo:[1,0,0] neg_hi:[1,0,0]
	v_pk_fma_f32 v[252:253], v[94:95], v[6:7], v[252:253] neg_lo:[1,0,0] neg_hi:[1,0,0]
	ds_read_b128 v[80:83], v161 offset:15328
	ds_read_b128 v[84:87], v161 offset:15360
	ds_read_b128 v[88:91], v161 offset:15376
	ds_read_b128 v[92:95], v161 offset:15392
	s_waitcnt lgkmcnt(12)
	v_pk_fma_f32 v[250:251], v[96:97], v[22:23], v[250:251] neg_lo:[1,0,0] neg_hi:[1,0,0]
	v_pk_fma_f32 v[252:253], v[98:99], v[24:25], v[252:253] neg_lo:[1,0,0] neg_hi:[1,0,0]
	v_pk_fma_f32 v[250:251], v[100:101], v[26:27], v[250:251] neg_lo:[1,0,0] neg_hi:[1,0,0]
	v_pk_fma_f32 v[252:253], v[102:103], v[28:29], v[252:253] neg_lo:[1,0,0] neg_hi:[1,0,0]
	v_pk_fma_f32 v[250:251], v[104:105], v[30:31], v[250:251] neg_lo:[1,0,0] neg_hi:[1,0,0]
	v_pk_fma_f32 v[252:253], v[106:107], v[32:33], v[252:253] neg_lo:[1,0,0] neg_hi:[1,0,0]
	v_pk_fma_f32 v[250:251], v[108:109], v[34:35], v[250:251] neg_lo:[1,0,0] neg_hi:[1,0,0]
	v_pk_fma_f32 v[252:253], v[110:111], v[36:37], v[252:253] neg_lo:[1,0,0] neg_hi:[1,0,0]
	ds_read_b128 v[96:99], v161 offset:15408
	ds_read_b128 v[100:103], v161 offset:15424
	ds_read_b128 v[104:107], v161 offset:15440
	ds_read_b128 v[108:111], v161 offset:15456
	s_waitcnt lgkmcnt(12)
	v_pk_fma_f32 v[250:251], v[112:113], v[38:39], v[250:251] neg_lo:[1,0,0] neg_hi:[1,0,0]
	v_pk_fma_f32 v[252:253], v[114:115], v[40:41], v[252:253] neg_lo:[1,0,0] neg_hi:[1,0,0]
	v_pk_fma_f32 v[250:251], v[116:117], v[42:43], v[250:251] neg_lo:[1,0,0] neg_hi:[1,0,0]
	v_pk_fma_f32 v[252:253], v[118:119], v[44:45], v[252:253] neg_lo:[1,0,0] neg_hi:[1,0,0]
	v_pk_fma_f32 v[250:251], v[120:121], v[46:47], v[250:251] neg_lo:[1,0,0] neg_hi:[1,0,0]
	v_pk_fma_f32 v[252:253], v[122:123], v[48:49], v[252:253] neg_lo:[1,0,0] neg_hi:[1,0,0]
	v_pk_fma_f32 v[250:251], v[124:125], v[50:51], v[250:251] neg_lo:[1,0,0] neg_hi:[1,0,0]
	v_pk_fma_f32 v[252:253], v[126:127], v[52:53], v[252:253] neg_lo:[1,0,0] neg_hi:[1,0,0]
	ds_read_b128 v[112:115], v161 offset:15472
	ds_read_b128 v[116:119], v161 offset:15488
	ds_read_b128 v[120:123], v161 offset:15504
	ds_read_b128 v[124:127], v161 offset:15520
	s_waitcnt lgkmcnt(12)
	v_pk_fma_f32 v[250:251], v[128:129], v[54:55], v[250:251] neg_lo:[1,0,0] neg_hi:[1,0,0]
	v_pk_fma_f32 v[252:253], v[130:131], v[56:57], v[252:253] neg_lo:[1,0,0] neg_hi:[1,0,0]
	v_pk_fma_f32 v[250:251], v[132:133], v[58:59], v[250:251] neg_lo:[1,0,0] neg_hi:[1,0,0]
	v_pk_fma_f32 v[252:253], v[134:135], v[60:61], v[252:253] neg_lo:[1,0,0] neg_hi:[1,0,0]
	v_pk_fma_f32 v[250:251], v[136:137], v[62:63], v[250:251] neg_lo:[1,0,0] neg_hi:[1,0,0]
	v_pk_fma_f32 v[252:253], v[138:139], v[226:227], v[252:253] neg_lo:[1,0,0] neg_hi:[1,0,0]
	v_pk_fma_f32 v[250:251], v[140:141], v[228:229], v[250:251] neg_lo:[1,0,0] neg_hi:[1,0,0]
	v_pk_fma_f32 v[252:253], v[142:143], v[230:231], v[252:253] neg_lo:[1,0,0] neg_hi:[1,0,0]
	ds_read_b128 v[128:131], v161 offset:15536
	ds_read_b128 v[132:135], v161 offset:15552
	ds_read_b128 v[136:139], v161 offset:15568
	ds_read_b128 v[140:143], v161 offset:15584
	s_waitcnt lgkmcnt(12)
	v_pk_fma_f32 v[250:251], v[80:81], v[232:233], v[250:251] neg_lo:[1,0,0] neg_hi:[1,0,0]
	v_pk_fma_f32 v[252:253], v[82:83], v[234:235], v[252:253] neg_lo:[1,0,0] neg_hi:[1,0,0]
	v_add_f32_e32 v250, v250, v251
	v_add_f32_e32 v252, v252, v253
	v_add_f32_e32 v235, v250, v252
	v_subrev_u32_e32 v249, 60, v208
	v_cvt_f32_i32_e32 v249, v249
	v_sub_f32_e64 v254, 1.0, |v249| clamp
	v_pk_fma_f32 v[250:251], v[84:85], v[0:1], v[254:255] neg_lo:[1,0,0] neg_hi:[1,0,0]
	v_pk_fma_f32 v[252:253], v[86:87], v[2:3], 0 neg_lo:[1,0,0] neg_hi:[1,0,0]
	v_pk_fma_f32 v[250:251], v[88:89], v[4:5], v[250:251] neg_lo:[1,0,0] neg_hi:[1,0,0]
	v_pk_fma_f32 v[252:253], v[90:91], v[6:7], v[252:253] neg_lo:[1,0,0] neg_hi:[1,0,0]
	v_pk_fma_f32 v[250:251], v[92:93], v[22:23], v[250:251] neg_lo:[1,0,0] neg_hi:[1,0,0]
	v_pk_fma_f32 v[252:253], v[94:95], v[24:25], v[252:253] neg_lo:[1,0,0] neg_hi:[1,0,0]
	ds_read_b128 v[80:83], v161 offset:15616
	ds_read_b128 v[84:87], v161 offset:15632
	ds_read_b128 v[88:91], v161 offset:15648
	ds_read_b128 v[92:95], v161 offset:15664
	s_waitcnt lgkmcnt(12)
	v_pk_fma_f32 v[250:251], v[96:97], v[26:27], v[250:251] neg_lo:[1,0,0] neg_hi:[1,0,0]
	v_pk_fma_f32 v[252:253], v[98:99], v[28:29], v[252:253] neg_lo:[1,0,0] neg_hi:[1,0,0]
	v_pk_fma_f32 v[250:251], v[100:101], v[30:31], v[250:251] neg_lo:[1,0,0] neg_hi:[1,0,0]
	v_pk_fma_f32 v[252:253], v[102:103], v[32:33], v[252:253] neg_lo:[1,0,0] neg_hi:[1,0,0]
	v_pk_fma_f32 v[250:251], v[104:105], v[34:35], v[250:251] neg_lo:[1,0,0] neg_hi:[1,0,0]
	v_pk_fma_f32 v[252:253], v[106:107], v[36:37], v[252:253] neg_lo:[1,0,0] neg_hi:[1,0,0]
	v_pk_fma_f32 v[250:251], v[108:109], v[38:39], v[250:251] neg_lo:[1,0,0] neg_hi:[1,0,0]
	v_pk_fma_f32 v[252:253], v[110:111], v[40:41], v[252:253] neg_lo:[1,0,0] neg_hi:[1,0,0]
	ds_read_b128 v[96:99], v161 offset:15680
	ds_read_b128 v[100:103], v161 offset:15696
	ds_read_b128 v[104:107], v161 offset:15712
	ds_read_b128 v[108:111], v161 offset:15728
	s_waitcnt lgkmcnt(12)
	v_pk_fma_f32 v[250:251], v[112:113], v[42:43], v[250:251] neg_lo:[1,0,0] neg_hi:[1,0,0]
	v_pk_fma_f32 v[252:253], v[114:115], v[44:45], v[252:253] neg_lo:[1,0,0] neg_hi:[1,0,0]
	v_pk_fma_f32 v[250:251], v[116:117], v[46:47], v[250:251] neg_lo:[1,0,0] neg_hi:[1,0,0]
	v_pk_fma_f32 v[252:253], v[118:119], v[48:49], v[252:253] neg_lo:[1,0,0] neg_hi:[1,0,0]
	v_pk_fma_f32 v[250:251], v[120:121], v[50:51], v[250:251] neg_lo:[1,0,0] neg_hi:[1,0,0]
	v_pk_fma_f32 v[252:253], v[122:123], v[52:53], v[252:253] neg_lo:[1,0,0] neg_hi:[1,0,0]
	v_pk_fma_f32 v[250:251], v[124:125], v[54:55], v[250:251] neg_lo:[1,0,0] neg_hi:[1,0,0]
	v_pk_fma_f32 v[252:253], v[126:127], v[56:57], v[252:253] neg_lo:[1,0,0] neg_hi:[1,0,0]
	ds_read_b128 v[112:115], v161 offset:15744
	ds_read_b128 v[116:119], v161 offset:15760
	ds_read_b128 v[120:123], v161 offset:15776
	ds_read_b128 v[124:127], v161 offset:15792
	s_waitcnt lgkmcnt(12)
	v_pk_fma_f32 v[250:251], v[128:129], v[58:59], v[250:251] neg_lo:[1,0,0] neg_hi:[1,0,0]
	v_pk_fma_f32 v[252:253], v[130:131], v[60:61], v[252:253] neg_lo:[1,0,0] neg_hi:[1,0,0]
	v_pk_fma_f32 v[250:251], v[132:133], v[62:63], v[250:251] neg_lo:[1,0,0] neg_hi:[1,0,0]
	v_pk_fma_f32 v[252:253], v[134:135], v[226:227], v[252:253] neg_lo:[1,0,0] neg_hi:[1,0,0]
	v_pk_fma_f32 v[250:251], v[136:137], v[228:229], v[250:251] neg_lo:[1,0,0] neg_hi:[1,0,0]
	v_pk_fma_f32 v[252:253], v[138:139], v[230:231], v[252:253] neg_lo:[1,0,0] neg_hi:[1,0,0]
	v_pk_fma_f32 v[250:251], v[140:141], v[232:233], v[250:251] neg_lo:[1,0,0] neg_hi:[1,0,0]
	v_pk_fma_f32 v[252:253], v[142:143], v[234:235], v[252:253] neg_lo:[1,0,0] neg_hi:[1,0,0]
	v_add_f32_e32 v250, v250, v251
	v_add_f32_e32 v252, v252, v253
	v_add_f32_e32 v236, v250, v252
	ds_read_b128 v[128:131], v161 offset:15808
	ds_read_b128 v[132:135], v161 offset:15824
	ds_read_b128 v[136:139], v161 offset:15840
	ds_read_b128 v[140:143], v161 offset:15856
	s_waitcnt lgkmcnt(12)
	v_subrev_u32_e32 v249, 61, v208
	v_cvt_f32_i32_e32 v249, v249
	v_sub_f32_e64 v254, 1.0, |v249| clamp
	v_pk_fma_f32 v[250:251], v[80:81], v[0:1], v[254:255] neg_lo:[1,0,0] neg_hi:[1,0,0]
	v_pk_fma_f32 v[252:253], v[82:83], v[2:3], 0 neg_lo:[1,0,0] neg_hi:[1,0,0]
	v_pk_fma_f32 v[250:251], v[84:85], v[4:5], v[250:251] neg_lo:[1,0,0] neg_hi:[1,0,0]
	v_pk_fma_f32 v[252:253], v[86:87], v[6:7], v[252:253] neg_lo:[1,0,0] neg_hi:[1,0,0]
	v_pk_fma_f32 v[250:251], v[88:89], v[22:23], v[250:251] neg_lo:[1,0,0] neg_hi:[1,0,0]
	v_pk_fma_f32 v[252:253], v[90:91], v[24:25], v[252:253] neg_lo:[1,0,0] neg_hi:[1,0,0]
	v_pk_fma_f32 v[250:251], v[92:93], v[26:27], v[250:251] neg_lo:[1,0,0] neg_hi:[1,0,0]
	v_pk_fma_f32 v[252:253], v[94:95], v[28:29], v[252:253] neg_lo:[1,0,0] neg_hi:[1,0,0]
	ds_read_b128 v[80:83], v161 offset:15872
	ds_read_b128 v[84:87], v161 offset:15888
	ds_read_b128 v[88:91], v161 offset:15904
	ds_read_b128 v[92:95], v161 offset:15920
	s_waitcnt lgkmcnt(12)
	v_pk_fma_f32 v[250:251], v[96:97], v[30:31], v[250:251] neg_lo:[1,0,0] neg_hi:[1,0,0]
	v_pk_fma_f32 v[252:253], v[98:99], v[32:33], v[252:253] neg_lo:[1,0,0] neg_hi:[1,0,0]
	v_pk_fma_f32 v[250:251], v[100:101], v[34:35], v[250:251] neg_lo:[1,0,0] neg_hi:[1,0,0]
	v_pk_fma_f32 v[252:253], v[102:103], v[36:37], v[252:253] neg_lo:[1,0,0] neg_hi:[1,0,0]
	v_pk_fma_f32 v[250:251], v[104:105], v[38:39], v[250:251] neg_lo:[1,0,0] neg_hi:[1,0,0]
	v_pk_fma_f32 v[252:253], v[106:107], v[40:41], v[252:253] neg_lo:[1,0,0] neg_hi:[1,0,0]
	v_pk_fma_f32 v[250:251], v[108:109], v[42:43], v[250:251] neg_lo:[1,0,0] neg_hi:[1,0,0]
	v_pk_fma_f32 v[252:253], v[110:111], v[44:45], v[252:253] neg_lo:[1,0,0] neg_hi:[1,0,0]
	ds_read_b128 v[96:99], v161 offset:15936
	ds_read_b128 v[100:103], v161 offset:15952
	ds_read_b128 v[104:107], v161 offset:15968
	ds_read_b128 v[108:111], v161 offset:15984
	s_waitcnt lgkmcnt(12)
	v_pk_fma_f32 v[250:251], v[112:113], v[46:47], v[250:251] neg_lo:[1,0,0] neg_hi:[1,0,0]
	v_pk_fma_f32 v[252:253], v[114:115], v[48:49], v[252:253] neg_lo:[1,0,0] neg_hi:[1,0,0]
	v_pk_fma_f32 v[250:251], v[116:117], v[50:51], v[250:251] neg_lo:[1,0,0] neg_hi:[1,0,0]
	v_pk_fma_f32 v[252:253], v[118:119], v[52:53], v[252:253] neg_lo:[1,0,0] neg_hi:[1,0,0]
	v_pk_fma_f32 v[250:251], v[120:121], v[54:55], v[250:251] neg_lo:[1,0,0] neg_hi:[1,0,0]
	v_pk_fma_f32 v[252:253], v[122:123], v[56:57], v[252:253] neg_lo:[1,0,0] neg_hi:[1,0,0]
	v_pk_fma_f32 v[250:251], v[124:125], v[58:59], v[250:251] neg_lo:[1,0,0] neg_hi:[1,0,0]
	v_pk_fma_f32 v[252:253], v[126:127], v[60:61], v[252:253] neg_lo:[1,0,0] neg_hi:[1,0,0]
	ds_read_b128 v[112:115], v161 offset:16000
	ds_read_b128 v[116:119], v161 offset:16016
	ds_read_b128 v[120:123], v161 offset:16032
	ds_read_b128 v[124:127], v161 offset:16048
	s_waitcnt lgkmcnt(12)
	v_pk_fma_f32 v[250:251], v[128:129], v[62:63], v[250:251] neg_lo:[1,0,0] neg_hi:[1,0,0]
	v_pk_fma_f32 v[252:253], v[130:131], v[226:227], v[252:253] neg_lo:[1,0,0] neg_hi:[1,0,0]
	v_pk_fma_f32 v[250:251], v[132:133], v[228:229], v[250:251] neg_lo:[1,0,0] neg_hi:[1,0,0]
	v_pk_fma_f32 v[252:253], v[134:135], v[230:231], v[252:253] neg_lo:[1,0,0] neg_hi:[1,0,0]
	v_pk_fma_f32 v[250:251], v[136:137], v[232:233], v[250:251] neg_lo:[1,0,0] neg_hi:[1,0,0]
	v_pk_fma_f32 v[252:253], v[138:139], v[234:235], v[252:253] neg_lo:[1,0,0] neg_hi:[1,0,0]
	v_pk_fma_f32 v[250:251], v[140:141], v[236:237], v[250:251] neg_lo:[1,0,0] neg_hi:[1,0,0]
	v_pk_fma_f32 v[252:253], v[142:143], v[238:239], v[252:253] neg_lo:[1,0,0] neg_hi:[1,0,0]
	v_add_f32_e32 v250, v250, v251
	v_add_f32_e32 v252, v252, v253
	v_add_f32_e32 v237, v250, v252
	ds_read_b128 v[128:131], v161 offset:16064
	ds_read_b128 v[132:135], v161 offset:16080
	ds_read_b128 v[136:139], v161 offset:16096
	ds_read_b128 v[140:143], v161 offset:16112
	s_waitcnt lgkmcnt(12)
	v_subrev_u32_e32 v249, 62, v208
	v_cvt_f32_i32_e32 v249, v249
	v_sub_f32_e64 v254, 1.0, |v249| clamp
	v_pk_fma_f32 v[250:251], v[80:81], v[0:1], v[254:255] neg_lo:[1,0,0] neg_hi:[1,0,0]
	v_pk_fma_f32 v[252:253], v[82:83], v[2:3], 0 neg_lo:[1,0,0] neg_hi:[1,0,0]
	v_pk_fma_f32 v[250:251], v[84:85], v[4:5], v[250:251] neg_lo:[1,0,0] neg_hi:[1,0,0]
	v_pk_fma_f32 v[252:253], v[86:87], v[6:7], v[252:253] neg_lo:[1,0,0] neg_hi:[1,0,0]
	v_pk_fma_f32 v[250:251], v[88:89], v[22:23], v[250:251] neg_lo:[1,0,0] neg_hi:[1,0,0]
	v_pk_fma_f32 v[252:253], v[90:91], v[24:25], v[252:253] neg_lo:[1,0,0] neg_hi:[1,0,0]
	v_pk_fma_f32 v[250:251], v[92:93], v[26:27], v[250:251] neg_lo:[1,0,0] neg_hi:[1,0,0]
	v_pk_fma_f32 v[252:253], v[94:95], v[28:29], v[252:253] neg_lo:[1,0,0] neg_hi:[1,0,0]
	ds_read_b128 v[80:83], v161 offset:16128
	ds_read_b128 v[84:87], v161 offset:16144
	ds_read_b128 v[88:91], v161 offset:16160
	ds_read_b128 v[92:95], v161 offset:16176
	s_waitcnt lgkmcnt(12)
	v_pk_fma_f32 v[250:251], v[96:97], v[30:31], v[250:251] neg_lo:[1,0,0] neg_hi:[1,0,0]
	v_pk_fma_f32 v[252:253], v[98:99], v[32:33], v[252:253] neg_lo:[1,0,0] neg_hi:[1,0,0]
	v_pk_fma_f32 v[250:251], v[100:101], v[34:35], v[250:251] neg_lo:[1,0,0] neg_hi:[1,0,0]
	v_pk_fma_f32 v[252:253], v[102:103], v[36:37], v[252:253] neg_lo:[1,0,0] neg_hi:[1,0,0]
	v_pk_fma_f32 v[250:251], v[104:105], v[38:39], v[250:251] neg_lo:[1,0,0] neg_hi:[1,0,0]
	v_pk_fma_f32 v[252:253], v[106:107], v[40:41], v[252:253] neg_lo:[1,0,0] neg_hi:[1,0,0]
	v_pk_fma_f32 v[250:251], v[108:109], v[42:43], v[250:251] neg_lo:[1,0,0] neg_hi:[1,0,0]
	v_pk_fma_f32 v[252:253], v[110:111], v[44:45], v[252:253] neg_lo:[1,0,0] neg_hi:[1,0,0]
	ds_read_b128 v[96:99], v161 offset:16192
	ds_read_b128 v[100:103], v161 offset:16208
	ds_read_b128 v[104:107], v161 offset:16224
	ds_read_b128 v[108:111], v161 offset:16240
	s_waitcnt lgkmcnt(12)
	v_pk_fma_f32 v[250:251], v[112:113], v[46:47], v[250:251] neg_lo:[1,0,0] neg_hi:[1,0,0]
	v_pk_fma_f32 v[252:253], v[114:115], v[48:49], v[252:253] neg_lo:[1,0,0] neg_hi:[1,0,0]
	v_pk_fma_f32 v[250:251], v[116:117], v[50:51], v[250:251] neg_lo:[1,0,0] neg_hi:[1,0,0]
	v_pk_fma_f32 v[252:253], v[118:119], v[52:53], v[252:253] neg_lo:[1,0,0] neg_hi:[1,0,0]
	v_pk_fma_f32 v[250:251], v[120:121], v[54:55], v[250:251] neg_lo:[1,0,0] neg_hi:[1,0,0]
	v_pk_fma_f32 v[252:253], v[122:123], v[56:57], v[252:253] neg_lo:[1,0,0] neg_hi:[1,0,0]
	v_pk_fma_f32 v[250:251], v[124:125], v[58:59], v[250:251] neg_lo:[1,0,0] neg_hi:[1,0,0]
	v_pk_fma_f32 v[252:253], v[126:127], v[60:61], v[252:253] neg_lo:[1,0,0] neg_hi:[1,0,0]
	ds_read_b128 v[112:115], v161 offset:16256
	ds_read_b128 v[116:119], v161 offset:16272
	ds_read_b128 v[120:123], v161 offset:16288
	ds_read_b128 v[124:127], v161 offset:16304
	s_waitcnt lgkmcnt(12)
	v_pk_fma_f32 v[250:251], v[128:129], v[62:63], v[250:251] neg_lo:[1,0,0] neg_hi:[1,0,0]
	v_pk_fma_f32 v[252:253], v[130:131], v[226:227], v[252:253] neg_lo:[1,0,0] neg_hi:[1,0,0]
	v_pk_fma_f32 v[250:251], v[132:133], v[228:229], v[250:251] neg_lo:[1,0,0] neg_hi:[1,0,0]
	v_pk_fma_f32 v[252:253], v[134:135], v[230:231], v[252:253] neg_lo:[1,0,0] neg_hi:[1,0,0]
	v_pk_fma_f32 v[250:251], v[136:137], v[232:233], v[250:251] neg_lo:[1,0,0] neg_hi:[1,0,0]
	v_pk_fma_f32 v[252:253], v[138:139], v[234:235], v[252:253] neg_lo:[1,0,0] neg_hi:[1,0,0]
	v_pk_fma_f32 v[250:251], v[140:141], v[236:237], v[250:251] neg_lo:[1,0,0] neg_hi:[1,0,0]
	v_pk_fma_f32 v[252:253], v[142:143], v[238:239], v[252:253] neg_lo:[1,0,0] neg_hi:[1,0,0]
	v_add_f32_e32 v250, v250, v251
	v_add_f32_e32 v252, v252, v253
	v_add_f32_e32 v238, v250, v252
	ds_read_b128 v[128:131], v161 offset:16320
	ds_read_b128 v[132:135], v161 offset:16336
	ds_read_b128 v[136:139], v161 offset:16352
	ds_read_b128 v[140:143], v161 offset:16368
	s_waitcnt lgkmcnt(12)
	v_subrev_u32_e32 v249, 63, v208
	v_cvt_f32_i32_e32 v249, v249
	v_sub_f32_e64 v254, 1.0, |v249| clamp
	v_pk_fma_f32 v[250:251], v[80:81], v[0:1], v[254:255] neg_lo:[1,0,0] neg_hi:[1,0,0]
	v_pk_fma_f32 v[252:253], v[82:83], v[2:3], 0 neg_lo:[1,0,0] neg_hi:[1,0,0]
	v_pk_fma_f32 v[250:251], v[84:85], v[4:5], v[250:251] neg_lo:[1,0,0] neg_hi:[1,0,0]
	v_pk_fma_f32 v[252:253], v[86:87], v[6:7], v[252:253] neg_lo:[1,0,0] neg_hi:[1,0,0]
	v_pk_fma_f32 v[250:251], v[88:89], v[22:23], v[250:251] neg_lo:[1,0,0] neg_hi:[1,0,0]
	v_pk_fma_f32 v[252:253], v[90:91], v[24:25], v[252:253] neg_lo:[1,0,0] neg_hi:[1,0,0]
	v_pk_fma_f32 v[250:251], v[92:93], v[26:27], v[250:251] neg_lo:[1,0,0] neg_hi:[1,0,0]
	v_pk_fma_f32 v[252:253], v[94:95], v[28:29], v[252:253] neg_lo:[1,0,0] neg_hi:[1,0,0]
	s_waitcnt lgkmcnt(8)
	v_pk_fma_f32 v[250:251], v[96:97], v[30:31], v[250:251] neg_lo:[1,0,0] neg_hi:[1,0,0]
	v_pk_fma_f32 v[252:253], v[98:99], v[32:33], v[252:253] neg_lo:[1,0,0] neg_hi:[1,0,0]
	v_pk_fma_f32 v[250:251], v[100:101], v[34:35], v[250:251] neg_lo:[1,0,0] neg_hi:[1,0,0]
	v_pk_fma_f32 v[252:253], v[102:103], v[36:37], v[252:253] neg_lo:[1,0,0] neg_hi:[1,0,0]
	v_pk_fma_f32 v[250:251], v[104:105], v[38:39], v[250:251] neg_lo:[1,0,0] neg_hi:[1,0,0]
	v_pk_fma_f32 v[252:253], v[106:107], v[40:41], v[252:253] neg_lo:[1,0,0] neg_hi:[1,0,0]
	v_pk_fma_f32 v[250:251], v[108:109], v[42:43], v[250:251] neg_lo:[1,0,0] neg_hi:[1,0,0]
	v_pk_fma_f32 v[252:253], v[110:111], v[44:45], v[252:253] neg_lo:[1,0,0] neg_hi:[1,0,0]
	s_waitcnt lgkmcnt(4)
	v_pk_fma_f32 v[250:251], v[112:113], v[46:47], v[250:251] neg_lo:[1,0,0] neg_hi:[1,0,0]
	v_pk_fma_f32 v[252:253], v[114:115], v[48:49], v[252:253] neg_lo:[1,0,0] neg_hi:[1,0,0]
	v_pk_fma_f32 v[250:251], v[116:117], v[50:51], v[250:251] neg_lo:[1,0,0] neg_hi:[1,0,0]
	v_pk_fma_f32 v[252:253], v[118:119], v[52:53], v[252:253] neg_lo:[1,0,0] neg_hi:[1,0,0]
	v_pk_fma_f32 v[250:251], v[120:121], v[54:55], v[250:251] neg_lo:[1,0,0] neg_hi:[1,0,0]
	v_pk_fma_f32 v[252:253], v[122:123], v[56:57], v[252:253] neg_lo:[1,0,0] neg_hi:[1,0,0]
	v_pk_fma_f32 v[250:251], v[124:125], v[58:59], v[250:251] neg_lo:[1,0,0] neg_hi:[1,0,0]
	v_pk_fma_f32 v[252:253], v[126:127], v[60:61], v[252:253] neg_lo:[1,0,0] neg_hi:[1,0,0]
	s_waitcnt lgkmcnt(0)
	v_pk_fma_f32 v[250:251], v[128:129], v[62:63], v[250:251] neg_lo:[1,0,0] neg_hi:[1,0,0]
	v_pk_fma_f32 v[252:253], v[130:131], v[226:227], v[252:253] neg_lo:[1,0,0] neg_hi:[1,0,0]
	v_pk_fma_f32 v[250:251], v[132:133], v[228:229], v[250:251] neg_lo:[1,0,0] neg_hi:[1,0,0]
	v_pk_fma_f32 v[252:253], v[134:135], v[230:231], v[252:253] neg_lo:[1,0,0] neg_hi:[1,0,0]
	v_pk_fma_f32 v[250:251], v[136:137], v[232:233], v[250:251] neg_lo:[1,0,0] neg_hi:[1,0,0]
	v_pk_fma_f32 v[252:253], v[138:139], v[234:235], v[252:253] neg_lo:[1,0,0] neg_hi:[1,0,0]
	v_pk_fma_f32 v[250:251], v[140:141], v[236:237], v[250:251] neg_lo:[1,0,0] neg_hi:[1,0,0]
	v_pk_fma_f32 v[252:253], v[142:143], v[238:239], v[252:253] neg_lo:[1,0,0] neg_hi:[1,0,0]
	v_add_f32_e32 v250, v250, v251
	v_add_f32_e32 v252, v252, v253
	v_add_f32_e32 v239, v250, v252
	v_cvt_pk_bf16_f32 v240, v0, 0
	ds_write_b16 v196, v240 offset:16384
	v_cvt_pk_bf16_f32 v249, v1, 0
	ds_write_b16 v197, v249 offset:16512
	v_cvt_pk_bf16_f32 v254, v2, 0
	ds_write_b16 v198, v254 offset:16640
	v_cvt_pk_bf16_f32 v253, v3, 0
	ds_write_b16 v199, v253 offset:16768
	v_cvt_pk_bf16_f32 v240, v4, 0
	ds_write_b16 v200, v240 offset:16896
	v_cvt_pk_bf16_f32 v249, v5, 0
	ds_write_b16 v201, v249 offset:17024
	v_cvt_pk_bf16_f32 v254, v6, 0
	ds_write_b16 v202, v254 offset:17152
	v_cvt_pk_bf16_f32 v253, v7, 0
	ds_write_b16 v203, v253 offset:17280
	v_cvt_pk_bf16_f32 v240, v22, 0
	ds_write_b16 v196, v240 offset:17408
	v_cvt_pk_bf16_f32 v249, v23, 0
	ds_write_b16 v197, v249 offset:17536
	v_cvt_pk_bf16_f32 v254, v24, 0
	ds_write_b16 v198, v254 offset:17664
	v_cvt_pk_bf16_f32 v253, v25, 0
	ds_write_b16 v199, v253 offset:17792
	v_cvt_pk_bf16_f32 v240, v26, 0
	ds_write_b16 v200, v240 offset:17920
	v_cvt_pk_bf16_f32 v249, v27, 0
	ds_write_b16 v201, v249 offset:18048
	v_cvt_pk_bf16_f32 v254, v28, 0
	ds_write_b16 v202, v254 offset:18176
	v_cvt_pk_bf16_f32 v253, v29, 0
	ds_write_b16 v203, v253 offset:18304
	v_cvt_pk_bf16_f32 v240, v30, 0
	ds_write_b16 v196, v240 offset:18432
	v_cvt_pk_bf16_f32 v249, v31, 0
	ds_write_b16 v197, v249 offset:18560
	v_cvt_pk_bf16_f32 v254, v32, 0
	ds_write_b16 v198, v254 offset:18688
	v_cvt_pk_bf16_f32 v253, v33, 0
	ds_write_b16 v199, v253 offset:18816
	v_cvt_pk_bf16_f32 v240, v34, 0
	ds_write_b16 v200, v240 offset:18944
	v_cvt_pk_bf16_f32 v249, v35, 0
	ds_write_b16 v201, v249 offset:19072
	v_cvt_pk_bf16_f32 v254, v36, 0
	ds_write_b16 v202, v254 offset:19200
	v_cvt_pk_bf16_f32 v253, v37, 0
	ds_write_b16 v203, v253 offset:19328
	v_cvt_pk_bf16_f32 v240, v38, 0
	ds_write_b16 v196, v240 offset:19456
	v_cvt_pk_bf16_f32 v249, v39, 0
	ds_write_b16 v197, v249 offset:19584
	v_cvt_pk_bf16_f32 v254, v40, 0
	ds_write_b16 v198, v254 offset:19712
	v_cvt_pk_bf16_f32 v253, v41, 0
	ds_write_b16 v199, v253 offset:19840
	v_cvt_pk_bf16_f32 v240, v42, 0
	ds_write_b16 v200, v240 offset:19968
	v_cvt_pk_bf16_f32 v249, v43, 0
	ds_write_b16 v201, v249 offset:20096
	v_cvt_pk_bf16_f32 v254, v44, 0
	ds_write_b16 v202, v254 offset:20224
	v_cvt_pk_bf16_f32 v253, v45, 0
	ds_write_b16 v203, v253 offset:20352
	v_cvt_pk_bf16_f32 v240, v46, 0
	ds_write_b16 v196, v240 offset:20480
	v_cvt_pk_bf16_f32 v249, v47, 0
	ds_write_b16 v197, v249 offset:20608
	v_cvt_pk_bf16_f32 v254, v48, 0
	ds_write_b16 v198, v254 offset:20736
	v_cvt_pk_bf16_f32 v253, v49, 0
	ds_write_b16 v199, v253 offset:20864
	v_cvt_pk_bf16_f32 v240, v50, 0
	ds_write_b16 v200, v240 offset:20992
	v_cvt_pk_bf16_f32 v249, v51, 0
	ds_write_b16 v201, v249 offset:21120
	v_cvt_pk_bf16_f32 v254, v52, 0
	ds_write_b16 v202, v254 offset:21248
	v_cvt_pk_bf16_f32 v253, v53, 0
	ds_write_b16 v203, v253 offset:21376
	v_cvt_pk_bf16_f32 v240, v54, 0
	ds_write_b16 v196, v240 offset:21504
	v_cvt_pk_bf16_f32 v249, v55, 0
	ds_write_b16 v197, v249 offset:21632
	v_cvt_pk_bf16_f32 v254, v56, 0
	ds_write_b16 v198, v254 offset:21760
	v_cvt_pk_bf16_f32 v253, v57, 0
	ds_write_b16 v199, v253 offset:21888
	v_cvt_pk_bf16_f32 v240, v58, 0
	ds_write_b16 v200, v240 offset:22016
	v_cvt_pk_bf16_f32 v249, v59, 0
	ds_write_b16 v201, v249 offset:22144
	v_cvt_pk_bf16_f32 v254, v60, 0
	ds_write_b16 v202, v254 offset:22272
	v_cvt_pk_bf16_f32 v253, v61, 0
	ds_write_b16 v203, v253 offset:22400
	v_cvt_pk_bf16_f32 v240, v62, 0
	ds_write_b16 v196, v240 offset:22528
	v_cvt_pk_bf16_f32 v249, v63, 0
	ds_write_b16 v197, v249 offset:22656
	v_cvt_pk_bf16_f32 v254, v226, 0
	ds_write_b16 v198, v254 offset:22784
	v_cvt_pk_bf16_f32 v253, v227, 0
	ds_write_b16 v199, v253 offset:22912
	v_cvt_pk_bf16_f32 v240, v228, 0
	ds_write_b16 v200, v240 offset:23040
	v_cvt_pk_bf16_f32 v249, v229, 0
	ds_write_b16 v201, v249 offset:23168
	v_cvt_pk_bf16_f32 v254, v230, 0
	ds_write_b16 v202, v254 offset:23296
	v_cvt_pk_bf16_f32 v253, v231, 0
	ds_write_b16 v203, v253 offset:23424
	v_cvt_pk_bf16_f32 v240, v232, 0
	ds_write_b16 v196, v240 offset:23552
	v_cvt_pk_bf16_f32 v249, v233, 0
	ds_write_b16 v197, v249 offset:23680
	v_cvt_pk_bf16_f32 v254, v234, 0
	ds_write_b16 v198, v254 offset:23808
	v_cvt_pk_bf16_f32 v253, v235, 0
	ds_write_b16 v199, v253 offset:23936
	v_cvt_pk_bf16_f32 v240, v236, 0
	ds_write_b16 v200, v240 offset:24064
	v_cvt_pk_bf16_f32 v249, v237, 0
	ds_write_b16 v201, v249 offset:24192
	v_cvt_pk_bf16_f32 v254, v238, 0
	ds_write_b16 v202, v254 offset:24320
	v_cvt_pk_bf16_f32 v253, v239, 0
	ds_write_b16 v203, v253 offset:24448
	ds_read_b32 v80, v160 offset:0
	ds_read_b32 v81, v160 offset:256
	ds_read_b32 v82, v160 offset:512
	ds_read_b32 v83, v160 offset:768
	ds_read_b32 v84, v160 offset:1024
	ds_read_b32 v85, v160 offset:1280
	ds_read_b32 v86, v160 offset:1536
	ds_read_b32 v87, v160 offset:1792
	ds_read_b32 v88, v160 offset:2048
	ds_read_b32 v89, v160 offset:2304
	ds_read_b32 v90, v160 offset:2560
	ds_read_b32 v91, v160 offset:2816
	ds_read_b32 v92, v160 offset:3072
	ds_read_b32 v93, v160 offset:3328
	ds_read_b32 v94, v160 offset:3584
	ds_read_b32 v95, v160 offset:3840
	ds_read_b32 v96, v160 offset:4096
	ds_read_b32 v97, v160 offset:4352
	ds_read_b32 v98, v160 offset:4608
	ds_read_b32 v99, v160 offset:4864
	ds_read_b32 v100, v160 offset:5120
	ds_read_b32 v101, v160 offset:5376
	ds_read_b32 v102, v160 offset:5632
	ds_read_b32 v103, v160 offset:5888
	ds_read_b32 v104, v160 offset:6144
	ds_read_b32 v105, v160 offset:6400
	ds_read_b32 v106, v160 offset:6656
	ds_read_b32 v107, v160 offset:6912
	ds_read_b32 v108, v160 offset:7168
	ds_read_b32 v109, v160 offset:7424
	ds_read_b32 v110, v160 offset:7680
	ds_read_b32 v111, v160 offset:7936
	ds_read_b32 v112, v160 offset:8192
	ds_read_b32 v113, v160 offset:8448
	ds_read_b32 v114, v160 offset:8704
	ds_read_b32 v115, v160 offset:8960
	ds_read_b32 v116, v160 offset:9216
	ds_read_b32 v117, v160 offset:9472
	ds_read_b32 v118, v160 offset:9728
	ds_read_b32 v119, v160 offset:9984
	ds_read_b32 v120, v160 offset:10240
	ds_read_b32 v121, v160 offset:10496
	ds_read_b32 v122, v160 offset:10752
	ds_read_b32 v123, v160 offset:11008
	ds_read_b32 v124, v160 offset:11264
	ds_read_b32 v125, v160 offset:11520
	ds_read_b32 v126, v160 offset:11776
	ds_read_b32 v127, v160 offset:12032
	ds_read_b32 v128, v160 offset:12288
	ds_read_b32 v129, v160 offset:12544
	ds_read_b32 v130, v160 offset:12800
	ds_read_b32 v131, v160 offset:13056
	ds_read_b32 v132, v160 offset:13312
	ds_read_b32 v133, v160 offset:13568
	ds_read_b32 v134, v160 offset:13824
	ds_read_b32 v135, v160 offset:14080
	ds_read_b32 v136, v160 offset:14336
	ds_read_b32 v137, v160 offset:14592
	ds_read_b32 v138, v160 offset:14848
	ds_read_b32 v139, v160 offset:15104
	ds_read_b32 v140, v160 offset:15360
	ds_read_b32 v141, v160 offset:15616
	ds_read_b32 v142, v160 offset:15872
	ds_read_b32 v143, v160 offset:16128
	s_waitcnt lgkmcnt(0)
	s_mov_b64 s[48:49], s[74:75]
	s_and_saveexec_b64 s[4:5], s[74:75]
	s_cbranch_execz .LBB0_1672
	v_mul_f32_e32 v0, 0x3fb8aa3b, v165
	v_exp_f32_e32 v0, v0
	s_lshl_b64 s[30:31], s[0:1], 2
	v_readlane_b32 s10, v247, 42
	s_add_u32 s30, s10, s30
	v_readlane_b32 s10, v247, 43
	s_addc_u32 s31, s10, s31
	global_store_dword v161, v0, s[30:31]
	s_branch .LBB0_1672

	.amdhsa_kernel _Z14fwd_megakernel6Params
		.amdhsa_group_segment_fixed_size 0
		.amdhsa_private_segment_fixed_size 0
		.amdhsa_kernarg_size 608
		.amdhsa_user_sgpr_count 2
		.amdhsa_user_sgpr_dispatch_ptr 0
		.amdhsa_user_sgpr_queue_ptr 0
		.amdhsa_user_sgpr_kernarg_segment_ptr 1
		.amdhsa_user_sgpr_dispatch_id 0
		.amdhsa_user_sgpr_kernarg_preload_length 0
		.amdhsa_user_sgpr_kernarg_preload_offset 0
		.amdhsa_user_sgpr_private_segment_size 0
		.amdhsa_uses_dynamic_stack 0
		.amdhsa_enable_private_segment 0
		.amdhsa_system_sgpr_workgroup_id_x 1
		.amdhsa_system_sgpr_workgroup_id_y 0
		.amdhsa_system_sgpr_workgroup_id_z 0
		.amdhsa_system_sgpr_workgroup_info 0
		.amdhsa_system_vgpr_workitem_id 2
		.amdhsa_next_free_vgpr 256
		.amdhsa_next_free_sgpr 100
		.amdhsa_accum_offset 256
		.amdhsa_reserve_vcc 1
		.amdhsa_float_round_mode_32 0
		.amdhsa_float_round_mode_16_64 0
		.amdhsa_float_denorm_mode_32 3
		.amdhsa_float_denorm_mode_16_64 3
		.amdhsa_dx10_clamp 1
		.amdhsa_ieee_mode 1
		.amdhsa_fp16_overflow 0
		.amdhsa_tg_split 0
		.amdhsa_exception_fp_ieee_invalid_op 0
		.amdhsa_exception_fp_denorm_src 0
		.amdhsa_exception_fp_ieee_div_zero 0
		.amdhsa_exception_fp_ieee_overflow 0
		.amdhsa_exception_fp_ieee_underflow 0
		.amdhsa_exception_fp_ieee_inexact 0
		.amdhsa_exception_int_div_zero 0
	.end_amdhsa_kernel

amdhsa.kernels:
  - .agpr_count:     0
    .args:
      - .offset:         0
        .size:           352
        .value_kind:     by_value
      - .offset:         352
        .size:           4
        .value_kind:     hidden_block_count_x
      - .offset:         356
        .size:           4
        .value_kind:     hidden_block_count_y
      - .offset:         360
        .size:           4
        .value_kind:     hidden_block_count_z
      - .offset:         364
        .size:           2
        .value_kind:     hidden_group_size_x
      - .offset:         366
        .size:           2
        .value_kind:     hidden_group_size_y
      - .offset:         368
        .size:           2
        .value_kind:     hidden_group_size_z
      - .offset:         370
        .size:           2
        .value_kind:     hidden_remainder_x
      - .offset:         372
        .size:           2
        .value_kind:     hidden_remainder_y
      - .offset:         374
        .size:           2
        .value_kind:     hidden_remainder_z
      - .offset:         392
        .size:           8
        .value_kind:     hidden_global_offset_x
      - .offset:         400
        .size:           8
        .value_kind:     hidden_global_offset_y
      - .offset:         408
        .size:           8
        .value_kind:     hidden_global_offset_z
      - .offset:         416
        .size:           2
        .value_kind:     hidden_grid_dims
      - .offset:         440
        .size:           8
        .value_kind:     hidden_multigrid_sync_arg
      - .offset:         472
        .size:           4
        .value_kind:     hidden_dynamic_lds_size
    .group_segment_fixed_size: 0
    .kernarg_segment_align: 8
    .kernarg_segment_size: 608
    .language:       OpenCL C
    .language_version:
      - 2
      - 0
    .max_flat_workgroup_size: 512
    .name:           _Z14fwd_megakernel6Params
    .private_segment_fixed_size: 0
    .sgpr_count:     106
    .sgpr_spill_count: 150
    .symbol:         _Z14fwd_megakernel6Params.kd
    .uniform_work_group_size: 1
    .uses_dynamic_stack: false
    .vgpr_count:     256
    .vgpr_spill_count: 0
    .wavefront_size: 64
